# a+b plus: s_setprio 0 moved in front of the last MFMA of each sub-phase (barrier right behind the last MFMA)
# baseline (speedup 1.0000x reference)
; #define PG8_STAGE(bufoff, gbase, voff) do { const char* _gb = (const char*)(gbase); asm volatile("" : "+s"(_gb)); _Pragma("unroll") for (int _i = 0; _i < 2; ++_i) { asm volatile("" : "+v"((voff)[_i])); \
;         __builtin_amdgcn_global_load_lds((const unsigned*)(_gb + (voff)[_i]), (PG8_LAS unsigned*)(lds + (bufoff) + ldsw + _i * 8192), 16, 0, 0); } } while (0)
; #define PG8_LDA(dst, b, h) do { _Pragma("unroll") for (int m = 0; m < 4; ++m) _Pragma("unroll") for (int k = 0; k < 2; ++k) dst[m][k] = *(const PG8_LAS bf16x8*)(lds + PG8_SA(b, h) + aoff + m * 2048 + k * 1024); } while (0)
; #define PG8_LDB(dst, b, h) do { _Pragma("unroll") for (int n = 0; n < 2; ++n) _Pragma("unroll") for (int k = 0; k < 2; ++k) dst[n][k] = *(const PG8_LAS bf16x8*)(lds + PG8_SB(b, h) + boff + n * 2048 + k * 1024); } while (0)
; #define PG8_WAIT_V(n) asm volatile("s_waitcnt vmcnt(" #n ")" ::: "memory")
; #define PG8_WAIT_L(n) asm volatile("s_waitcnt lgkmcnt(" #n ")" ::: "memory")
; #define PG8_BAR __builtin_amdgcn_s_barrier()
; #define PG8_SCHED __builtin_amdgcn_sched_barrier(0)
; #define PG8_LDA(dst, b, h) do { _Pragma("unroll") for (int m = 0; m < 4; ++m) _Pragma("unroll") for (int k = 0; k < 2; ++k) dst[m][k] = *(const PG8_LAS bf16x8*)(lds + PG8_SA(b, h) + aoff + m * 2048 + k * 1024); } while (0)
; template <class Epi, class Sched, bool ALIGN_EPI = false, bool SP2 = false>
; __device__ __forceinline__ void gemm_phase(PG8_LAS unsigned char* lds, const Gemm g, const Sched& S, const Epi& E) {
;     ...
;         for (int t = 0; t < nt; t += 2) {
;             const bool last = (t == nt - 2);
;             const char* a1 = cA + (size_t)(t + 1) * kstep;
;             const char* a2 = last ? nA : cA + (size_t)(t + 2) * kstep; const char* b2 = last ? nB : cB + (size_t)(t + 2) * kstep;
;             const char* a3 = a2 + kstep; const char* b3 = b2 + kstep;
;             if (last && has_next) S.a_ready(nxt);
;             if constexpr (SP2) {
;             PG8_LDB(B0, 0, 0); PG8_LDB(B1, 0, 1); PG8_SCHED; PG8_LDA(At, 0, 0); PG8_STAGE(PG8_SA(1, 1), a1 + hstep, voffA);
;             PG8_WAIT_V(8); PG8_WAIT_L(0); PG8_BAR; PG8_MMA2(0); PG8_BAR; PG8_SCHED;
;             PG8_LDA(At, 0, 1); PG8_STAGE(PG8_SB(0, 0), b2, voffB); PG8_STAGE(PG8_SB(0, 1), b2 + hstep, voffB); PG8_STAGE(PG8_SA(0, 0), a2, voffA);
;             PG8_WAIT_V(8); PG8_WAIT_L(0); PG8_BAR; PG8_MMA2(1); PG8_BAR; PG8_SCHED;
.LBB0_313:
	ds_read_b128 v[136:139], v150
	ds_read_b128 v[140:143], v150 offset:1024
	ds_read_b128 v[154:157], v150 offset:2048
	ds_read_b128 v[158:161], v150 offset:3072
	ds_read_b128 v[162:165], v151
	ds_read_b128 v[166:169], v151 offset:1024
	ds_read_b128 v[170:173], v151 offset:2048
	ds_read_b128 v[174:177], v151 offset:3072
	s_add_u32 s14, s8, 0x100
	s_addc_u32 s15, s9, 0
	s_cmp_eq_u32 s43, 60
	s_cselect_b32 s24, s13, s14
	s_cselect_b32 s25, s11, s15
	s_cselect_b32 s16, s36, s37
	s_cselect_b32 s17, s33, s42
	s_add_u32 s2, s24, 0x80
	s_addc_u32 s3, s25, 0
	s_add_u32 s8, s8, 0x100080
	s_addc_u32 s9, s9, 0
	s_add_i32 m0, s63, 0xc000
	ds_read_b128 v[178:181], v152
	ds_read_b128 v[182:185], v152 offset:1024
	ds_read_b128 v[186:189], v152 offset:2048
	ds_read_b128 v[190:193], v152 offset:3072
	ds_read_b128 v[194:197], v152 offset:4096
	ds_read_b128 v[198:201], v152 offset:5120
	ds_read_b128 v[202:205], v152 offset:6144
	ds_read_b128 v[206:209], v152 offset:7168
	s_nop 0
	global_load_lds_dwordx4 v1, s[8:9]
	s_add_i32 m0, s63, 0xe000
	s_nop 0
	global_load_lds_dwordx4 v145, s[8:9]
	s_waitcnt vmcnt(8)
	s_waitcnt lgkmcnt(0)
	s_setprio 1
	s_waitcnt lgkmcnt(0)
	s_barrier
	v_mfma_f32_16x16x32_bf16 v[126:129], v[136:139], v[178:181], v[126:129]
	v_mfma_f32_16x16x32_bf16 v[122:125], v[154:157], v[178:181], v[122:125]
	v_mfma_f32_16x16x32_bf16 v[110:113], v[136:139], v[186:189], v[110:113]
	v_mfma_f32_16x16x32_bf16 v[106:109], v[154:157], v[186:189], v[106:109]
	v_mfma_f32_16x16x32_bf16 v[94:97], v[136:139], v[194:197], v[94:97]
	v_mfma_f32_16x16x32_bf16 v[90:93], v[154:157], v[194:197], v[90:93]
	v_mfma_f32_16x16x32_bf16 v[78:81], v[136:139], v[202:205], v[78:81]
	v_mfma_f32_16x16x32_bf16 v[74:77], v[154:157], v[202:205], v[74:77]
	v_mfma_f32_16x16x32_bf16 v[118:121], v[162:165], v[178:181], v[118:121]
	v_mfma_f32_16x16x32_bf16 v[114:117], v[170:173], v[178:181], v[114:117]
	v_mfma_f32_16x16x32_bf16 v[102:105], v[162:165], v[186:189], v[102:105]
	v_mfma_f32_16x16x32_bf16 v[98:101], v[170:173], v[186:189], v[98:101]
	v_mfma_f32_16x16x32_bf16 v[86:89], v[162:165], v[194:197], v[86:89]
	v_mfma_f32_16x16x32_bf16 v[82:85], v[170:173], v[194:197], v[82:85]
	v_mfma_f32_16x16x32_bf16 v[70:73], v[162:165], v[202:205], v[70:73]
	v_mfma_f32_16x16x32_bf16 v[66:69], v[170:173], v[202:205], v[66:69]
	v_mfma_f32_16x16x32_bf16 v[126:129], v[140:143], v[182:185], v[126:129]
	v_mfma_f32_16x16x32_bf16 v[122:125], v[158:161], v[182:185], v[122:125]
	v_mfma_f32_16x16x32_bf16 v[110:113], v[140:143], v[190:193], v[110:113]
	v_mfma_f32_16x16x32_bf16 v[106:109], v[158:161], v[190:193], v[106:109]
	v_mfma_f32_16x16x32_bf16 v[94:97], v[140:143], v[198:201], v[94:97]
	v_mfma_f32_16x16x32_bf16 v[90:93], v[158:161], v[198:201], v[90:93]
	v_mfma_f32_16x16x32_bf16 v[78:81], v[140:143], v[206:209], v[78:81]
	v_mfma_f32_16x16x32_bf16 v[74:77], v[158:161], v[206:209], v[74:77]
	v_mfma_f32_16x16x32_bf16 v[118:121], v[166:169], v[182:185], v[118:121]
	v_mfma_f32_16x16x32_bf16 v[114:117], v[174:177], v[182:185], v[114:117]
	v_mfma_f32_16x16x32_bf16 v[102:105], v[166:169], v[190:193], v[102:105]
	v_mfma_f32_16x16x32_bf16 v[98:101], v[174:177], v[190:193], v[98:101]
	v_mfma_f32_16x16x32_bf16 v[86:89], v[166:169], v[198:201], v[86:89]
	v_mfma_f32_16x16x32_bf16 v[82:85], v[174:177], v[198:201], v[82:85]
	v_mfma_f32_16x16x32_bf16 v[70:73], v[166:169], v[206:209], v[70:73]
	s_setprio 0
	v_mfma_f32_16x16x32_bf16 v[66:69], v[174:177], v[206:209], v[66:69]
	s_barrier
	s_add_i32 s44, s95, s61
	s_mov_b64 s[8:9], s[16:17]
	s_mov_b32 m0, s44
	ds_read_b128 v[178:181], v152 offset:16384
	ds_read_b128 v[182:185], v152 offset:17408
	ds_read_b128 v[186:189], v152 offset:18432
	ds_read_b128 v[190:193], v152 offset:19456
	ds_read_b128 v[194:197], v152 offset:20480
	ds_read_b128 v[198:201], v152 offset:21504
	ds_read_b128 v[202:205], v152 offset:22528
	ds_read_b128 v[206:209], v152 offset:23552
	s_nop 0
	global_load_lds_dwordx4 v144, s[8:9]
	s_add_i32 m0, s44, 0x2000
	s_nop 0
	global_load_lds_dwordx4 v146, s[8:9]
	s_add_u32 s8, s16, 0x100000
	s_addc_u32 s9, s17, 0
	s_add_i32 s44, s96, s61
	s_mov_b32 m0, s44
	s_nop 0
	global_load_lds_dwordx4 v144, s[8:9]
	s_add_i32 m0, s44, 0x2000
	s_nop 0
	global_load_lds_dwordx4 v146, s[8:9]
	s_mov_b64 s[8:9], s[24:25]
	s_mov_b32 m0, s63
	s_nop 0
	global_load_lds_dwordx4 v1, s[8:9]
	s_mov_b32 m0, s65
	s_nop 0
	global_load_lds_dwordx4 v145, s[8:9]
	s_waitcnt vmcnt(8)
	s_waitcnt lgkmcnt(0)
	s_setprio 1
	s_waitcnt lgkmcnt(0)
	s_barrier
	v_mfma_f32_16x16x32_bf16 v[62:65], v[136:139], v[178:181], v[62:65]
	v_mfma_f32_16x16x32_bf16 v[58:61], v[154:157], v[178:181], v[58:61]
	v_mfma_f32_16x16x32_bf16 v[46:49], v[136:139], v[186:189], v[46:49]
	v_mfma_f32_16x16x32_bf16 v[42:45], v[154:157], v[186:189], v[42:45]
	v_mfma_f32_16x16x32_bf16 v[30:33], v[136:139], v[194:197], v[30:33]
	v_mfma_f32_16x16x32_bf16 v[26:29], v[154:157], v[194:197], v[26:29]
	v_mfma_f32_16x16x32_bf16 v[14:17], v[136:139], v[202:205], v[14:17]
	v_mfma_f32_16x16x32_bf16 v[10:13], v[154:157], v[202:205], v[10:13]
	v_mfma_f32_16x16x32_bf16 v[54:57], v[162:165], v[178:181], v[54:57]
	v_mfma_f32_16x16x32_bf16 v[50:53], v[170:173], v[178:181], v[50:53]
	v_mfma_f32_16x16x32_bf16 v[38:41], v[162:165], v[186:189], v[38:41]
	v_mfma_f32_16x16x32_bf16 v[34:37], v[170:173], v[186:189], v[34:37]
	v_mfma_f32_16x16x32_bf16 v[22:25], v[162:165], v[194:197], v[22:25]
	v_mfma_f32_16x16x32_bf16 v[18:21], v[170:173], v[194:197], v[18:21]
	v_mfma_f32_16x16x32_bf16 v[6:9], v[162:165], v[202:205], v[6:9]
	v_mfma_f32_16x16x32_bf16 v[2:5], v[170:173], v[202:205], v[2:5]
	v_mfma_f32_16x16x32_bf16 v[62:65], v[140:143], v[182:185], v[62:65]
	v_mfma_f32_16x16x32_bf16 v[58:61], v[158:161], v[182:185], v[58:61]
	v_mfma_f32_16x16x32_bf16 v[46:49], v[140:143], v[190:193], v[46:49]
	v_mfma_f32_16x16x32_bf16 v[42:45], v[158:161], v[190:193], v[42:45]
	v_mfma_f32_16x16x32_bf16 v[30:33], v[140:143], v[198:201], v[30:33]
	v_mfma_f32_16x16x32_bf16 v[26:29], v[158:161], v[198:201], v[26:29]
	v_mfma_f32_16x16x32_bf16 v[14:17], v[140:143], v[206:209], v[14:17]
	v_mfma_f32_16x16x32_bf16 v[10:13], v[158:161], v[206:209], v[10:13]
	v_mfma_f32_16x16x32_bf16 v[54:57], v[166:169], v[182:185], v[54:57]
	v_mfma_f32_16x16x32_bf16 v[50:53], v[174:177], v[182:185], v[50:53]
	v_mfma_f32_16x16x32_bf16 v[38:41], v[166:169], v[190:193], v[38:41]
	v_mfma_f32_16x16x32_bf16 v[34:37], v[174:177], v[190:193], v[34:37]
	v_mfma_f32_16x16x32_bf16 v[22:25], v[166:169], v[198:201], v[22:25]
	v_mfma_f32_16x16x32_bf16 v[18:21], v[174:177], v[198:201], v[18:21]
	v_mfma_f32_16x16x32_bf16 v[6:9], v[166:169], v[206:209], v[6:9]
	s_setprio 0
	v_mfma_f32_16x16x32_bf16 v[2:5], v[174:177], v[206:209], v[2:5]
	s_barrier
; #define PG8_STAGE(bufoff, gbase, voff) do { const char* _gb = (const char*)(gbase); asm volatile("" : "+s"(_gb)); _Pragma("unroll") for (int _i = 0; _i < 2; ++_i) { asm volatile("" : "+v"((voff)[_i])); \
;         __builtin_amdgcn_global_load_lds((const unsigned*)(_gb + (voff)[_i]), (PG8_LAS unsigned*)(lds + (bufoff) + ldsw + _i * 8192), 16, 0, 0); } } while (0)
; #define PG8_LDA(dst, b, h) do { _Pragma("unroll") for (int m = 0; m < 4; ++m) _Pragma("unroll") for (int k = 0; k < 2; ++k) dst[m][k] = *(const PG8_LAS bf16x8*)(lds + PG8_SA(b, h) + aoff + m * 2048 + k * 1024); } while (0)
; #define PG8_LDB(dst, b, h) do { _Pragma("unroll") for (int n = 0; n < 2; ++n) _Pragma("unroll") for (int k = 0; k < 2; ++k) dst[n][k] = *(const PG8_LAS bf16x8*)(lds + PG8_SB(b, h) + boff + n * 2048 + k * 1024); } while (0)
; #define PG8_WAIT_V(n) asm volatile("s_waitcnt vmcnt(" #n ")" ::: "memory")
; #define PG8_WAIT_L(n) asm volatile("s_waitcnt lgkmcnt(" #n ")" ::: "memory")
; #define PG8_BAR __builtin_amdgcn_s_barrier()
; #define PG8_SCHED __builtin_amdgcn_sched_barrier(0)
; #define PG8_STAGE(bufoff, gbase, voff) do { const char* _gb = (const char*)(gbase); asm volatile("" : "+s"(_gb)); _Pragma("unroll") for (int _i = 0; _i < 2; ++_i) { asm volatile("" : "+v"((voff)[_i])); \
;         __builtin_amdgcn_global_load_lds((const unsigned*)(_gb + (voff)[_i]), (PG8_LAS unsigned*)(lds + (bufoff) + ldsw + _i * 8192), 16, 0, 0); } } while (0)
; #define PG8_LDA(dst, b, h) do { _Pragma("unroll") for (int m = 0; m < 4; ++m) _Pragma("unroll") for (int k = 0; k < 2; ++k) dst[m][k] = *(const PG8_LAS bf16x8*)(lds + PG8_SA(b, h) + aoff + m * 2048 + k * 1024); } while (0)
; #define PG8_WAIT_V(n) asm volatile("s_waitcnt vmcnt(" #n ")" ::: "memory")
; template <class Epi, class Sched, bool ALIGN_EPI = false, bool SP2 = false>
; __device__ __forceinline__ void gemm_phase(PG8_LAS unsigned char* lds, const Gemm g, const Sched& S, const Epi& E) {
;     ...
;             PG8_LDB(B0, 1, 0); PG8_LDB(B1, 1, 1); PG8_SCHED; PG8_LDA(At, 1, 0); PG8_STAGE(PG8_SA(0, 1), a2 + hstep, voffA);
;             PG8_WAIT_V(8); PG8_WAIT_L(0); PG8_BAR; PG8_MMA2(0); PG8_BAR; PG8_SCHED;
;             PG8_LDA(At, 1, 1); PG8_STAGE(PG8_SB(1, 0), b3, voffB); PG8_STAGE(PG8_SB(1, 1), b3 + hstep, voffB); PG8_STAGE(PG8_SA(1, 0), a3, voffA);
;             PG8_WAIT_V(8); PG8_WAIT_L(0); PG8_BAR; PG8_MMA2(1); PG8_BAR; PG8_SCHED;
	s_add_i32 s44, 0, 0x18000
	v_add_u32_e32 v135, s44, v148
	s_add_i32 s45, 0, 0x1c000
	ds_read_b128 v[136:139], v135
	ds_read_b128 v[140:143], v135 offset:1024
	ds_read_b128 v[154:157], v135 offset:2048
	ds_read_b128 v[158:161], v135 offset:3072
	v_add_u32_e32 v135, s45, v148
	ds_read_b128 v[162:165], v135
	ds_read_b128 v[166:169], v135 offset:1024
	ds_read_b128 v[170:173], v135 offset:2048
	ds_read_b128 v[174:177], v135 offset:3072
	s_add_u32 s8, s24, 0x100000
	s_addc_u32 s9, s25, 0
	s_mov_b32 m0, s88
	ds_read_b128 v[178:181], v152 offset:32768
	ds_read_b128 v[182:185], v152 offset:33792
	ds_read_b128 v[186:189], v152 offset:34816
	ds_read_b128 v[190:193], v152 offset:35840
	ds_read_b128 v[194:197], v152 offset:36864
	ds_read_b128 v[198:201], v152 offset:37888
	ds_read_b128 v[202:205], v152 offset:38912
	ds_read_b128 v[206:209], v152 offset:39936
	s_nop 0
	global_load_lds_dwordx4 v1, s[8:9]
	s_mov_b32 m0, s89
	s_nop 0
	global_load_lds_dwordx4 v145, s[8:9]
	s_waitcnt vmcnt(8)
	s_waitcnt lgkmcnt(0)
	s_setprio 1
	s_waitcnt lgkmcnt(0)
	s_barrier
	v_mfma_f32_16x16x32_bf16 v[126:129], v[136:139], v[178:181], v[126:129]
	v_mfma_f32_16x16x32_bf16 v[122:125], v[154:157], v[178:181], v[122:125]
	v_mfma_f32_16x16x32_bf16 v[110:113], v[136:139], v[186:189], v[110:113]
	v_mfma_f32_16x16x32_bf16 v[106:109], v[154:157], v[186:189], v[106:109]
	v_mfma_f32_16x16x32_bf16 v[94:97], v[136:139], v[194:197], v[94:97]
	v_mfma_f32_16x16x32_bf16 v[90:93], v[154:157], v[194:197], v[90:93]
	v_mfma_f32_16x16x32_bf16 v[78:81], v[136:139], v[202:205], v[78:81]
	v_mfma_f32_16x16x32_bf16 v[74:77], v[154:157], v[202:205], v[74:77]
	v_mfma_f32_16x16x32_bf16 v[118:121], v[162:165], v[178:181], v[118:121]
	v_mfma_f32_16x16x32_bf16 v[114:117], v[170:173], v[178:181], v[114:117]
	v_mfma_f32_16x16x32_bf16 v[102:105], v[162:165], v[186:189], v[102:105]
	v_mfma_f32_16x16x32_bf16 v[98:101], v[170:173], v[186:189], v[98:101]
	v_mfma_f32_16x16x32_bf16 v[86:89], v[162:165], v[194:197], v[86:89]
	v_mfma_f32_16x16x32_bf16 v[82:85], v[170:173], v[194:197], v[82:85]
	v_mfma_f32_16x16x32_bf16 v[70:73], v[162:165], v[202:205], v[70:73]
	v_mfma_f32_16x16x32_bf16 v[66:69], v[170:173], v[202:205], v[66:69]
	v_mfma_f32_16x16x32_bf16 v[126:129], v[140:143], v[182:185], v[126:129]
	v_mfma_f32_16x16x32_bf16 v[122:125], v[158:161], v[182:185], v[122:125]
	v_mfma_f32_16x16x32_bf16 v[110:113], v[140:143], v[190:193], v[110:113]
	v_mfma_f32_16x16x32_bf16 v[106:109], v[158:161], v[190:193], v[106:109]
	v_mfma_f32_16x16x32_bf16 v[94:97], v[140:143], v[198:201], v[94:97]
	v_mfma_f32_16x16x32_bf16 v[90:93], v[158:161], v[198:201], v[90:93]
	v_mfma_f32_16x16x32_bf16 v[78:81], v[140:143], v[206:209], v[78:81]
	v_mfma_f32_16x16x32_bf16 v[74:77], v[158:161], v[206:209], v[74:77]
	v_mfma_f32_16x16x32_bf16 v[118:121], v[166:169], v[182:185], v[118:121]
	v_mfma_f32_16x16x32_bf16 v[114:117], v[174:177], v[182:185], v[114:117]
	v_mfma_f32_16x16x32_bf16 v[102:105], v[166:169], v[190:193], v[102:105]
	v_mfma_f32_16x16x32_bf16 v[98:101], v[174:177], v[190:193], v[98:101]
	v_mfma_f32_16x16x32_bf16 v[86:89], v[166:169], v[198:201], v[86:89]
	v_mfma_f32_16x16x32_bf16 v[82:85], v[174:177], v[198:201], v[82:85]
	v_mfma_f32_16x16x32_bf16 v[70:73], v[166:169], v[206:209], v[70:73]
	s_setprio 0
	v_mfma_f32_16x16x32_bf16 v[66:69], v[174:177], v[206:209], v[66:69]
	s_barrier
	s_add_u32 s8, s16, 0x80
	s_addc_u32 s9, s17, 0
	s_add_i32 s24, s44, s61
	s_mov_b32 m0, s24
	ds_read_b128 v[178:181], v152 offset:49152
	ds_read_b128 v[182:185], v152 offset:50176
	ds_read_b128 v[186:189], v152 offset:51200
	ds_read_b128 v[190:193], v152 offset:52224
	ds_read_b128 v[194:197], v152 offset:53248
	ds_read_b128 v[198:201], v152 offset:54272
	ds_read_b128 v[202:205], v152 offset:55296
	ds_read_b128 v[206:209], v152 offset:56320
	s_nop 0
	global_load_lds_dwordx4 v144, s[8:9]
	s_add_i32 m0, s24, 0x2000
	s_nop 0
	global_load_lds_dwordx4 v146, s[8:9]
	s_add_u32 s8, s16, 0x100080
	s_addc_u32 s9, s17, 0
	s_add_i32 s16, s45, s61
	s_mov_b32 m0, s16
	s_nop 0
	global_load_lds_dwordx4 v144, s[8:9]
	s_add_i32 m0, s16, 0x2000
	s_nop 0
	global_load_lds_dwordx4 v146, s[8:9]
	s_mov_b32 m0, s91
	s_nop 0
	global_load_lds_dwordx4 v1, s[2:3]
	s_mov_b32 m0, s92
	s_nop 0
	global_load_lds_dwordx4 v145, s[2:3]
	s_waitcnt vmcnt(8)
	s_waitcnt lgkmcnt(0)
	s_setprio 1
	s_waitcnt lgkmcnt(0)
	s_barrier
	v_mfma_f32_16x16x32_bf16 v[62:65], v[136:139], v[178:181], v[62:65]
	v_mfma_f32_16x16x32_bf16 v[58:61], v[154:157], v[178:181], v[58:61]
	v_mfma_f32_16x16x32_bf16 v[46:49], v[136:139], v[186:189], v[46:49]
	v_mfma_f32_16x16x32_bf16 v[42:45], v[154:157], v[186:189], v[42:45]
	v_mfma_f32_16x16x32_bf16 v[30:33], v[136:139], v[194:197], v[30:33]
	v_mfma_f32_16x16x32_bf16 v[26:29], v[154:157], v[194:197], v[26:29]
	v_mfma_f32_16x16x32_bf16 v[14:17], v[136:139], v[202:205], v[14:17]
	v_mfma_f32_16x16x32_bf16 v[10:13], v[154:157], v[202:205], v[10:13]
	v_mfma_f32_16x16x32_bf16 v[54:57], v[162:165], v[178:181], v[54:57]
	v_mfma_f32_16x16x32_bf16 v[50:53], v[170:173], v[178:181], v[50:53]
	v_mfma_f32_16x16x32_bf16 v[38:41], v[162:165], v[186:189], v[38:41]
	v_mfma_f32_16x16x32_bf16 v[34:37], v[170:173], v[186:189], v[34:37]
	v_mfma_f32_16x16x32_bf16 v[22:25], v[162:165], v[194:197], v[22:25]
	v_mfma_f32_16x16x32_bf16 v[18:21], v[170:173], v[194:197], v[18:21]
	v_mfma_f32_16x16x32_bf16 v[6:9], v[162:165], v[202:205], v[6:9]
	v_mfma_f32_16x16x32_bf16 v[2:5], v[170:173], v[202:205], v[2:5]
	v_mfma_f32_16x16x32_bf16 v[62:65], v[140:143], v[182:185], v[62:65]
	v_mfma_f32_16x16x32_bf16 v[58:61], v[158:161], v[182:185], v[58:61]
	v_mfma_f32_16x16x32_bf16 v[46:49], v[140:143], v[190:193], v[46:49]
	v_mfma_f32_16x16x32_bf16 v[42:45], v[158:161], v[190:193], v[42:45]
	v_mfma_f32_16x16x32_bf16 v[30:33], v[140:143], v[198:201], v[30:33]
	v_mfma_f32_16x16x32_bf16 v[26:29], v[158:161], v[198:201], v[26:29]
	v_mfma_f32_16x16x32_bf16 v[14:17], v[140:143], v[206:209], v[14:17]
	v_mfma_f32_16x16x32_bf16 v[10:13], v[158:161], v[206:209], v[10:13]
	v_mfma_f32_16x16x32_bf16 v[54:57], v[166:169], v[182:185], v[54:57]
	v_mfma_f32_16x16x32_bf16 v[50:53], v[174:177], v[182:185], v[50:53]
	v_mfma_f32_16x16x32_bf16 v[38:41], v[166:169], v[190:193], v[38:41]
	v_mfma_f32_16x16x32_bf16 v[34:37], v[174:177], v[190:193], v[34:37]
	v_mfma_f32_16x16x32_bf16 v[22:25], v[166:169], v[198:201], v[22:25]
	v_mfma_f32_16x16x32_bf16 v[18:21], v[174:177], v[198:201], v[18:21]
	v_mfma_f32_16x16x32_bf16 v[6:9], v[166:169], v[206:209], v[6:9]
	s_setprio 0
	v_mfma_f32_16x16x32_bf16 v[2:5], v[174:177], v[206:209], v[2:5]
	s_barrier
	s_add_i32 s43, s43, 2
	s_add_u32 s37, s37, 0x100
	s_addc_u32 s42, s42, 0
	s_cmp_gt_u32 s43, 61
	s_mov_b64 s[8:9], s[14:15]
	s_cbranch_scc0 .LBB0_313
	s_and_b64 vcc, exec, s[58:59]
	s_cbranch_vccz .LBB0_333
	s_barrier
	s_cmp_lt_i32 s12, 24
	s_cbranch_scc0 .LBB0_334

.LBB0_746:
	ds_read_b128 v[118:121], v172
	ds_read_b128 v[134:137], v172 offset:1024
	ds_read_b128 v[138:141], v172 offset:2048
	ds_read_b128 v[142:145], v172 offset:3072
	ds_read_b128 v[146:149], v173
	ds_read_b128 v[150:153], v173 offset:1024
	ds_read_b128 v[154:157], v173 offset:2048
	ds_read_b128 v[176:179], v173 offset:3072
	s_add_u32 s16, s0, 0x100
	s_addc_u32 s17, s1, 0
	s_cmp_eq_u32 s33, 28
	s_cselect_b32 s26, s30, s16
	s_cselect_b32 s27, s31, s17
	s_cselect_b32 s24, s78, s5
	s_cselect_b32 s25, s79, s21
	s_add_u32 s2, s26, 0x80
	s_addc_u32 s3, s27, 0
	s_add_u32 s0, s0, 0x100080
	s_addc_u32 s1, s1, 0
	s_add_i32 s76, s46, 0xc000
	s_mov_b32 m0, s76
	s_add_i32 s77, s46, 0xe000
	ds_read_b128 v[180:183], v174
	ds_read_b128 v[184:187], v174 offset:1024
	ds_read_b128 v[188:191], v174 offset:2048
	ds_read_b128 v[192:195], v174 offset:3072
	ds_read_b128 v[196:199], v174 offset:4096
	ds_read_b128 v[200:203], v174 offset:5120
	ds_read_b128 v[204:207], v174 offset:6144
	ds_read_b128 v[208:211], v174 offset:7168
	s_nop 0
	global_load_lds_dwordx4 v1, s[0:1]
	s_mov_b32 m0, s77
	s_nop 0
	global_load_lds_dwordx4 v165, s[0:1]
	s_waitcnt vmcnt(8)
	s_waitcnt lgkmcnt(0)
	s_setprio 1
	s_waitcnt lgkmcnt(0)
	s_barrier
	v_mfma_f32_16x16x32_bf16 v[34:37], v[118:121], v[180:183], v[34:37]
	v_mfma_f32_16x16x32_bf16 v[30:33], v[138:141], v[180:183], v[30:33]
	v_mfma_f32_16x16x32_bf16 v[46:49], v[118:121], v[188:191], v[46:49]
	v_mfma_f32_16x16x32_bf16 v[62:65], v[138:141], v[188:191], v[62:65]
	v_mfma_f32_16x16x32_bf16 v[78:81], v[118:121], v[196:199], v[78:81]
	v_mfma_f32_16x16x32_bf16 v[90:93], v[138:141], v[196:199], v[90:93]
	v_mfma_f32_16x16x32_bf16 v[130:133], v[118:121], v[204:207], v[130:133]
	v_mfma_f32_16x16x32_bf16 v[114:117], v[138:141], v[204:207], v[114:117]
	v_mfma_f32_16x16x32_bf16 v[26:29], v[146:149], v[180:183], v[26:29]
	v_mfma_f32_16x16x32_bf16 v[50:53], v[154:157], v[180:183], v[50:53]
	v_mfma_f32_16x16x32_bf16 v[58:61], v[146:149], v[188:191], v[58:61]
	v_mfma_f32_16x16x32_bf16 v[82:85], v[154:157], v[188:191], v[82:85]
	v_mfma_f32_16x16x32_bf16 v[110:113], v[146:149], v[196:199], v[110:113]
	v_mfma_f32_16x16x32_bf16 v[106:109], v[154:157], v[196:199], v[106:109]
	v_mfma_f32_16x16x32_bf16 v[122:125], v[146:149], v[204:207], v[122:125]
	v_mfma_f32_16x16x32_bf16 v[126:129], v[154:157], v[204:207], v[126:129]
	v_mfma_f32_16x16x32_bf16 v[34:37], v[134:137], v[184:187], v[34:37]
	v_mfma_f32_16x16x32_bf16 v[30:33], v[142:145], v[184:187], v[30:33]
	v_mfma_f32_16x16x32_bf16 v[46:49], v[134:137], v[192:195], v[46:49]
	v_mfma_f32_16x16x32_bf16 v[62:65], v[142:145], v[192:195], v[62:65]
	v_mfma_f32_16x16x32_bf16 v[78:81], v[134:137], v[200:203], v[78:81]
	v_mfma_f32_16x16x32_bf16 v[90:93], v[142:145], v[200:203], v[90:93]
	v_mfma_f32_16x16x32_bf16 v[130:133], v[134:137], v[208:211], v[130:133]
	v_mfma_f32_16x16x32_bf16 v[114:117], v[142:145], v[208:211], v[114:117]
	v_mfma_f32_16x16x32_bf16 v[26:29], v[150:153], v[184:187], v[26:29]
	v_mfma_f32_16x16x32_bf16 v[50:53], v[176:179], v[184:187], v[50:53]
	v_mfma_f32_16x16x32_bf16 v[58:61], v[150:153], v[192:195], v[58:61]
	v_mfma_f32_16x16x32_bf16 v[82:85], v[176:179], v[192:195], v[82:85]
	v_mfma_f32_16x16x32_bf16 v[110:113], v[150:153], v[200:203], v[110:113]
	v_mfma_f32_16x16x32_bf16 v[106:109], v[176:179], v[200:203], v[106:109]
	v_mfma_f32_16x16x32_bf16 v[122:125], v[150:153], v[208:211], v[122:125]
	s_setprio 0
	v_mfma_f32_16x16x32_bf16 v[126:129], v[176:179], v[208:211], v[126:129]
	s_barrier
	s_add_i32 s80, s72, s45
	s_mov_b64 s[0:1], s[24:25]
	s_mov_b32 m0, s80
	s_add_i32 s81, s80, 0x2000
	ds_read_b128 v[180:183], v174 offset:16384
	ds_read_b128 v[184:187], v174 offset:17408
	ds_read_b128 v[188:191], v174 offset:18432
	ds_read_b128 v[192:195], v174 offset:19456
	ds_read_b128 v[196:199], v174 offset:20480
	ds_read_b128 v[200:203], v174 offset:21504
	ds_read_b128 v[204:207], v174 offset:22528
	ds_read_b128 v[208:211], v174 offset:23552
	s_nop 0
	global_load_lds_dwordx4 v164, s[0:1]
	s_mov_b32 m0, s81
	s_nop 0
	global_load_lds_dwordx4 v166, s[0:1]
	s_add_u32 s0, s24, 0x100000
	s_addc_u32 s1, s25, 0
	s_add_i32 s82, s73, s45
	s_mov_b32 m0, s82
	s_add_i32 s83, s82, 0x2000
	s_nop 0
	global_load_lds_dwordx4 v164, s[0:1]
	s_mov_b32 m0, s83
	s_nop 0
	global_load_lds_dwordx4 v166, s[0:1]
	s_mov_b64 s[0:1], s[26:27]
	s_mov_b32 m0, s46
	s_nop 0
	global_load_lds_dwordx4 v1, s[0:1]
	s_mov_b32 m0, s47
	s_nop 0
	global_load_lds_dwordx4 v165, s[0:1]
	s_waitcnt vmcnt(8)
	s_waitcnt lgkmcnt(0)
	s_setprio 1
	s_waitcnt lgkmcnt(0)
	s_barrier
	v_mfma_f32_16x16x32_bf16 v[102:105], v[118:121], v[180:183], v[102:105]
	v_mfma_f32_16x16x32_bf16 v[98:101], v[138:141], v[180:183], v[98:101]
	v_mfma_f32_16x16x32_bf16 v[74:77], v[118:121], v[188:191], v[74:77]
	v_mfma_f32_16x16x32_bf16 v[70:73], v[138:141], v[188:191], v[70:73]
	v_mfma_f32_16x16x32_bf16 v[42:45], v[118:121], v[196:199], v[42:45]
	v_mfma_f32_16x16x32_bf16 v[38:41], v[138:141], v[196:199], v[38:41]
	v_mfma_f32_16x16x32_bf16 v[18:21], v[118:121], v[204:207], v[18:21]
	v_mfma_f32_16x16x32_bf16 v[10:13], v[138:141], v[204:207], v[10:13]
	v_mfma_f32_16x16x32_bf16 v[94:97], v[146:149], v[180:183], v[94:97]
	v_mfma_f32_16x16x32_bf16 v[86:89], v[154:157], v[180:183], v[86:89]
	v_mfma_f32_16x16x32_bf16 v[66:69], v[146:149], v[188:191], v[66:69]
	v_mfma_f32_16x16x32_bf16 v[54:57], v[154:157], v[188:191], v[54:57]
	v_mfma_f32_16x16x32_bf16 v[22:25], v[146:149], v[196:199], v[22:25]
	v_mfma_f32_16x16x32_bf16 v[14:17], v[154:157], v[196:199], v[14:17]
	v_mfma_f32_16x16x32_bf16 v[6:9], v[146:149], v[204:207], v[6:9]
	v_mfma_f32_16x16x32_bf16 v[2:5], v[154:157], v[204:207], v[2:5]
	v_mfma_f32_16x16x32_bf16 v[102:105], v[134:137], v[184:187], v[102:105]
	v_mfma_f32_16x16x32_bf16 v[98:101], v[142:145], v[184:187], v[98:101]
	v_mfma_f32_16x16x32_bf16 v[74:77], v[134:137], v[192:195], v[74:77]
	v_mfma_f32_16x16x32_bf16 v[70:73], v[142:145], v[192:195], v[70:73]
	v_mfma_f32_16x16x32_bf16 v[42:45], v[134:137], v[200:203], v[42:45]
	v_mfma_f32_16x16x32_bf16 v[38:41], v[142:145], v[200:203], v[38:41]
	v_mfma_f32_16x16x32_bf16 v[18:21], v[134:137], v[208:211], v[18:21]
	v_mfma_f32_16x16x32_bf16 v[10:13], v[142:145], v[208:211], v[10:13]
	v_mfma_f32_16x16x32_bf16 v[94:97], v[150:153], v[184:187], v[94:97]
	v_mfma_f32_16x16x32_bf16 v[86:89], v[176:179], v[184:187], v[86:89]
	v_mfma_f32_16x16x32_bf16 v[66:69], v[150:153], v[192:195], v[66:69]
	v_mfma_f32_16x16x32_bf16 v[54:57], v[176:179], v[192:195], v[54:57]
	v_mfma_f32_16x16x32_bf16 v[22:25], v[150:153], v[200:203], v[22:25]
	v_mfma_f32_16x16x32_bf16 v[14:17], v[176:179], v[200:203], v[14:17]
	v_mfma_f32_16x16x32_bf16 v[6:9], v[150:153], v[208:211], v[6:9]
	s_setprio 0
	v_mfma_f32_16x16x32_bf16 v[2:5], v[176:179], v[208:211], v[2:5]
	s_barrier
	s_add_i32 s84, 0, 0x18000
	s_add_i32 s86, 0, 0x1c000
	v_add_u32_e32 v175, s84, v170
	v_add_u32_e32 v176, s86, v170
	ds_read_b128 v[118:121], v175
	ds_read_b128 v[134:137], v175 offset:1024
	ds_read_b128 v[138:141], v175 offset:2048
	ds_read_b128 v[142:145], v175 offset:3072
	ds_read_b128 v[146:149], v176
	ds_read_b128 v[150:153], v176 offset:1024
	ds_read_b128 v[154:157], v176 offset:2048
	ds_read_b128 v[178:181], v176 offset:3072
	s_add_u32 s0, s26, 0x100000
	s_addc_u32 s1, s27, 0
	s_mov_b32 m0, s48
	ds_read_b128 v[182:185], v174 offset:32768
	ds_read_b128 v[186:189], v174 offset:33792
	ds_read_b128 v[190:193], v174 offset:34816
	ds_read_b128 v[194:197], v174 offset:35840
	ds_read_b128 v[198:201], v174 offset:36864
	ds_read_b128 v[202:205], v174 offset:37888
	ds_read_b128 v[206:209], v174 offset:38912
	ds_read_b128 v[210:213], v174 offset:39936
	s_nop 0
	global_load_lds_dwordx4 v1, s[0:1]
	s_mov_b32 m0, s49
	s_nop 0
	global_load_lds_dwordx4 v165, s[0:1]
	s_waitcnt vmcnt(8)
	s_waitcnt lgkmcnt(0)
	s_setprio 1
	s_waitcnt lgkmcnt(0)
	s_barrier
	v_mfma_f32_16x16x32_bf16 v[34:37], v[118:121], v[182:185], v[34:37]
	v_mfma_f32_16x16x32_bf16 v[30:33], v[138:141], v[182:185], v[30:33]
	v_mfma_f32_16x16x32_bf16 v[46:49], v[118:121], v[190:193], v[46:49]
	v_mfma_f32_16x16x32_bf16 v[62:65], v[138:141], v[190:193], v[62:65]
	v_mfma_f32_16x16x32_bf16 v[78:81], v[118:121], v[198:201], v[78:81]
	v_mfma_f32_16x16x32_bf16 v[90:93], v[138:141], v[198:201], v[90:93]
	v_mfma_f32_16x16x32_bf16 v[130:133], v[118:121], v[206:209], v[130:133]
	v_mfma_f32_16x16x32_bf16 v[114:117], v[138:141], v[206:209], v[114:117]
	v_mfma_f32_16x16x32_bf16 v[26:29], v[146:149], v[182:185], v[26:29]
	v_mfma_f32_16x16x32_bf16 v[50:53], v[154:157], v[182:185], v[50:53]
	v_mfma_f32_16x16x32_bf16 v[58:61], v[146:149], v[190:193], v[58:61]
	v_mfma_f32_16x16x32_bf16 v[82:85], v[154:157], v[190:193], v[82:85]
	v_mfma_f32_16x16x32_bf16 v[110:113], v[146:149], v[198:201], v[110:113]
	v_mfma_f32_16x16x32_bf16 v[106:109], v[154:157], v[198:201], v[106:109]
	v_mfma_f32_16x16x32_bf16 v[122:125], v[146:149], v[206:209], v[122:125]
	v_mfma_f32_16x16x32_bf16 v[126:129], v[154:157], v[206:209], v[126:129]
	v_mfma_f32_16x16x32_bf16 v[34:37], v[134:137], v[186:189], v[34:37]
	v_mfma_f32_16x16x32_bf16 v[30:33], v[142:145], v[186:189], v[30:33]
	v_mfma_f32_16x16x32_bf16 v[46:49], v[134:137], v[194:197], v[46:49]
	v_mfma_f32_16x16x32_bf16 v[62:65], v[142:145], v[194:197], v[62:65]
	v_mfma_f32_16x16x32_bf16 v[78:81], v[134:137], v[202:205], v[78:81]
	v_mfma_f32_16x16x32_bf16 v[90:93], v[142:145], v[202:205], v[90:93]
	v_mfma_f32_16x16x32_bf16 v[130:133], v[134:137], v[210:213], v[130:133]
	v_mfma_f32_16x16x32_bf16 v[114:117], v[142:145], v[210:213], v[114:117]
	v_mfma_f32_16x16x32_bf16 v[26:29], v[150:153], v[186:189], v[26:29]
	v_mfma_f32_16x16x32_bf16 v[50:53], v[178:181], v[186:189], v[50:53]
	v_mfma_f32_16x16x32_bf16 v[58:61], v[150:153], v[194:197], v[58:61]
	v_mfma_f32_16x16x32_bf16 v[82:85], v[178:181], v[194:197], v[82:85]
	v_mfma_f32_16x16x32_bf16 v[110:113], v[150:153], v[202:205], v[110:113]
	v_mfma_f32_16x16x32_bf16 v[106:109], v[178:181], v[202:205], v[106:109]
	v_mfma_f32_16x16x32_bf16 v[122:125], v[150:153], v[210:213], v[122:125]
	s_setprio 0
	v_mfma_f32_16x16x32_bf16 v[126:129], v[178:181], v[210:213], v[126:129]
	s_barrier
;     __device__ __forceinline__ void mid(f32x4 (&acc)[2][2][4][2], const Unit& u, int wr, int wc, int fr, int fq) const {
;     ...
;         const int row0 = u.pm * BM + wr * 64 + fr, col0 = u.pn * BM + wc * 32 + 8 * fq;
; #pragma unroll
;         for (int ai = 0; ai < 2; ++ai)
; #pragma unroll
;             for (int m = 0; m < 4; ++m) { const size_t off = (size_t)(row0 + ai * HALF + m * 16) * 4096 + col0;
; #pragma unroll
;                 for (int bj = 0; bj < 2; ++bj) { const u32x4 ga = *(const u32x4*)(SGA + off + bj * HALF), gb = *(const u32x4*)(SGB + off + bj * HALF);
	s_add_u32 s0, s24, 0x80
	s_addc_u32 s1, s25, 0
	s_add_i32 s84, s84, s45
	s_mov_b32 m0, s84
	s_add_i32 s85, s84, 0x2000
	ds_read_b128 v[182:185], v174 offset:49152
	ds_read_b128 v[186:189], v174 offset:50176
	ds_read_b128 v[190:193], v174 offset:51200
	ds_read_b128 v[194:197], v174 offset:52224
	ds_read_b128 v[198:201], v174 offset:53248
	ds_read_b128 v[202:205], v174 offset:54272
	ds_read_b128 v[206:209], v174 offset:55296
	ds_read_b128 v[210:213], v174 offset:56320
	s_nop 0
	global_load_lds_dwordx4 v164, s[0:1]
	s_mov_b32 m0, s85
	s_nop 0
	global_load_lds_dwordx4 v166, s[0:1]
	s_add_u32 s0, s24, 0x100080
	s_addc_u32 s1, s25, 0
	s_add_i32 s86, s86, s45
	s_mov_b32 m0, s86
	s_add_i32 s87, s86, 0x2000
	s_nop 0
	global_load_lds_dwordx4 v164, s[0:1]
	s_mov_b32 m0, s87
	s_nop 0
	global_load_lds_dwordx4 v166, s[0:1]
	s_mov_b32 m0, s57
	s_nop 0
	global_load_lds_dwordx4 v1, s[2:3]
	s_mov_b32 m0, s62
	s_nop 0
	global_load_lds_dwordx4 v165, s[2:3]
	s_waitcnt vmcnt(8)
	s_waitcnt lgkmcnt(0)
	s_setprio 1
	s_waitcnt lgkmcnt(0)
	s_barrier
	v_mfma_f32_16x16x32_bf16 v[102:105], v[118:121], v[182:185], v[102:105]
	v_mfma_f32_16x16x32_bf16 v[98:101], v[138:141], v[182:185], v[98:101]
	v_mfma_f32_16x16x32_bf16 v[74:77], v[118:121], v[190:193], v[74:77]
	v_mfma_f32_16x16x32_bf16 v[70:73], v[138:141], v[190:193], v[70:73]
	v_mfma_f32_16x16x32_bf16 v[42:45], v[118:121], v[198:201], v[42:45]
	v_mfma_f32_16x16x32_bf16 v[38:41], v[138:141], v[198:201], v[38:41]
	v_mfma_f32_16x16x32_bf16 v[18:21], v[118:121], v[206:209], v[18:21]
	v_mfma_f32_16x16x32_bf16 v[10:13], v[138:141], v[206:209], v[10:13]
	v_mfma_f32_16x16x32_bf16 v[94:97], v[146:149], v[182:185], v[94:97]
	v_mfma_f32_16x16x32_bf16 v[86:89], v[154:157], v[182:185], v[86:89]
	v_mfma_f32_16x16x32_bf16 v[66:69], v[146:149], v[190:193], v[66:69]
	v_mfma_f32_16x16x32_bf16 v[54:57], v[154:157], v[190:193], v[54:57]
	v_mfma_f32_16x16x32_bf16 v[22:25], v[146:149], v[198:201], v[22:25]
	v_mfma_f32_16x16x32_bf16 v[14:17], v[154:157], v[198:201], v[14:17]
	v_mfma_f32_16x16x32_bf16 v[6:9], v[146:149], v[206:209], v[6:9]
	v_mfma_f32_16x16x32_bf16 v[2:5], v[154:157], v[206:209], v[2:5]
	v_mfma_f32_16x16x32_bf16 v[102:105], v[134:137], v[186:189], v[102:105]
	v_mfma_f32_16x16x32_bf16 v[98:101], v[142:145], v[186:189], v[98:101]
	v_mfma_f32_16x16x32_bf16 v[74:77], v[134:137], v[194:197], v[74:77]
	v_mfma_f32_16x16x32_bf16 v[70:73], v[142:145], v[194:197], v[70:73]
	v_mfma_f32_16x16x32_bf16 v[42:45], v[134:137], v[202:205], v[42:45]
	v_mfma_f32_16x16x32_bf16 v[38:41], v[142:145], v[202:205], v[38:41]
	v_mfma_f32_16x16x32_bf16 v[18:21], v[134:137], v[210:213], v[18:21]
	v_mfma_f32_16x16x32_bf16 v[10:13], v[142:145], v[210:213], v[10:13]
	v_mfma_f32_16x16x32_bf16 v[94:97], v[150:153], v[186:189], v[94:97]
	v_mfma_f32_16x16x32_bf16 v[86:89], v[178:181], v[186:189], v[86:89]
	v_mfma_f32_16x16x32_bf16 v[66:69], v[150:153], v[194:197], v[66:69]
	v_mfma_f32_16x16x32_bf16 v[54:57], v[178:181], v[194:197], v[54:57]
	v_mfma_f32_16x16x32_bf16 v[22:25], v[150:153], v[202:205], v[22:25]
	v_mfma_f32_16x16x32_bf16 v[14:17], v[178:181], v[202:205], v[14:17]
	v_mfma_f32_16x16x32_bf16 v[6:9], v[150:153], v[210:213], v[6:9]
	s_setprio 0
	v_mfma_f32_16x16x32_bf16 v[2:5], v[178:181], v[210:213], v[2:5]
	s_barrier
	s_add_i32 s33, s33, 2
	s_add_u32 s5, s5, 0x100
	s_addc_u32 s21, s21, 0
	s_cmp_gt_u32 s33, 29
	s_mov_b64 s[0:1], s[16:17]
	s_cbranch_scc0 .LBB0_746
	v_mov_b32_e32 v119, v167
	v_mov_b32_e32 v118, v168
	s_lshl_b32 s89, s20, 8
	s_lshl_b32 s88, s4, 8
	s_or_b32 s0, s89, s56
	v_lshl_add_u32 v118, v118, 3, s0
	s_add_i32 s0, s88, s55
	v_add_u32_e32 v120, s0, v119
	v_ashrrev_i32_e32 v121, 31, v120
	v_ashrrev_i32_e32 v119, 31, v118
	v_lshlrev_b64 v[120:121], 12, v[120:121]
	v_lshl_add_u64 v[118:119], v[120:121], 0, v[118:119]
	v_lshlrev_b64 v[162:163], 1, v[118:119]
	v_lshl_add_u64 v[138:139], s[12:13], 0, v[162:163]
	global_load_dwordx4 v[134:137], v[138:139], off
	v_lshl_add_u64 v[140:141], s[10:11], 0, v[162:163]
	global_load_dwordx4 v[118:121], v[140:141], off
	global_load_dwordx4 v[150:153], v[138:139], off offset:256
	global_load_dwordx4 v[146:149], v[140:141], off offset:256
	s_mov_b64 s[0:1], 0x20000
	v_lshl_add_u64 v[138:139], v[162:163], 0, s[0:1]
	v_lshl_add_u64 v[154:155], s[10:11], 0, v[138:139]
	v_lshl_add_u64 v[156:157], s[12:13], 0, v[138:139]
	global_load_dwordx4 v[138:141], v[154:155], off
	global_load_dwordx4 v[142:145], v[156:157], off
	s_mov_b64 s[0:1], 0x40000
	s_add_i32 s50, s50, 1
	v_readlane_b32 s2, v238, 45
	s_waitcnt vmcnt(0)
; __device__ __forceinline__ float bf_lo(unsigned w) { return __uint_as_float(w << 16); }
; __device__ __forceinline__ float bf_hi(unsigned w) { return __uint_as_float(w & 0xffff0000u); }
;     __device__ __forceinline__ void mid(f32x4 (&acc)[2][2][4][2], const Unit& u, int wr, int wc, int fr, int fq) const {
;     ...
;             for (int m = 0; m < 4; ++m) { const size_t off = (size_t)(row0 + ai * HALF + m * 16) * 4096 + col0;
; #pragma unroll
;                 for (int bj = 0; bj < 2; ++bj) { const u32x4 ga = *(const u32x4*)(SGA + off + bj * HALF), gb = *(const u32x4*)(SGB + off + bj * HALF);
;                     const unsigned wa[4] = {ga.x, ga.y, ga.z, ga.w}, wb[4] = {gb.x, gb.y, gb.z, gb.w};
; #pragma unroll
;                     for (int p = 0; p < 4; ++p) { const float rl = bf_lo(wa[p]) * __builtin_amdgcn_rcpf(fmaxf(bf_lo(wb[p]), 1e-20f)), rh = bf_hi(wa[p]) * __builtin_amdgcn_rcpf(fmaxf(bf_hi(wb[p]), 1e-20f));
;                         acc[ai][bj][m][p >> 1][(p & 1) * 2] *= rl; acc[ai][bj][m][p >> 1][(p & 1) * 2 + 1] *= rh; } }
	v_lshlrev_b32_e32 v178, 16, v118
	v_and_b32_e32 v180, 0xffff0000, v134
	v_lshlrev_b32_e32 v181, 16, v135
	v_and_b32_e32 v182, 0xffff0000, v135
	v_lshlrev_b32_e32 v183, 16, v136
	v_and_b32_e32 v184, 0xffff0000, v136
	v_lshlrev_b32_e32 v185, 16, v137
	v_and_b32_e32 v186, 0xffff0000, v137
	v_lshlrev_b32_e32 v187, 16, v150
	v_and_b32_e32 v150, 0xffff0000, v150
	v_lshlrev_b32_e32 v188, 16, v151
	v_and_b32_e32 v151, 0xffff0000, v151
	v_max_f32_e32 v180, v180, v180
	v_max_f32_e32 v181, v181, v181
	v_max_f32_e32 v182, v182, v182
	v_max_f32_e32 v183, v183, v183
	v_max_f32_e32 v184, v184, v184
	v_max_f32_e32 v185, v185, v185
	v_max_f32_e32 v186, v186, v186
	v_max_f32_e32 v187, v187, v187
	v_max_f32_e32 v150, v150, v150
	v_max_f32_e32 v188, v188, v188
	v_max_f32_e32 v151, v151, v151
	v_max_f32_e32 v180, 0x1e3ce508, v180
	v_max_f32_e32 v181, 0x1e3ce508, v181
	v_max_f32_e32 v182, 0x1e3ce508, v182
	v_max_f32_e32 v183, 0x1e3ce508, v183
	v_max_f32_e32 v184, 0x1e3ce508, v184
	v_max_f32_e32 v185, 0x1e3ce508, v185
	v_max_f32_e32 v186, 0x1e3ce508, v186
	v_max_f32_e32 v187, 0x1e3ce508, v187
	v_max_f32_e32 v189, 0x1e3ce508, v150
	v_max_f32_e32 v188, 0x1e3ce508, v188
	v_max_f32_e32 v190, 0x1e3ce508, v151
	v_rcp_f32_e32 v151, v180
	v_rcp_f32_e32 v180, v181
	v_rcp_f32_e32 v181, v182
	v_rcp_f32_e32 v182, v183
	v_rcp_f32_e32 v183, v184
	v_rcp_f32_e32 v184, v185
	v_rcp_f32_e32 v185, v186
	v_rcp_f32_e32 v186, v187
	v_rcp_f32_e32 v187, v189
	v_rcp_f32_e32 v188, v188
	v_rcp_f32_e32 v189, v190
	v_and_b32_e32 v179, 0xffff0000, v118
	v_lshlrev_b32_e32 v118, 16, v119
	v_and_b32_e32 v119, 0xffff0000, v119
	v_lshlrev_b32_e32 v177, 16, v134
	v_lshlrev_b32_e32 v134, 16, v120
	v_and_b32_e32 v135, 0xffff0000, v120
	v_lshlrev_b32_e32 v120, 16, v121
	v_and_b32_e32 v121, 0xffff0000, v121
	v_lshlrev_b32_e32 v136, 16, v146
	v_and_b32_e32 v137, 0xffff0000, v146
	v_lshlrev_b32_e32 v146, 16, v147
	v_and_b32_e32 v147, 0xffff0000, v147
	v_pk_mul_f32 v[118:119], v[180:181], v[118:119]
	v_pk_mul_f32 v[134:135], v[182:183], v[134:135]
	v_pk_mul_f32 v[120:121], v[184:185], v[120:121]
	v_pk_mul_f32 v[36:37], v[36:37], v[118:119]
	v_pk_mul_f32 v[118:119], v[188:189], v[146:147]
	v_pk_mul_f32 v[30:31], v[30:31], v[134:135]
	v_pk_mul_f32 v[32:33], v[32:33], v[120:121]
	v_pk_mul_f32 v[28:29], v[28:29], v[118:119]
	global_load_dwordx4 v[118:121], v[156:157], off offset:256
	v_lshlrev_b32_e32 v134, 16, v152
	v_max_f32_e32 v134, v134, v134
	v_max_f32_e32 v134, 0x1e3ce508, v134
	v_rcp_f32_e32 v146, v134
	v_and_b32_e32 v134, 0xffff0000, v152
	v_max_f32_e32 v134, v134, v134
	v_pk_mul_f32 v[136:137], v[186:187], v[136:137]
	v_max_f32_e32 v134, 0x1e3ce508, v134
	v_pk_mul_f32 v[26:27], v[26:27], v[136:137]
	v_rcp_f32_e32 v147, v134
	global_load_dwordx4 v[134:137], v[154:155], off offset:256
	v_max_f32_e32 v177, v177, v177
	v_max_f32_e32 v177, 0x1e3ce508, v177
	v_rcp_f32_e32 v150, v177
	s_nop 0
	v_pk_mul_f32 v[150:151], v[150:151], v[178:179]
	s_nop 0
	v_pk_mul_f32 v[34:35], v[34:35], v[150:151]
	v_lshlrev_b32_e32 v150, 16, v148
	v_and_b32_e32 v151, 0xffff0000, v148
	v_lshlrev_b32_e32 v148, 16, v153
	v_max_f32_e32 v148, v148, v148
	v_max_f32_e32 v148, 0x1e3ce508, v148
	v_pk_mul_f32 v[146:147], v[146:147], v[150:151]
	v_rcp_f32_e32 v150, v148
	v_and_b32_e32 v148, 0xffff0000, v153
	v_max_f32_e32 v148, v148, v148
	v_max_f32_e32 v148, 0x1e3ce508, v148
	v_rcp_f32_e32 v151, v148
	v_pk_mul_f32 v[50:51], v[50:51], v[146:147]
	v_lshlrev_b32_e32 v146, 16, v149
	v_and_b32_e32 v147, 0xffff0000, v149
	v_pk_mul_f32 v[146:147], v[150:151], v[146:147]
	v_lshlrev_b32_e32 v148, 16, v142
	v_and_b32_e32 v142, 0xffff0000, v142
	v_pk_mul_f32 v[52:53], v[52:53], v[146:147]
	v_lshlrev_b32_e32 v146, 16, v138
	v_and_b32_e32 v147, 0xffff0000, v138
	v_lshlrev_b32_e32 v138, 16, v143
	v_max_f32_e32 v148, v148, v148
	v_max_f32_e32 v142, v142, v142
	v_max_f32_e32 v138, v138, v138
	v_max_f32_e32 v148, 0x1e3ce508, v148
	v_max_f32_e32 v142, 0x1e3ce508, v142
	v_max_f32_e32 v138, 0x1e3ce508, v138
	v_rcp_f32_e32 v148, v148
	v_rcp_f32_e32 v149, v142
	v_rcp_f32_e32 v142, v138
	v_and_b32_e32 v138, 0xffff0000, v143
	v_max_f32_e32 v138, v138, v138
	v_max_f32_e32 v138, 0x1e3ce508, v138
	v_rcp_f32_e32 v143, v138
	v_lshl_add_u64 v[150:151], v[162:163], 0, s[0:1]
	v_pk_mul_f32 v[146:147], v[148:149], v[146:147]
	v_lshl_add_u64 v[154:155], s[12:13], 0, v[150:151]
	v_pk_mul_f32 v[46:47], v[46:47], v[146:147]
	global_load_dwordx4 v[146:149], v[154:155], off
	v_lshlrev_b32_e32 v138, 16, v139
	v_and_b32_e32 v139, 0xffff0000, v139
	v_pk_mul_f32 v[138:139], v[142:143], v[138:139]
	v_lshlrev_b32_e32 v142, 16, v144
	v_max_f32_e32 v142, v142, v142
	v_max_f32_e32 v142, 0x1e3ce508, v142
	v_rcp_f32_e32 v156, v142
	v_lshl_add_u64 v[142:143], s[10:11], 0, v[150:151]
	global_load_dwordx4 v[150:153], v[142:143], off
	v_and_b32_e32 v144, 0xffff0000, v144
	v_pk_mul_f32 v[48:49], v[48:49], v[138:139]
	v_lshlrev_b32_e32 v138, 16, v140
	v_and_b32_e32 v139, 0xffff0000, v140
	v_lshlrev_b32_e32 v140, 16, v145
	v_max_f32_e32 v144, v144, v144
	v_max_f32_e32 v140, v140, v140
	v_max_f32_e32 v144, 0x1e3ce508, v144
	v_max_f32_e32 v140, 0x1e3ce508, v140
	v_rcp_f32_e32 v157, v144
	v_rcp_f32_e32 v144, v140
	v_and_b32_e32 v140, 0xffff0000, v145
	v_max_f32_e32 v140, v140, v140
	v_max_f32_e32 v140, 0x1e3ce508, v140
	v_rcp_f32_e32 v145, v140
	s_waitcnt vmcnt(3)
	v_lshlrev_b32_e32 v140, 16, v118
	v_and_b32_e32 v118, 0xffff0000, v118
	v_max_f32_e32 v140, v140, v140
	v_max_f32_e32 v118, v118, v118
	v_pk_mul_f32 v[138:139], v[156:157], v[138:139]
	v_max_f32_e32 v140, 0x1e3ce508, v140
	v_max_f32_e32 v118, 0x1e3ce508, v118
	v_pk_mul_f32 v[62:63], v[62:63], v[138:139]
	v_lshlrev_b32_e32 v138, 16, v141
	v_and_b32_e32 v139, 0xffff0000, v141
	v_rcp_f32_e32 v140, v140
	v_rcp_f32_e32 v141, v118
	v_pk_mul_f32 v[138:139], v[144:145], v[138:139]
	global_load_dwordx4 v[142:145], v[142:143], off offset:256
	v_pk_mul_f32 v[64:65], v[64:65], v[138:139]
	s_waitcnt vmcnt(3)
; __device__ __forceinline__ float bf_lo(unsigned w) { return __uint_as_float(w << 16); }
; __device__ __forceinline__ float bf_hi(unsigned w) { return __uint_as_float(w & 0xffff0000u); }
;     __device__ __forceinline__ void mid(f32x4 (&acc)[2][2][4][2], const Unit& u, int wr, int wc, int fr, int fq) const {
;     ...
;             for (int m = 0; m < 4; ++m) { const size_t off = (size_t)(row0 + ai * HALF + m * 16) * 4096 + col0;
; #pragma unroll
;                 for (int bj = 0; bj < 2; ++bj) { const u32x4 ga = *(const u32x4*)(SGA + off + bj * HALF), gb = *(const u32x4*)(SGB + off + bj * HALF);
;                     const unsigned wa[4] = {ga.x, ga.y, ga.z, ga.w}, wb[4] = {gb.x, gb.y, gb.z, gb.w};
; #pragma unroll
;                     for (int p = 0; p < 4; ++p) { const float rl = bf_lo(wa[p]) * __builtin_amdgcn_rcpf(fmaxf(bf_lo(wb[p]), 1e-20f)), rh = bf_hi(wa[p]) * __builtin_amdgcn_rcpf(fmaxf(bf_hi(wb[p]), 1e-20f));
;                         acc[ai][bj][m][p >> 1][(p & 1) * 2] *= rl; acc[ai][bj][m][p >> 1][(p & 1) * 2 + 1] *= rh; } }
	v_lshlrev_b32_e32 v138, 16, v134
	v_and_b32_e32 v139, 0xffff0000, v134
	v_pk_mul_f32 v[138:139], v[140:141], v[138:139]
	v_lshlrev_b32_e32 v118, 16, v119
	v_pk_mul_f32 v[58:59], v[58:59], v[138:139]
	global_load_dwordx4 v[138:141], v[154:155], off offset:256
	v_and_b32_e32 v119, 0xffff0000, v119
	v_max_f32_e32 v118, v118, v118
	v_max_f32_e32 v119, v119, v119
	v_max_f32_e32 v118, 0x1e3ce508, v118
	v_max_f32_e32 v119, 0x1e3ce508, v119
	v_rcp_f32_e32 v118, v118
	v_rcp_f32_e32 v119, v119
	v_lshlrev_b32_e32 v134, 16, v135
	v_and_b32_e32 v135, 0xffff0000, v135
	s_mov_b64 s[0:1], 0x60000
	v_pk_mul_f32 v[118:119], v[118:119], v[134:135]
	v_lshlrev_b32_e32 v134, 16, v136
	v_pk_mul_f32 v[60:61], v[60:61], v[118:119]
	v_lshlrev_b32_e32 v118, 16, v120
	v_and_b32_e32 v119, 0xffff0000, v120
	v_max_f32_e32 v118, v118, v118
	v_max_f32_e32 v119, v119, v119
	v_max_f32_e32 v118, 0x1e3ce508, v118
	v_max_f32_e32 v119, 0x1e3ce508, v119
	v_lshlrev_b32_e32 v120, 16, v121
	v_and_b32_e32 v121, 0xffff0000, v121
	v_rcp_f32_e32 v118, v118
	v_rcp_f32_e32 v119, v119
	v_max_f32_e32 v120, v120, v120
	v_max_f32_e32 v121, v121, v121
	v_max_f32_e32 v120, 0x1e3ce508, v120
	v_max_f32_e32 v121, 0x1e3ce508, v121
	v_rcp_f32_e32 v120, v120
	v_rcp_f32_e32 v121, v121
	v_and_b32_e32 v135, 0xffff0000, v136
	v_pk_mul_f32 v[118:119], v[118:119], v[134:135]
	s_nop 0
	v_pk_mul_f32 v[82:83], v[82:83], v[118:119]
	v_lshlrev_b32_e32 v118, 16, v137
	v_and_b32_e32 v119, 0xffff0000, v137
	v_pk_mul_f32 v[118:119], v[120:121], v[118:119]
	s_waitcnt vmcnt(3)
	v_lshlrev_b32_e32 v120, 16, v146
	v_and_b32_e32 v121, 0xffff0000, v146
	v_max_f32_e32 v120, v120, v120
	v_max_f32_e32 v121, v121, v121
	v_max_f32_e32 v120, 0x1e3ce508, v120
	v_max_f32_e32 v121, 0x1e3ce508, v121
	v_rcp_f32_e32 v120, v120
	v_rcp_f32_e32 v121, v121
	v_pk_mul_f32 v[84:85], v[84:85], v[118:119]
	s_waitcnt vmcnt(2)
	v_lshlrev_b32_e32 v118, 16, v150
	v_and_b32_e32 v119, 0xffff0000, v150
	v_pk_mul_f32 v[118:119], v[120:121], v[118:119]
	v_lshlrev_b32_e32 v150, 16, v151
	v_pk_mul_f32 v[78:79], v[78:79], v[118:119]
	v_lshlrev_b32_e32 v118, 16, v147
	v_and_b32_e32 v119, 0xffff0000, v147
	v_lshl_add_u64 v[146:147], v[162:163], 0, s[0:1]
	v_lshl_add_u64 v[120:121], s[12:13], 0, v[146:147]
	v_max_f32_e32 v118, v118, v118
	v_max_f32_e32 v119, v119, v119
	global_load_dwordx4 v[134:137], v[120:121], off
	v_max_f32_e32 v118, 0x1e3ce508, v118
	v_max_f32_e32 v119, 0x1e3ce508, v119
	v_rcp_f32_e32 v118, v118
	v_rcp_f32_e32 v119, v119
	v_and_b32_e32 v151, 0xffff0000, v151
	s_mov_b64 s[0:1], 0x120000
	v_pk_mul_f32 v[150:151], v[118:119], v[150:151]
	v_lshlrev_b32_e32 v118, 16, v148
	v_max_f32_e32 v118, v118, v118
	v_max_f32_e32 v118, 0x1e3ce508, v118
	v_rcp_f32_e32 v178, v118
	v_lshl_add_u64 v[118:119], s[10:11], 0, v[146:147]
	global_load_dwordx4 v[154:157], v[118:119], off
	v_and_b32_e32 v146, 0xffff0000, v148
	v_max_f32_e32 v146, v146, v146
	v_max_f32_e32 v146, 0x1e3ce508, v146
	v_lshlrev_b32_e32 v148, 16, v149
	v_and_b32_e32 v149, 0xffff0000, v149
	v_rcp_f32_e32 v179, v146
	v_max_f32_e32 v148, v148, v148
	v_max_f32_e32 v149, v149, v149
	v_max_f32_e32 v148, 0x1e3ce508, v148
	v_max_f32_e32 v149, 0x1e3ce508, v149
	v_rcp_f32_e32 v148, v148
	v_rcp_f32_e32 v149, v149
	v_lshlrev_b32_e32 v146, 16, v152
	v_and_b32_e32 v147, 0xffff0000, v152
	v_pk_mul_f32 v[146:147], v[178:179], v[146:147]
	v_pk_mul_f32 v[80:81], v[80:81], v[150:151]
	v_pk_mul_f32 v[90:91], v[90:91], v[146:147]
	v_lshlrev_b32_e32 v146, 16, v153
	v_and_b32_e32 v147, 0xffff0000, v153
	v_pk_mul_f32 v[146:147], v[148:149], v[146:147]
	s_waitcnt vmcnt(2)
	v_lshlrev_b32_e32 v148, 16, v138
	v_and_b32_e32 v138, 0xffff0000, v138
	v_max_f32_e32 v148, v148, v148
	v_max_f32_e32 v138, v138, v138
	v_max_f32_e32 v148, 0x1e3ce508, v148
	v_max_f32_e32 v138, 0x1e3ce508, v138
	global_load_dwordx4 v[150:153], v[120:121], off offset:256
	v_rcp_f32_e32 v148, v148
	v_rcp_f32_e32 v149, v138
	v_pk_mul_f32 v[92:93], v[92:93], v[146:147]
	v_lshlrev_b32_e32 v146, 16, v142
	v_and_b32_e32 v147, 0xffff0000, v142
	v_pk_mul_f32 v[146:147], v[148:149], v[146:147]
	v_lshlrev_b32_e32 v138, 16, v139
	v_pk_mul_f32 v[110:111], v[110:111], v[146:147]
	global_load_dwordx4 v[146:149], v[118:119], off offset:256
	v_and_b32_e32 v139, 0xffff0000, v139
	v_max_f32_e32 v138, v138, v138
	v_max_f32_e32 v139, v139, v139
	v_max_f32_e32 v138, 0x1e3ce508, v138
	v_max_f32_e32 v120, 0x1e3ce508, v139
	v_rcp_f32_e32 v138, v138
	v_rcp_f32_e32 v139, v120
	v_lshlrev_b32_e32 v120, 16, v143
	v_and_b32_e32 v121, 0xffff0000, v143
	v_and_b32_e32 v119, 0xffff0000, v140
	v_pk_mul_f32 v[120:121], v[138:139], v[120:121]
	v_lshlrev_b32_e32 v138, 16, v140
	v_max_f32_e32 v138, v138, v138
	v_max_f32_e32 v119, v119, v119
	v_max_f32_e32 v118, 0x1e3ce508, v138
	v_max_f32_e32 v119, 0x1e3ce508, v119
	v_rcp_f32_e32 v118, v118
	v_rcp_f32_e32 v119, v119
	v_pk_mul_f32 v[112:113], v[112:113], v[120:121]
	v_lshlrev_b32_e32 v120, 16, v144
	v_and_b32_e32 v121, 0xffff0000, v144
	v_pk_mul_f32 v[118:119], v[118:119], v[120:121]
	v_lshlrev_b32_e32 v120, 16, v141
	v_and_b32_e32 v121, 0xffff0000, v141
	v_max_f32_e32 v120, v120, v120
	v_max_f32_e32 v121, v121, v121
	v_max_f32_e32 v120, 0x1e3ce508, v120
	v_max_f32_e32 v121, 0x1e3ce508, v121
	v_rcp_f32_e32 v120, v120
	v_rcp_f32_e32 v121, v121
	v_pk_mul_f32 v[118:119], v[106:107], v[118:119]
	v_lshlrev_b32_e32 v106, 16, v145
	v_and_b32_e32 v107, 0xffff0000, v145
	v_pk_mul_f32 v[106:107], v[120:121], v[106:107]
	s_waitcnt vmcnt(3)
; __device__ __forceinline__ float bf_lo(unsigned w) { return __uint_as_float(w << 16); }
; __device__ __forceinline__ float bf_hi(unsigned w) { return __uint_as_float(w & 0xffff0000u); }
;     __device__ __forceinline__ void mid(f32x4 (&acc)[2][2][4][2], const Unit& u, int wr, int wc, int fr, int fq) const {
;     ...
;             for (int m = 0; m < 4; ++m) { const size_t off = (size_t)(row0 + ai * HALF + m * 16) * 4096 + col0;
; #pragma unroll
;                 for (int bj = 0; bj < 2; ++bj) { const u32x4 ga = *(const u32x4*)(SGA + off + bj * HALF), gb = *(const u32x4*)(SGB + off + bj * HALF);
;                     const unsigned wa[4] = {ga.x, ga.y, ga.z, ga.w}, wb[4] = {gb.x, gb.y, gb.z, gb.w};
; #pragma unroll
;                     for (int p = 0; p < 4; ++p) { const float rl = bf_lo(wa[p]) * __builtin_amdgcn_rcpf(fmaxf(bf_lo(wb[p]), 1e-20f)), rh = bf_hi(wa[p]) * __builtin_amdgcn_rcpf(fmaxf(bf_hi(wb[p]), 1e-20f));
;                         acc[ai][bj][m][p >> 1][(p & 1) * 2] *= rl; acc[ai][bj][m][p >> 1][(p & 1) * 2 + 1] *= rh; } }
	v_lshlrev_b32_e32 v120, 16, v134
	v_max_f32_e32 v120, v120, v120
	v_max_f32_e32 v120, 0x1e3ce508, v120
	v_rcp_f32_e32 v138, v120
	v_and_b32_e32 v120, 0xffff0000, v134
	v_max_f32_e32 v120, v120, v120
	v_max_f32_e32 v120, 0x1e3ce508, v120
	v_rcp_f32_e32 v139, v120
	v_pk_mul_f32 v[120:121], v[108:109], v[106:107]
	v_lshlrev_b32_e32 v108, 16, v135
	v_and_b32_e32 v109, 0xffff0000, v135
	v_max_f32_e32 v108, v108, v108
	v_max_f32_e32 v109, v109, v109
	v_max_f32_e32 v108, 0x1e3ce508, v108
	v_max_f32_e32 v109, 0x1e3ce508, v109
	v_rcp_f32_e32 v108, v108
	v_rcp_f32_e32 v109, v109
	s_waitcnt vmcnt(2)
	v_lshlrev_b32_e32 v106, 16, v154
	v_and_b32_e32 v107, 0xffff0000, v154
	v_pk_mul_f32 v[106:107], v[138:139], v[106:107]
	v_lshl_add_u64 v[140:141], v[162:163], 0, s[0:1]
	v_pk_mul_f32 v[106:107], v[130:131], v[106:107]
	v_lshlrev_b32_e32 v130, 16, v155
	v_and_b32_e32 v131, 0xffff0000, v155
	v_pk_mul_f32 v[108:109], v[108:109], v[130:131]
	v_lshlrev_b32_e32 v130, 16, v136
	v_and_b32_e32 v131, 0xffff0000, v136
	v_max_f32_e32 v130, v130, v130
	v_max_f32_e32 v131, v131, v131
	v_max_f32_e32 v130, 0x1e3ce508, v130
	v_max_f32_e32 v131, 0x1e3ce508, v131
	v_rcp_f32_e32 v130, v130
	v_rcp_f32_e32 v131, v131
	v_pk_mul_f32 v[108:109], v[132:133], v[108:109]
	v_lshlrev_b32_e32 v132, 16, v156
	v_and_b32_e32 v133, 0xffff0000, v156
	v_pk_mul_f32 v[130:131], v[130:131], v[132:133]
	v_lshlrev_b32_e32 v132, 16, v137
	v_and_b32_e32 v133, 0xffff0000, v137
	v_max_f32_e32 v132, v132, v132
	v_max_f32_e32 v133, v133, v133
	v_max_f32_e32 v132, 0x1e3ce508, v132
	v_max_f32_e32 v133, 0x1e3ce508, v133
	v_rcp_f32_e32 v132, v132
	v_rcp_f32_e32 v133, v133
	v_pk_mul_f32 v[114:115], v[114:115], v[130:131]
	v_lshlrev_b32_e32 v130, 16, v157
	v_and_b32_e32 v131, 0xffff0000, v157
	v_pk_mul_f32 v[130:131], v[132:133], v[130:131]
	s_waitcnt vmcnt(1)
	v_lshlrev_b32_e32 v132, 16, v150
	v_and_b32_e32 v133, 0xffff0000, v150
	v_max_f32_e32 v132, v132, v132
	v_max_f32_e32 v133, v133, v133
	v_max_f32_e32 v132, 0x1e3ce508, v132
	v_max_f32_e32 v133, 0x1e3ce508, v133
	v_rcp_f32_e32 v132, v132
	v_rcp_f32_e32 v133, v133
	v_pk_mul_f32 v[116:117], v[116:117], v[130:131]
	s_waitcnt vmcnt(0)
	v_lshlrev_b32_e32 v130, 16, v146
	v_and_b32_e32 v131, 0xffff0000, v146
	v_pk_mul_f32 v[130:131], v[132:133], v[130:131]
	v_lshlrev_b32_e32 v132, 16, v151
	v_and_b32_e32 v133, 0xffff0000, v151
	v_max_f32_e32 v132, v132, v132
	v_max_f32_e32 v133, v133, v133
	v_max_f32_e32 v132, 0x1e3ce508, v132
	v_max_f32_e32 v133, 0x1e3ce508, v133
	v_rcp_f32_e32 v132, v132
	v_rcp_f32_e32 v133, v133
	v_pk_mul_f32 v[122:123], v[122:123], v[130:131]
	v_lshlrev_b32_e32 v130, 16, v147
	v_and_b32_e32 v131, 0xffff0000, v147
	v_pk_mul_f32 v[130:131], v[132:133], v[130:131]
	v_lshlrev_b32_e32 v132, 16, v152
	v_and_b32_e32 v133, 0xffff0000, v152
	v_max_f32_e32 v132, v132, v132
	v_max_f32_e32 v133, v133, v133
	v_max_f32_e32 v132, 0x1e3ce508, v132
	v_max_f32_e32 v133, 0x1e3ce508, v133
	v_rcp_f32_e32 v132, v132
	v_rcp_f32_e32 v133, v133
	v_pk_mul_f32 v[124:125], v[124:125], v[130:131]
	v_lshlrev_b32_e32 v130, 16, v148
	v_and_b32_e32 v131, 0xffff0000, v148
	v_pk_mul_f32 v[130:131], v[132:133], v[130:131]
	v_lshlrev_b32_e32 v132, 16, v153
	v_and_b32_e32 v133, 0xffff0000, v153
	v_max_f32_e32 v132, v132, v132
	v_max_f32_e32 v133, v133, v133
	v_max_f32_e32 v132, 0x1e3ce508, v132
	v_max_f32_e32 v133, 0x1e3ce508, v133
	v_rcp_f32_e32 v132, v132
	v_rcp_f32_e32 v133, v133
	v_pk_mul_f32 v[126:127], v[126:127], v[130:131]
	v_lshlrev_b32_e32 v130, 16, v149
	v_and_b32_e32 v131, 0xffff0000, v149
	v_pk_mul_f32 v[130:131], v[132:133], v[130:131]
	v_lshl_add_u64 v[154:155], s[12:13], 0, v[140:141]
	v_pk_mul_f32 v[128:129], v[128:129], v[130:131]
	v_lshl_add_u64 v[130:131], v[162:163], 0, s[8:9]
	v_lshl_add_u64 v[132:133], s[12:13], 0, v[130:131]
	global_load_dwordx4 v[150:153], v[132:133], off
	v_lshl_add_u64 v[130:131], s[10:11], 0, v[130:131]
	global_load_dwordx4 v[146:149], v[130:131], off
	global_load_dwordx4 v[142:145], v[132:133], off offset:256
	global_load_dwordx4 v[134:137], v[130:131], off offset:256
	s_mov_b64 s[0:1], 0x140000
	s_waitcnt vmcnt(3)
	v_lshlrev_b32_e32 v130, 16, v150
	v_and_b32_e32 v131, 0xffff0000, v150
	v_max_f32_e32 v130, v130, v130
	v_max_f32_e32 v131, v131, v131
	v_max_f32_e32 v130, 0x1e3ce508, v130
	v_max_f32_e32 v131, 0x1e3ce508, v131
	v_rcp_f32_e32 v130, v130
	v_rcp_f32_e32 v131, v131
	s_waitcnt vmcnt(2)
	v_lshlrev_b32_e32 v132, 16, v146
	v_and_b32_e32 v133, 0xffff0000, v146
	v_lshlrev_b32_e32 v146, 16, v147
	v_pk_mul_f32 v[130:131], v[130:131], v[132:133]
	v_and_b32_e32 v147, 0xffff0000, v147
	v_pk_mul_f32 v[102:103], v[102:103], v[130:131]
	v_lshlrev_b32_e32 v130, 16, v151
	v_max_f32_e32 v130, v130, v130
	v_max_f32_e32 v130, 0x1e3ce508, v130
	v_rcp_f32_e32 v138, v130
	v_and_b32_e32 v130, 0xffff0000, v151
	v_max_f32_e32 v130, v130, v130
	v_max_f32_e32 v130, 0x1e3ce508, v130
	v_rcp_f32_e32 v139, v130
	global_load_dwordx4 v[130:133], v[154:155], off
	v_lshl_add_u64 v[150:151], s[10:11], 0, v[140:141]
	v_pk_mul_f32 v[146:147], v[138:139], v[146:147]
	v_lshlrev_b32_e32 v138, 16, v152
	v_max_f32_e32 v138, v138, v138
	v_max_f32_e32 v138, 0x1e3ce508, v138
	v_rcp_f32_e32 v156, v138
	global_load_dwordx4 v[138:141], v[150:151], off
	v_and_b32_e32 v152, 0xffff0000, v152
	v_pk_mul_f32 v[104:105], v[104:105], v[146:147]
	v_lshlrev_b32_e32 v146, 16, v148
	v_and_b32_e32 v147, 0xffff0000, v148
	v_lshlrev_b32_e32 v148, 16, v153
	v_max_f32_e32 v152, v152, v152
	v_max_f32_e32 v148, v148, v148
	v_max_f32_e32 v152, 0x1e3ce508, v152
	v_max_f32_e32 v148, 0x1e3ce508, v148
	v_rcp_f32_e32 v157, v152
	v_rcp_f32_e32 v152, v148
	v_and_b32_e32 v148, 0xffff0000, v153
	v_max_f32_e32 v148, v148, v148
	v_max_f32_e32 v148, 0x1e3ce508, v148
	v_rcp_f32_e32 v153, v148
	s_waitcnt vmcnt(3)
; __device__ __forceinline__ float bf_lo(unsigned w) { return __uint_as_float(w << 16); }
; __device__ __forceinline__ float bf_hi(unsigned w) { return __uint_as_float(w & 0xffff0000u); }
;     __device__ __forceinline__ void mid(f32x4 (&acc)[2][2][4][2], const Unit& u, int wr, int wc, int fr, int fq) const {
;     ...
;             for (int m = 0; m < 4; ++m) { const size_t off = (size_t)(row0 + ai * HALF + m * 16) * 4096 + col0;
; #pragma unroll
;                 for (int bj = 0; bj < 2; ++bj) { const u32x4 ga = *(const u32x4*)(SGA + off + bj * HALF), gb = *(const u32x4*)(SGB + off + bj * HALF);
;                     const unsigned wa[4] = {ga.x, ga.y, ga.z, ga.w}, wb[4] = {gb.x, gb.y, gb.z, gb.w};
; #pragma unroll
;                     for (int p = 0; p < 4; ++p) { const float rl = bf_lo(wa[p]) * __builtin_amdgcn_rcpf(fmaxf(bf_lo(wb[p]), 1e-20f)), rh = bf_hi(wa[p]) * __builtin_amdgcn_rcpf(fmaxf(bf_hi(wb[p]), 1e-20f));
;                         acc[ai][bj][m][p >> 1][(p & 1) * 2] *= rl; acc[ai][bj][m][p >> 1][(p & 1) * 2 + 1] *= rh; } }
	v_lshlrev_b32_e32 v148, 16, v142
	v_and_b32_e32 v142, 0xffff0000, v142
	v_max_f32_e32 v148, v148, v148
	v_max_f32_e32 v142, v142, v142
	v_pk_mul_f32 v[146:147], v[156:157], v[146:147]
	v_max_f32_e32 v148, 0x1e3ce508, v148
	v_max_f32_e32 v142, 0x1e3ce508, v142
	v_pk_mul_f32 v[98:99], v[98:99], v[146:147]
	v_lshlrev_b32_e32 v146, 16, v149
	v_and_b32_e32 v147, 0xffff0000, v149
	v_rcp_f32_e32 v148, v148
	v_rcp_f32_e32 v149, v142
	v_pk_mul_f32 v[146:147], v[152:153], v[146:147]
	global_load_dwordx4 v[150:153], v[150:151], off offset:256
	v_pk_mul_f32 v[100:101], v[100:101], v[146:147]
	s_waitcnt vmcnt(3)
	v_lshlrev_b32_e32 v146, 16, v134
	v_and_b32_e32 v147, 0xffff0000, v134
	v_pk_mul_f32 v[146:147], v[148:149], v[146:147]
	v_lshlrev_b32_e32 v134, 16, v143
	v_pk_mul_f32 v[94:95], v[94:95], v[146:147]
	global_load_dwordx4 v[146:149], v[154:155], off offset:256
	v_max_f32_e32 v134, v134, v134
	v_max_f32_e32 v134, 0x1e3ce508, v134
	v_rcp_f32_e32 v142, v134
	v_and_b32_e32 v134, 0xffff0000, v143
	v_max_f32_e32 v134, v134, v134
	v_max_f32_e32 v134, 0x1e3ce508, v134
	v_rcp_f32_e32 v143, v134
	v_lshlrev_b32_e32 v134, 16, v135
	v_and_b32_e32 v135, 0xffff0000, v135
	v_pk_mul_f32 v[134:135], v[142:143], v[134:135]
	s_nop 0
	v_pk_mul_f32 v[96:97], v[96:97], v[134:135]
	v_lshlrev_b32_e32 v134, 16, v144
	v_and_b32_e32 v135, 0xffff0000, v144
	v_max_f32_e32 v134, v134, v134
	v_max_f32_e32 v135, v135, v135
	v_max_f32_e32 v134, 0x1e3ce508, v134
	v_max_f32_e32 v135, 0x1e3ce508, v135
	v_rcp_f32_e32 v134, v134
	v_rcp_f32_e32 v135, v135
	v_lshlrev_b32_e32 v142, 16, v136
	v_and_b32_e32 v143, 0xffff0000, v136
	v_lshlrev_b32_e32 v136, 16, v145
	v_max_f32_e32 v136, v136, v136
	v_max_f32_e32 v136, 0x1e3ce508, v136
	v_pk_mul_f32 v[134:135], v[134:135], v[142:143]
	v_rcp_f32_e32 v142, v136
	v_and_b32_e32 v136, 0xffff0000, v145
	v_max_f32_e32 v136, v136, v136
	v_max_f32_e32 v136, 0x1e3ce508, v136
	v_rcp_f32_e32 v143, v136
	v_pk_mul_f32 v[86:87], v[86:87], v[134:135]
	v_lshlrev_b32_e32 v134, 16, v137
	v_and_b32_e32 v135, 0xffff0000, v137
	v_pk_mul_f32 v[134:135], v[142:143], v[134:135]
	s_waitcnt vmcnt(3)
	v_lshlrev_b32_e32 v136, 16, v130
	v_and_b32_e32 v130, 0xffff0000, v130
	v_max_f32_e32 v130, v130, v130
	v_max_f32_e32 v130, 0x1e3ce508, v130
	v_rcp_f32_e32 v137, v130
	v_lshlrev_b32_e32 v130, 16, v131
	v_max_f32_e32 v136, v136, v136
	v_max_f32_e32 v130, v130, v130
	v_max_f32_e32 v136, 0x1e3ce508, v136
	v_max_f32_e32 v130, 0x1e3ce508, v130
	v_rcp_f32_e32 v136, v136
	v_rcp_f32_e32 v142, v130
	v_and_b32_e32 v130, 0xffff0000, v131
	v_max_f32_e32 v130, v130, v130
	v_max_f32_e32 v130, 0x1e3ce508, v130
	v_pk_mul_f32 v[88:89], v[88:89], v[134:135]
	s_waitcnt vmcnt(2)
	v_lshlrev_b32_e32 v134, 16, v138
	v_and_b32_e32 v135, 0xffff0000, v138
	v_rcp_f32_e32 v143, v130
	v_lshl_add_u64 v[144:145], v[162:163], 0, s[0:1]
	v_pk_mul_f32 v[134:135], v[136:137], v[134:135]
	v_lshl_add_u64 v[130:131], s[12:13], 0, v[144:145]
	v_pk_mul_f32 v[74:75], v[74:75], v[134:135]
	global_load_dwordx4 v[134:137], v[130:131], off
	v_lshlrev_b32_e32 v138, 16, v139
	v_and_b32_e32 v139, 0xffff0000, v139
	v_pk_mul_f32 v[154:155], v[142:143], v[138:139]
	v_lshlrev_b32_e32 v138, 16, v132
	v_max_f32_e32 v138, v138, v138
	v_and_b32_e32 v132, 0xffff0000, v132
	v_max_f32_e32 v138, 0x1e3ce508, v138
	v_max_f32_e32 v132, v132, v132
	v_rcp_f32_e32 v156, v138
	v_lshl_add_u64 v[138:139], s[10:11], 0, v[144:145]
	v_max_f32_e32 v132, 0x1e3ce508, v132
	global_load_dwordx4 v[142:145], v[138:139], off
	v_rcp_f32_e32 v157, v132
	v_lshlrev_b32_e32 v132, 16, v133
	v_and_b32_e32 v133, 0xffff0000, v133
	v_max_f32_e32 v132, v132, v132
	v_max_f32_e32 v133, v133, v133
	v_max_f32_e32 v132, 0x1e3ce508, v132
	v_max_f32_e32 v133, 0x1e3ce508, v133
	v_rcp_f32_e32 v132, v132
	v_rcp_f32_e32 v133, v133
	v_pk_mul_f32 v[76:77], v[76:77], v[154:155]
	v_lshlrev_b32_e32 v154, 16, v140
	v_and_b32_e32 v155, 0xffff0000, v140
	v_lshlrev_b32_e32 v140, 16, v141
	v_and_b32_e32 v141, 0xffff0000, v141
	v_pk_mul_f32 v[132:133], v[132:133], v[140:141]
	s_waitcnt vmcnt(2)
	v_lshlrev_b32_e32 v140, 16, v146
	v_and_b32_e32 v141, 0xffff0000, v146
	v_max_f32_e32 v140, v140, v140
	v_max_f32_e32 v141, v141, v141
	v_max_f32_e32 v140, 0x1e3ce508, v140
	v_max_f32_e32 v141, 0x1e3ce508, v141
	v_rcp_f32_e32 v140, v140
	v_rcp_f32_e32 v141, v141
	v_pk_mul_f32 v[72:73], v[72:73], v[132:133]
	v_lshlrev_b32_e32 v132, 16, v150
	v_and_b32_e32 v133, 0xffff0000, v150
	v_pk_mul_f32 v[132:133], v[140:141], v[132:133]
	v_lshlrev_b32_e32 v140, 16, v147
	v_and_b32_e32 v141, 0xffff0000, v147
	v_max_f32_e32 v140, v140, v140
	v_max_f32_e32 v141, v141, v141
	v_max_f32_e32 v140, 0x1e3ce508, v140
	v_max_f32_e32 v141, 0x1e3ce508, v141
	v_rcp_f32_e32 v140, v140
	v_rcp_f32_e32 v141, v141
	v_pk_mul_f32 v[66:67], v[66:67], v[132:133]
	v_lshlrev_b32_e32 v132, 16, v151
	v_and_b32_e32 v133, 0xffff0000, v151
	v_pk_mul_f32 v[132:133], v[140:141], v[132:133]
	v_lshlrev_b32_e32 v140, 16, v148
	v_pk_mul_f32 v[68:69], v[68:69], v[132:133]
	global_load_dwordx4 v[130:133], v[130:131], off offset:256
	v_max_f32_e32 v140, v140, v140
	v_max_f32_e32 v140, 0x1e3ce508, v140
	v_rcp_f32_e32 v146, v140
	v_and_b32_e32 v140, 0xffff0000, v148
	v_max_f32_e32 v140, v140, v140
	v_max_f32_e32 v140, 0x1e3ce508, v140
	v_rcp_f32_e32 v147, v140
	global_load_dwordx4 v[138:141], v[138:139], off offset:256
	v_lshlrev_b32_e32 v148, 16, v149
	v_and_b32_e32 v149, 0xffff0000, v149
	v_max_f32_e32 v148, v148, v148
	v_max_f32_e32 v149, v149, v149
	v_max_f32_e32 v148, 0x1e3ce508, v148
	v_max_f32_e32 v149, 0x1e3ce508, v149
	v_rcp_f32_e32 v148, v148
	v_rcp_f32_e32 v149, v149
	v_lshlrev_b32_e32 v150, 16, v152
	v_and_b32_e32 v151, 0xffff0000, v152
	v_pk_mul_f32 v[146:147], v[146:147], v[150:151]
	s_mov_b64 s[0:1], 0x160000
	v_pk_mul_f32 v[54:55], v[54:55], v[146:147]
	v_lshlrev_b32_e32 v146, 16, v153
	v_and_b32_e32 v147, 0xffff0000, v153
	v_pk_mul_f32 v[146:147], v[148:149], v[146:147]
	v_pk_mul_f32 v[154:155], v[156:157], v[154:155]
	s_waitcnt vmcnt(3)
; __device__ __forceinline__ float bf_lo(unsigned w) { return __uint_as_float(w << 16); }
; __device__ __forceinline__ float bf_hi(unsigned w) { return __uint_as_float(w & 0xffff0000u); }
;     __device__ __forceinline__ void mid(f32x4 (&acc)[2][2][4][2], const Unit& u, int wr, int wc, int fr, int fq) const {
;     ...
;             for (int m = 0; m < 4; ++m) { const size_t off = (size_t)(row0 + ai * HALF + m * 16) * 4096 + col0;
; #pragma unroll
;                 for (int bj = 0; bj < 2; ++bj) { const u32x4 ga = *(const u32x4*)(SGA + off + bj * HALF), gb = *(const u32x4*)(SGB + off + bj * HALF);
;                     const unsigned wa[4] = {ga.x, ga.y, ga.z, ga.w}, wb[4] = {gb.x, gb.y, gb.z, gb.w};
; #pragma unroll
;                     for (int p = 0; p < 4; ++p) { const float rl = bf_lo(wa[p]) * __builtin_amdgcn_rcpf(fmaxf(bf_lo(wb[p]), 1e-20f)), rh = bf_hi(wa[p]) * __builtin_amdgcn_rcpf(fmaxf(bf_hi(wb[p]), 1e-20f));
;                         acc[ai][bj][m][p >> 1][(p & 1) * 2] *= rl; acc[ai][bj][m][p >> 1][(p & 1) * 2 + 1] *= rh; } }
	v_lshlrev_b32_e32 v148, 16, v134
	v_and_b32_e32 v134, 0xffff0000, v134
	v_max_f32_e32 v148, v148, v148
	v_max_f32_e32 v134, v134, v134
	v_max_f32_e32 v148, 0x1e3ce508, v148
	v_max_f32_e32 v134, 0x1e3ce508, v134
	v_rcp_f32_e32 v148, v148
	v_rcp_f32_e32 v149, v134
	v_pk_mul_f32 v[56:57], v[56:57], v[146:147]
	v_lshl_add_u64 v[150:151], v[162:163], 0, s[0:1]
	v_pk_mul_f32 v[70:71], v[70:71], v[154:155]
	v_lshlrev_b32_e32 v134, 16, v135
	s_waitcnt vmcnt(2)
	v_lshlrev_b32_e32 v146, 16, v142
	v_and_b32_e32 v147, 0xffff0000, v142
	v_pk_mul_f32 v[146:147], v[148:149], v[146:147]
	v_and_b32_e32 v135, 0xffff0000, v135
	v_lshl_add_u64 v[154:155], s[12:13], 0, v[150:151]
	v_pk_mul_f32 v[42:43], v[42:43], v[146:147]
	v_max_f32_e32 v134, v134, v134
	v_max_f32_e32 v135, v135, v135
	global_load_dwordx4 v[146:149], v[154:155], off
	v_max_f32_e32 v134, 0x1e3ce508, v134
	v_max_f32_e32 v135, 0x1e3ce508, v135
	v_rcp_f32_e32 v134, v134
	v_rcp_f32_e32 v135, v135
	v_lshlrev_b32_e32 v142, 16, v143
	v_and_b32_e32 v143, 0xffff0000, v143
	s_mul_i32 s0, s50, s63
	v_pk_mul_f32 v[142:143], v[134:135], v[142:143]
	v_lshlrev_b32_e32 v134, 16, v136
	v_max_f32_e32 v134, v134, v134
	v_max_f32_e32 v134, 0x1e3ce508, v134
	v_rcp_f32_e32 v156, v134
	v_lshl_add_u64 v[134:135], s[10:11], 0, v[150:151]
	global_load_dwordx4 v[150:153], v[134:135], off
	v_and_b32_e32 v136, 0xffff0000, v136
	v_max_f32_e32 v136, v136, v136
	v_max_f32_e32 v136, 0x1e3ce508, v136
	v_rcp_f32_e32 v157, v136
	v_lshlrev_b32_e32 v136, 16, v137
	v_and_b32_e32 v137, 0xffff0000, v137
	v_max_f32_e32 v136, v136, v136
	v_max_f32_e32 v137, v137, v137
	v_max_f32_e32 v136, 0x1e3ce508, v136
	v_max_f32_e32 v137, 0x1e3ce508, v137
	v_rcp_f32_e32 v136, v136
	v_rcp_f32_e32 v137, v137
	v_pk_mul_f32 v[44:45], v[44:45], v[142:143]
	v_lshlrev_b32_e32 v142, 16, v144
	v_and_b32_e32 v143, 0xffff0000, v144
	v_pk_mul_f32 v[142:143], v[156:157], v[142:143]
	s_mul_hi_u32 s1, s50, s2
	v_pk_mul_f32 v[38:39], v[38:39], v[142:143]
	v_lshlrev_b32_e32 v142, 16, v145
	v_and_b32_e32 v143, 0xffff0000, v145
	v_pk_mul_f32 v[136:137], v[136:137], v[142:143]
	s_waitcnt vmcnt(3)
	v_lshlrev_b32_e32 v142, 16, v130
	v_and_b32_e32 v130, 0xffff0000, v130
	v_max_f32_e32 v142, v142, v142
	v_max_f32_e32 v130, v130, v130
	v_max_f32_e32 v142, 0x1e3ce508, v142
	v_max_f32_e32 v130, 0x1e3ce508, v130
	v_rcp_f32_e32 v142, v142
	v_rcp_f32_e32 v143, v130
	v_lshlrev_b32_e32 v130, 16, v131
	v_and_b32_e32 v131, 0xffff0000, v131
	v_pk_mul_f32 v[40:41], v[40:41], v[136:137]
	s_waitcnt vmcnt(2)
	v_lshlrev_b32_e32 v136, 16, v138
	v_and_b32_e32 v137, 0xffff0000, v138
	v_max_f32_e32 v130, v130, v130
	v_max_f32_e32 v131, v131, v131
	v_pk_mul_f32 v[136:137], v[142:143], v[136:137]
	v_max_f32_e32 v130, 0x1e3ce508, v130
	global_load_dwordx4 v[142:145], v[154:155], off offset:256
	v_max_f32_e32 v131, 0x1e3ce508, v131
	v_rcp_f32_e32 v130, v130
	v_rcp_f32_e32 v131, v131
	v_pk_mul_f32 v[22:23], v[22:23], v[136:137]
	v_lshlrev_b32_e32 v136, 16, v139
	v_and_b32_e32 v137, 0xffff0000, v139
	v_pk_mul_f32 v[130:131], v[130:131], v[136:137]
	v_lshlrev_b32_e32 v136, 16, v132
	v_max_f32_e32 v138, v136, v136
	global_load_dwordx4 v[134:137], v[134:135], off offset:256
	v_and_b32_e32 v132, 0xffff0000, v132
	v_max_f32_e32 v132, v132, v132
	v_max_f32_e32 v132, 0x1e3ce508, v132
	v_max_f32_e32 v138, 0x1e3ce508, v138
	v_rcp_f32_e32 v139, v132
	v_lshlrev_b32_e32 v132, 16, v133
	v_and_b32_e32 v133, 0xffff0000, v133
	v_rcp_f32_e32 v138, v138
	v_max_f32_e32 v132, v132, v132
	v_max_f32_e32 v133, v133, v133
	v_max_f32_e32 v132, 0x1e3ce508, v132
	v_max_f32_e32 v133, 0x1e3ce508, v133
	v_rcp_f32_e32 v132, v132
	v_rcp_f32_e32 v133, v133
	v_pk_mul_f32 v[24:25], v[24:25], v[130:131]
	v_lshlrev_b32_e32 v130, 16, v140
	v_and_b32_e32 v131, 0xffff0000, v140
	v_pk_mul_f32 v[130:131], v[138:139], v[130:131]
	s_add_i32 s1, s1, s0
	v_pk_mul_f32 v[130:131], v[14:15], v[130:131]
	v_lshlrev_b32_e32 v14, 16, v141
	v_and_b32_e32 v15, 0xffff0000, v141
	v_pk_mul_f32 v[14:15], v[132:133], v[14:15]
	s_waitcnt vmcnt(3)
; __device__ __forceinline__ float bf_lo(unsigned w) { return __uint_as_float(w << 16); }
; __device__ __forceinline__ float bf_hi(unsigned w) { return __uint_as_float(w & 0xffff0000u); }
;     __device__ bool next(int i, Unit& u) const { if (i > 1) return false; const int xcd = c & 7, idx = c >> 3; u.pm = 16 * i + 4 * (xcd >> 1) + (idx & 3); u.pn = 8 * (xcd & 1) + (idx >> 2); return true; }
;     __host__ __device__ bool next(int i, Unit& u) const {
;         const long L = (long)i * G + c; if (L >= nwg) return false;
;         int wgid = (int)L; { const int q = nwg / NXCD, r = nwg % NXCD, xcd = wgid % NXCD, off = wgid / NXCD; wgid = (xcd < r ? xcd * (q + 1) : r * (q + 1) + (xcd - r) * q) + off; }
;         const int nig = WGM * nN, gid = wgid / nig, fm = gid * WGM, gsz = (nM - fm) < WGM ? (nM - fm) : WGM;
;         u.pm = fm + ((wgid % nig) % gsz); u.pn = (wgid % nig) / gsz; return true;
;     __device__ __forceinline__ void mid(f32x4 (&acc)[2][2][4][2], const Unit& u, int wr, int wc, int fr, int fq) const {
;     ...
;             for (int m = 0; m < 4; ++m) { const size_t off = (size_t)(row0 + ai * HALF + m * 16) * 4096 + col0;
; #pragma unroll
;                 for (int bj = 0; bj < 2; ++bj) { const u32x4 ga = *(const u32x4*)(SGA + off + bj * HALF), gb = *(const u32x4*)(SGB + off + bj * HALF);
;                     const unsigned wa[4] = {ga.x, ga.y, ga.z, ga.w}, wb[4] = {gb.x, gb.y, gb.z, gb.w};
; #pragma unroll
;                     for (int p = 0; p < 4; ++p) { const float rl = bf_lo(wa[p]) * __builtin_amdgcn_rcpf(fmaxf(bf_lo(wb[p]), 1e-20f)), rh = bf_hi(wa[p]) * __builtin_amdgcn_rcpf(fmaxf(bf_hi(wb[p]), 1e-20f));
;                         acc[ai][bj][m][p >> 1][(p & 1) * 2] *= rl; acc[ai][bj][m][p >> 1][(p & 1) * 2 + 1] *= rh; } }
	v_lshlrev_b32_e32 v132, 16, v146
	v_max_f32_e32 v132, v132, v132
	v_max_f32_e32 v132, 0x1e3ce508, v132
	v_rcp_f32_e32 v138, v132
	v_and_b32_e32 v132, 0xffff0000, v146
	v_max_f32_e32 v132, v132, v132
	v_max_f32_e32 v132, 0x1e3ce508, v132
	v_rcp_f32_e32 v139, v132
	v_pk_mul_f32 v[132:133], v[16:17], v[14:15]
	v_lshlrev_b32_e32 v16, 16, v147
	v_and_b32_e32 v17, 0xffff0000, v147
	v_max_f32_e32 v16, v16, v16
	v_max_f32_e32 v17, v17, v17
	v_max_f32_e32 v16, 0x1e3ce508, v16
	v_max_f32_e32 v17, 0x1e3ce508, v17
	v_rcp_f32_e32 v16, v16
	v_rcp_f32_e32 v17, v17
	s_waitcnt vmcnt(2)
	v_lshlrev_b32_e32 v14, 16, v150
	v_and_b32_e32 v15, 0xffff0000, v150
	v_pk_mul_f32 v[14:15], v[138:139], v[14:15]
	s_mul_i32 s0, s50, s2
	v_pk_mul_f32 v[14:15], v[18:19], v[14:15]
	v_lshlrev_b32_e32 v18, 16, v151
	v_and_b32_e32 v19, 0xffff0000, v151
	v_pk_mul_f32 v[16:17], v[16:17], v[18:19]
	v_lshlrev_b32_e32 v18, 16, v148
	v_and_b32_e32 v19, 0xffff0000, v148
	v_max_f32_e32 v18, v18, v18
	v_max_f32_e32 v19, v19, v19
	v_max_f32_e32 v18, 0x1e3ce508, v18
	v_max_f32_e32 v19, 0x1e3ce508, v19
	v_rcp_f32_e32 v18, v18
	v_rcp_f32_e32 v19, v19
	v_pk_mul_f32 v[16:17], v[20:21], v[16:17]
	v_lshlrev_b32_e32 v20, 16, v152
	v_and_b32_e32 v21, 0xffff0000, v152
	v_pk_mul_f32 v[18:19], v[18:19], v[20:21]
	v_lshlrev_b32_e32 v20, 16, v149
	v_and_b32_e32 v21, 0xffff0000, v149
	v_max_f32_e32 v20, v20, v20
	v_max_f32_e32 v21, v21, v21
	v_max_f32_e32 v20, 0x1e3ce508, v20
	v_max_f32_e32 v21, 0x1e3ce508, v21
	v_rcp_f32_e32 v20, v20
	v_rcp_f32_e32 v21, v21
	v_pk_mul_f32 v[10:11], v[10:11], v[18:19]
	v_lshlrev_b32_e32 v18, 16, v153
	v_and_b32_e32 v19, 0xffff0000, v153
	v_pk_mul_f32 v[18:19], v[20:21], v[18:19]
	s_waitcnt vmcnt(1)
	v_lshlrev_b32_e32 v20, 16, v142
	v_and_b32_e32 v21, 0xffff0000, v142
	v_max_f32_e32 v20, v20, v20
	v_max_f32_e32 v21, v21, v21
	v_max_f32_e32 v20, 0x1e3ce508, v20
	v_max_f32_e32 v21, 0x1e3ce508, v21
	v_rcp_f32_e32 v20, v20
	v_rcp_f32_e32 v21, v21
	v_pk_mul_f32 v[12:13], v[12:13], v[18:19]
	s_waitcnt vmcnt(0)
	v_lshlrev_b32_e32 v18, 16, v134
	v_and_b32_e32 v19, 0xffff0000, v134
	v_pk_mul_f32 v[18:19], v[20:21], v[18:19]
	v_lshlrev_b32_e32 v20, 16, v143
	v_and_b32_e32 v21, 0xffff0000, v143
	v_max_f32_e32 v20, v20, v20
	v_max_f32_e32 v21, v21, v21
	v_max_f32_e32 v20, 0x1e3ce508, v20
	v_max_f32_e32 v21, 0x1e3ce508, v21
	v_rcp_f32_e32 v20, v20
	v_rcp_f32_e32 v21, v21
	v_pk_mul_f32 v[6:7], v[6:7], v[18:19]
	v_lshlrev_b32_e32 v18, 16, v135
	v_and_b32_e32 v19, 0xffff0000, v135
	v_pk_mul_f32 v[18:19], v[20:21], v[18:19]
	v_lshlrev_b32_e32 v20, 16, v144
	v_and_b32_e32 v21, 0xffff0000, v144
	v_max_f32_e32 v20, v20, v20
	v_max_f32_e32 v21, v21, v21
	v_max_f32_e32 v20, 0x1e3ce508, v20
	v_max_f32_e32 v21, 0x1e3ce508, v21
	v_rcp_f32_e32 v20, v20
	v_rcp_f32_e32 v21, v21
	v_pk_mul_f32 v[8:9], v[8:9], v[18:19]
	v_lshlrev_b32_e32 v18, 16, v136
	v_and_b32_e32 v19, 0xffff0000, v136
	v_pk_mul_f32 v[18:19], v[20:21], v[18:19]
	v_lshlrev_b32_e32 v20, 16, v145
	v_and_b32_e32 v21, 0xffff0000, v145
	v_max_f32_e32 v20, v20, v20
	v_max_f32_e32 v21, v21, v21
	v_max_f32_e32 v20, 0x1e3ce508, v20
	v_max_f32_e32 v21, 0x1e3ce508, v21
	v_rcp_f32_e32 v20, v20
	v_rcp_f32_e32 v21, v21
	v_pk_mul_f32 v[2:3], v[2:3], v[18:19]
	v_lshlrev_b32_e32 v18, 16, v137
	v_and_b32_e32 v19, 0xffff0000, v137
	v_pk_mul_f32 v[18:19], v[20:21], v[18:19]
	v_readlane_b32 s2, v238, 44
	v_pk_mul_f32 v[4:5], v[4:5], v[18:19]
	s_add_u32 s2, s0, s2
	s_addc_u32 s3, s1, s28
	v_cmp_gt_i64_e32 vcc, s[2:3], v[160:161]
	v_cmp_lt_i64_e64 s[0:1], s[2:3], v[158:159]
	s_cbranch_vccnz .LBB0_753
	s_ashr_i32 s3, s2, 31
	s_lshr_b32 s3, s3, 29
	s_add_i32 s4, s2, s3
	s_and_b32 s3, s4, -8
	s_sub_i32 s5, s2, s3
	s_cmp_gt_i32 s5, -1
	s_mov_b64 s[2:3], -1
	s_cbranch_scc0 .LBB0_750
	s_lshl_b32 s16, s5, 6
	s_mov_b64 s[2:3], 0

.LBB0_754:
	ds_read_b128 v[18:21], v172
	ds_read_b128 v[134:137], v172 offset:1024
	ds_read_b128 v[138:141], v172 offset:2048
	ds_read_b128 v[142:145], v172 offset:3072
	ds_read_b128 v[146:149], v173
	ds_read_b128 v[150:153], v173 offset:1024
	ds_read_b128 v[154:157], v173 offset:2048
	ds_read_b128 v[178:181], v173 offset:3072
	s_add_u32 s2, s30, 0x100
	s_addc_u32 s3, s31, 0
	s_cmp_eq_u32 s37, 60
	s_cselect_b32 s26, s33, s2
	s_cselect_b32 s27, s5, s3
	s_cselect_b32 s24, s36, s34
	s_cselect_b32 s25, s21, s35
	s_add_u32 s16, s26, 0x80
	s_addc_u32 s17, s27, 0
	s_add_u32 s30, s30, 0x100080
	s_addc_u32 s31, s31, 0
	s_mov_b32 m0, s76
	ds_read_b128 v[182:185], v174
	ds_read_b128 v[186:189], v174 offset:1024
	ds_read_b128 v[190:193], v174 offset:2048
	ds_read_b128 v[194:197], v174 offset:3072
	ds_read_b128 v[198:201], v174 offset:4096
	ds_read_b128 v[202:205], v174 offset:5120
	ds_read_b128 v[206:209], v174 offset:6144
	ds_read_b128 v[210:213], v174 offset:7168
	s_nop 0
	global_load_lds_dwordx4 v1, s[30:31]
	s_mov_b32 m0, s77
	s_nop 0
	global_load_lds_dwordx4 v165, s[30:31]
	s_waitcnt vmcnt(8)
	s_waitcnt lgkmcnt(0)
	s_setprio 1
	s_waitcnt lgkmcnt(0)
	s_barrier
	v_mfma_f32_16x16x32_bf16 v[34:37], v[18:21], v[182:185], v[34:37]
	v_mfma_f32_16x16x32_bf16 v[30:33], v[138:141], v[182:185], v[30:33]
	v_mfma_f32_16x16x32_bf16 v[46:49], v[18:21], v[190:193], v[46:49]
	v_mfma_f32_16x16x32_bf16 v[62:65], v[138:141], v[190:193], v[62:65]
	v_mfma_f32_16x16x32_bf16 v[78:81], v[18:21], v[198:201], v[78:81]
	v_mfma_f32_16x16x32_bf16 v[90:93], v[138:141], v[198:201], v[90:93]
	v_mfma_f32_16x16x32_bf16 v[106:109], v[18:21], v[206:209], v[106:109]
	v_mfma_f32_16x16x32_bf16 v[114:117], v[138:141], v[206:209], v[114:117]
	v_mfma_f32_16x16x32_bf16 v[26:29], v[146:149], v[182:185], v[26:29]
	v_mfma_f32_16x16x32_bf16 v[50:53], v[154:157], v[182:185], v[50:53]
	v_mfma_f32_16x16x32_bf16 v[58:61], v[146:149], v[190:193], v[58:61]
	v_mfma_f32_16x16x32_bf16 v[82:85], v[154:157], v[190:193], v[82:85]
	v_mfma_f32_16x16x32_bf16 v[110:113], v[146:149], v[198:201], v[110:113]
	v_mfma_f32_16x16x32_bf16 v[118:121], v[154:157], v[198:201], v[118:121]
	v_mfma_f32_16x16x32_bf16 v[122:125], v[146:149], v[206:209], v[122:125]
	v_mfma_f32_16x16x32_bf16 v[126:129], v[154:157], v[206:209], v[126:129]
	v_mfma_f32_16x16x32_bf16 v[34:37], v[134:137], v[186:189], v[34:37]
	v_mfma_f32_16x16x32_bf16 v[30:33], v[142:145], v[186:189], v[30:33]
	v_mfma_f32_16x16x32_bf16 v[46:49], v[134:137], v[194:197], v[46:49]
	v_mfma_f32_16x16x32_bf16 v[62:65], v[142:145], v[194:197], v[62:65]
	v_mfma_f32_16x16x32_bf16 v[78:81], v[134:137], v[202:205], v[78:81]
	v_mfma_f32_16x16x32_bf16 v[90:93], v[142:145], v[202:205], v[90:93]
	v_mfma_f32_16x16x32_bf16 v[106:109], v[134:137], v[210:213], v[106:109]
	v_mfma_f32_16x16x32_bf16 v[114:117], v[142:145], v[210:213], v[114:117]
	v_mfma_f32_16x16x32_bf16 v[26:29], v[150:153], v[186:189], v[26:29]
	v_mfma_f32_16x16x32_bf16 v[50:53], v[178:181], v[186:189], v[50:53]
	v_mfma_f32_16x16x32_bf16 v[58:61], v[150:153], v[194:197], v[58:61]
	v_mfma_f32_16x16x32_bf16 v[82:85], v[178:181], v[194:197], v[82:85]
	v_mfma_f32_16x16x32_bf16 v[110:113], v[150:153], v[202:205], v[110:113]
	v_mfma_f32_16x16x32_bf16 v[118:121], v[178:181], v[202:205], v[118:121]
	v_mfma_f32_16x16x32_bf16 v[122:125], v[150:153], v[210:213], v[122:125]
	s_setprio 0
	v_mfma_f32_16x16x32_bf16 v[126:129], v[178:181], v[210:213], v[126:129]
	s_barrier
	s_mov_b32 m0, s80
	s_mov_b64 s[30:31], s[24:25]
	ds_read_b128 v[182:185], v174 offset:16384
	ds_read_b128 v[186:189], v174 offset:17408
	ds_read_b128 v[190:193], v174 offset:18432
	ds_read_b128 v[194:197], v174 offset:19456
	ds_read_b128 v[198:201], v174 offset:20480
	ds_read_b128 v[202:205], v174 offset:21504
	ds_read_b128 v[206:209], v174 offset:22528
	ds_read_b128 v[210:213], v174 offset:23552
	s_nop 0
	global_load_lds_dwordx4 v164, s[30:31]
	s_mov_b32 m0, s81
	s_nop 0
	global_load_lds_dwordx4 v166, s[30:31]
	s_add_u32 s30, s24, 0x100000
	s_addc_u32 s31, s25, 0
	s_mov_b32 m0, s82
	s_nop 0
	global_load_lds_dwordx4 v164, s[30:31]
	s_mov_b32 m0, s83
	s_nop 0
	global_load_lds_dwordx4 v166, s[30:31]
	s_mov_b64 s[30:31], s[26:27]
	s_mov_b32 m0, s46
	s_nop 0
	global_load_lds_dwordx4 v1, s[30:31]
	s_mov_b32 m0, s47
	s_nop 0
	global_load_lds_dwordx4 v165, s[30:31]
	s_waitcnt vmcnt(8)
	s_waitcnt lgkmcnt(0)
	s_setprio 1
	s_waitcnt lgkmcnt(0)
	s_barrier
	v_mfma_f32_16x16x32_bf16 v[102:105], v[18:21], v[182:185], v[102:105]
	v_mfma_f32_16x16x32_bf16 v[98:101], v[138:141], v[182:185], v[98:101]
	v_mfma_f32_16x16x32_bf16 v[74:77], v[18:21], v[190:193], v[74:77]
	v_mfma_f32_16x16x32_bf16 v[70:73], v[138:141], v[190:193], v[70:73]
	v_mfma_f32_16x16x32_bf16 v[42:45], v[18:21], v[198:201], v[42:45]
	v_mfma_f32_16x16x32_bf16 v[38:41], v[138:141], v[198:201], v[38:41]
	v_mfma_f32_16x16x32_bf16 v[14:17], v[18:21], v[206:209], v[14:17]
	v_mfma_f32_16x16x32_bf16 v[10:13], v[138:141], v[206:209], v[10:13]
	v_mfma_f32_16x16x32_bf16 v[18:21], v[146:149], v[182:185], v[94:97]
	v_mfma_f32_16x16x32_bf16 v[86:89], v[154:157], v[182:185], v[86:89]
	v_mfma_f32_16x16x32_bf16 v[66:69], v[146:149], v[190:193], v[66:69]
	v_mfma_f32_16x16x32_bf16 v[54:57], v[154:157], v[190:193], v[54:57]
	v_mfma_f32_16x16x32_bf16 v[22:25], v[146:149], v[198:201], v[22:25]
	v_mfma_f32_16x16x32_bf16 v[94:97], v[154:157], v[198:201], v[130:133]
	v_mfma_f32_16x16x32_bf16 v[6:9], v[146:149], v[206:209], v[6:9]
	v_mfma_f32_16x16x32_bf16 v[2:5], v[154:157], v[206:209], v[2:5]
	v_mfma_f32_16x16x32_bf16 v[102:105], v[134:137], v[186:189], v[102:105]
	v_mfma_f32_16x16x32_bf16 v[98:101], v[142:145], v[186:189], v[98:101]
	v_mfma_f32_16x16x32_bf16 v[74:77], v[134:137], v[194:197], v[74:77]
	v_mfma_f32_16x16x32_bf16 v[70:73], v[142:145], v[194:197], v[70:73]
	v_mfma_f32_16x16x32_bf16 v[42:45], v[134:137], v[202:205], v[42:45]
	v_mfma_f32_16x16x32_bf16 v[38:41], v[142:145], v[202:205], v[38:41]
	v_mfma_f32_16x16x32_bf16 v[14:17], v[134:137], v[210:213], v[14:17]
	v_mfma_f32_16x16x32_bf16 v[10:13], v[142:145], v[210:213], v[10:13]
	v_mfma_f32_16x16x32_bf16 v[86:89], v[178:181], v[186:189], v[86:89]
	v_mfma_f32_16x16x32_bf16 v[66:69], v[150:153], v[194:197], v[66:69]
	v_mfma_f32_16x16x32_bf16 v[54:57], v[178:181], v[194:197], v[54:57]
	v_mfma_f32_16x16x32_bf16 v[22:25], v[150:153], v[202:205], v[22:25]
	v_mfma_f32_16x16x32_bf16 v[130:133], v[178:181], v[202:205], v[94:97]
	v_mfma_f32_16x16x32_bf16 v[6:9], v[150:153], v[210:213], v[6:9]
	v_mfma_f32_16x16x32_bf16 v[2:5], v[178:181], v[210:213], v[2:5]
	s_setprio 0
	v_mfma_f32_16x16x32_bf16 v[18:21], v[150:153], v[186:189], v[18:21]
	s_barrier
; #define PG8_BAR __builtin_amdgcn_s_barrier()
; #define PG8_BAR __builtin_amdgcn_s_barrier()
; template <class Epi, class Sched>
; __device__ __forceinline__ void gemm_phase_dual(PG8_LAS unsigned char* lds, const Gemm g  , const bf16_t* A0, const bf16_t* Bt0, int K0, const Sched& S, const Epi& E) {
;     ...
;         if (wr == 0) PG8_BAR;
	ds_read_b128 v[94:97], v175
	ds_read_b128 v[134:137], v175 offset:1024
	ds_read_b128 v[138:141], v175 offset:2048
	ds_read_b128 v[142:145], v175 offset:3072
	ds_read_b128 v[146:149], v176
	ds_read_b128 v[150:153], v176 offset:1024
	ds_read_b128 v[154:157], v176 offset:2048
	ds_read_b128 v[178:181], v176 offset:3072
	s_add_u32 s26, s26, 0x100000
	s_addc_u32 s27, s27, 0
	s_mov_b32 m0, s48
	ds_read_b128 v[182:185], v174 offset:32768
	ds_read_b128 v[186:189], v174 offset:33792
	ds_read_b128 v[190:193], v174 offset:34816
	ds_read_b128 v[194:197], v174 offset:35840
	ds_read_b128 v[198:201], v174 offset:36864
	ds_read_b128 v[202:205], v174 offset:37888
	ds_read_b128 v[206:209], v174 offset:38912
	ds_read_b128 v[210:213], v174 offset:39936
	s_nop 0
	global_load_lds_dwordx4 v1, s[26:27]
	s_mov_b32 m0, s49
	s_nop 0
	global_load_lds_dwordx4 v165, s[26:27]
	s_waitcnt vmcnt(8)
	s_waitcnt lgkmcnt(0)
	s_setprio 1
	s_waitcnt lgkmcnt(0)
	s_barrier
	v_mfma_f32_16x16x32_bf16 v[34:37], v[94:97], v[182:185], v[34:37]
	v_mfma_f32_16x16x32_bf16 v[30:33], v[138:141], v[182:185], v[30:33]
	v_mfma_f32_16x16x32_bf16 v[46:49], v[94:97], v[190:193], v[46:49]
	v_mfma_f32_16x16x32_bf16 v[62:65], v[138:141], v[190:193], v[62:65]
	v_mfma_f32_16x16x32_bf16 v[78:81], v[94:97], v[198:201], v[78:81]
	v_mfma_f32_16x16x32_bf16 v[90:93], v[138:141], v[198:201], v[90:93]
	v_mfma_f32_16x16x32_bf16 v[106:109], v[94:97], v[206:209], v[106:109]
	v_mfma_f32_16x16x32_bf16 v[114:117], v[138:141], v[206:209], v[114:117]
	v_mfma_f32_16x16x32_bf16 v[26:29], v[146:149], v[182:185], v[26:29]
	v_mfma_f32_16x16x32_bf16 v[50:53], v[154:157], v[182:185], v[50:53]
	v_mfma_f32_16x16x32_bf16 v[58:61], v[146:149], v[190:193], v[58:61]
	v_mfma_f32_16x16x32_bf16 v[82:85], v[154:157], v[190:193], v[82:85]
	v_mfma_f32_16x16x32_bf16 v[110:113], v[146:149], v[198:201], v[110:113]
	v_mfma_f32_16x16x32_bf16 v[118:121], v[154:157], v[198:201], v[118:121]
	v_mfma_f32_16x16x32_bf16 v[122:125], v[146:149], v[206:209], v[122:125]
	v_mfma_f32_16x16x32_bf16 v[126:129], v[154:157], v[206:209], v[126:129]
	v_mfma_f32_16x16x32_bf16 v[34:37], v[134:137], v[186:189], v[34:37]
	v_mfma_f32_16x16x32_bf16 v[30:33], v[142:145], v[186:189], v[30:33]
	v_mfma_f32_16x16x32_bf16 v[46:49], v[134:137], v[194:197], v[46:49]
	v_mfma_f32_16x16x32_bf16 v[62:65], v[142:145], v[194:197], v[62:65]
	v_mfma_f32_16x16x32_bf16 v[78:81], v[134:137], v[202:205], v[78:81]
	v_mfma_f32_16x16x32_bf16 v[90:93], v[142:145], v[202:205], v[90:93]
	v_mfma_f32_16x16x32_bf16 v[106:109], v[134:137], v[210:213], v[106:109]
	v_mfma_f32_16x16x32_bf16 v[114:117], v[142:145], v[210:213], v[114:117]
	v_mfma_f32_16x16x32_bf16 v[26:29], v[150:153], v[186:189], v[26:29]
	v_mfma_f32_16x16x32_bf16 v[50:53], v[178:181], v[186:189], v[50:53]
	v_mfma_f32_16x16x32_bf16 v[58:61], v[150:153], v[194:197], v[58:61]
	v_mfma_f32_16x16x32_bf16 v[82:85], v[178:181], v[194:197], v[82:85]
	v_mfma_f32_16x16x32_bf16 v[110:113], v[150:153], v[202:205], v[110:113]
	v_mfma_f32_16x16x32_bf16 v[118:121], v[178:181], v[202:205], v[118:121]
	v_mfma_f32_16x16x32_bf16 v[122:125], v[150:153], v[210:213], v[122:125]
	s_setprio 0
	v_mfma_f32_16x16x32_bf16 v[126:129], v[178:181], v[210:213], v[126:129]
	s_barrier
	s_add_u32 s26, s24, 0x80
	s_mov_b32 m0, s84
	s_addc_u32 s27, s25, 0
	ds_read_b128 v[182:185], v174 offset:49152
	ds_read_b128 v[186:189], v174 offset:50176
	ds_read_b128 v[190:193], v174 offset:51200
	ds_read_b128 v[194:197], v174 offset:52224
	ds_read_b128 v[198:201], v174 offset:53248
	ds_read_b128 v[202:205], v174 offset:54272
	ds_read_b128 v[206:209], v174 offset:55296
	ds_read_b128 v[210:213], v174 offset:56320
	s_add_u32 s24, s24, 0x100080
	global_load_lds_dwordx4 v164, s[26:27]
	s_mov_b32 m0, s85
	s_addc_u32 s25, s25, 0
	global_load_lds_dwordx4 v166, s[26:27]
	s_mov_b32 m0, s86
	s_nop 0
	global_load_lds_dwordx4 v164, s[24:25]
	s_mov_b32 m0, s87
	s_nop 0
	global_load_lds_dwordx4 v166, s[24:25]
	s_mov_b32 m0, s57
	s_nop 0
	global_load_lds_dwordx4 v1, s[16:17]
	s_mov_b32 m0, s62
	s_nop 0
	global_load_lds_dwordx4 v165, s[16:17]
	s_waitcnt vmcnt(8)
	s_waitcnt lgkmcnt(0)
	s_setprio 1
	s_waitcnt lgkmcnt(0)
	s_barrier
	v_mfma_f32_16x16x32_bf16 v[18:21], v[146:149], v[182:185], v[18:21]
	v_mfma_f32_16x16x32_bf16 v[102:105], v[94:97], v[182:185], v[102:105]
	v_mfma_f32_16x16x32_bf16 v[74:77], v[94:97], v[190:193], v[74:77]
	v_mfma_f32_16x16x32_bf16 v[42:45], v[94:97], v[198:201], v[42:45]
	v_mfma_f32_16x16x32_bf16 v[14:17], v[94:97], v[206:209], v[14:17]
	v_mfma_f32_16x16x32_bf16 v[94:97], v[150:153], v[186:189], v[18:21]
	v_mfma_f32_16x16x32_bf16 v[18:21], v[154:157], v[182:185], v[86:89]
	v_mfma_f32_16x16x32_bf16 v[86:89], v[178:181], v[186:189], v[18:21]
	v_mfma_f32_16x16x32_bf16 v[18:21], v[146:149], v[190:193], v[66:69]
	v_mfma_f32_16x16x32_bf16 v[66:69], v[150:153], v[194:197], v[18:21]
	v_mfma_f32_16x16x32_bf16 v[18:21], v[154:157], v[190:193], v[54:57]
	v_mfma_f32_16x16x32_bf16 v[54:57], v[178:181], v[194:197], v[18:21]
	v_mfma_f32_16x16x32_bf16 v[18:21], v[146:149], v[198:201], v[22:25]
	v_mfma_f32_16x16x32_bf16 v[98:101], v[138:141], v[182:185], v[98:101]
	v_mfma_f32_16x16x32_bf16 v[70:73], v[138:141], v[190:193], v[70:73]
	v_mfma_f32_16x16x32_bf16 v[38:41], v[138:141], v[198:201], v[38:41]
	v_mfma_f32_16x16x32_bf16 v[10:13], v[138:141], v[206:209], v[10:13]
	v_mfma_f32_16x16x32_bf16 v[22:25], v[150:153], v[202:205], v[18:21]
	v_mfma_f32_16x16x32_bf16 v[18:21], v[154:157], v[198:201], v[130:133]
	v_mfma_f32_16x16x32_bf16 v[6:9], v[146:149], v[206:209], v[6:9]
	v_mfma_f32_16x16x32_bf16 v[2:5], v[154:157], v[206:209], v[2:5]
	v_mfma_f32_16x16x32_bf16 v[102:105], v[134:137], v[186:189], v[102:105]
	v_mfma_f32_16x16x32_bf16 v[98:101], v[142:145], v[186:189], v[98:101]
	v_mfma_f32_16x16x32_bf16 v[74:77], v[134:137], v[194:197], v[74:77]
	v_mfma_f32_16x16x32_bf16 v[70:73], v[142:145], v[194:197], v[70:73]
	v_mfma_f32_16x16x32_bf16 v[42:45], v[134:137], v[202:205], v[42:45]
	v_mfma_f32_16x16x32_bf16 v[38:41], v[142:145], v[202:205], v[38:41]
	v_mfma_f32_16x16x32_bf16 v[14:17], v[134:137], v[210:213], v[14:17]
	v_mfma_f32_16x16x32_bf16 v[10:13], v[142:145], v[210:213], v[10:13]
	v_mfma_f32_16x16x32_bf16 v[130:133], v[178:181], v[202:205], v[18:21]
	v_mfma_f32_16x16x32_bf16 v[6:9], v[150:153], v[210:213], v[6:9]
	s_setprio 0
	v_mfma_f32_16x16x32_bf16 v[2:5], v[178:181], v[210:213], v[2:5]
	s_barrier
	s_add_i32 s37, s37, 2
	s_add_u32 s34, s34, 0x100
	s_addc_u32 s35, s35, 0
	s_cmp_gt_u32 s37, 61
	s_mov_b64 s[30:31], s[2:3]
	s_cbranch_scc0 .LBB0_754
	s_and_b64 vcc, exec, s[18:19]
	s_cbranch_vccz .LBB0_757
	s_barrier

; #define PG8_STAGE(bufoff, gbase, voff) do { const char* _gb = (const char*)(gbase); asm volatile("" : "+s"(_gb)); _Pragma("unroll") for (int _i = 0; _i < 2; ++_i) { asm volatile("" : "+v"((voff)[_i])); \
;         __builtin_amdgcn_global_load_lds((const unsigned*)(_gb + (voff)[_i]), (PG8_LAS unsigned*)(lds + (bufoff) + ldsw + _i * 8192), 16, 0, 0); } } while (0)
; #define PG8_LDA(dst, b, h) do { _Pragma("unroll") for (int m = 0; m < 4; ++m) _Pragma("unroll") for (int k = 0; k < 2; ++k) dst[m][k] = *(const PG8_LAS bf16x8*)(lds + PG8_SA(b, h) + aoff + m * 2048 + k * 1024); } while (0)
; #define PG8_LDB(dst, b, h) do { _Pragma("unroll") for (int n = 0; n < 2; ++n) _Pragma("unroll") for (int k = 0; k < 2; ++k) dst[n][k] = *(const PG8_LAS bf16x8*)(lds + PG8_SB(b, h) + boff + n * 2048 + k * 1024); } while (0)
; #define PG8_WAIT_V(n) asm volatile("s_waitcnt vmcnt(" #n ")" ::: "memory")
; #define PG8_WAIT_L(n) asm volatile("s_waitcnt lgkmcnt(" #n ")" ::: "memory")
; #define PG8_BAR __builtin_amdgcn_s_barrier()
; #define PG8_SCHED __builtin_amdgcn_sched_barrier(0)
; #define PG8_LDA(dst, b, h) do { _Pragma("unroll") for (int m = 0; m < 4; ++m) _Pragma("unroll") for (int k = 0; k < 2; ++k) dst[m][k] = *(const PG8_LAS bf16x8*)(lds + PG8_SA(b, h) + aoff + m * 2048 + k * 1024); } while (0)
; template <class Epi, class Sched, bool ALIGN_EPI = false, bool SP2 = false>
; __device__ __forceinline__ void gemm_phase(PG8_LAS unsigned char* lds, const Gemm g, const Sched& S, const Epi& E) {
;     ...
;         for (int t = 0; t < nt; t += 2) {
;             const bool last = (t == nt - 2);
;             const char* a1 = cA + (size_t)(t + 1) * kstep;
;             const char* a2 = last ? nA : cA + (size_t)(t + 2) * kstep; const char* b2 = last ? nB : cB + (size_t)(t + 2) * kstep;
;             const char* a3 = a2 + kstep; const char* b3 = b2 + kstep;
;             if (last && has_next) S.a_ready(nxt);
;             if constexpr (SP2) {
;             PG8_LDB(B0, 0, 0); PG8_LDB(B1, 0, 1); PG8_SCHED; PG8_LDA(At, 0, 0); PG8_STAGE(PG8_SA(1, 1), a1 + hstep, voffA);
;             PG8_WAIT_V(8); PG8_WAIT_L(0); PG8_BAR; PG8_MMA2(0); PG8_BAR; PG8_SCHED;
;             PG8_LDA(At, 0, 1); PG8_STAGE(PG8_SB(0, 0), b2, voffB); PG8_STAGE(PG8_SB(0, 1), b2 + hstep, voffB); PG8_STAGE(PG8_SA(0, 0), a2, voffA);
;             PG8_WAIT_V(8); PG8_WAIT_L(0); PG8_BAR; PG8_MMA2(1); PG8_BAR; PG8_SCHED;
.LBB0_833:
	ds_read_b128 v[130:133], v180
	ds_read_b128 v[134:137], v180 offset:1024
	ds_read_b128 v[138:141], v180 offset:2048
	ds_read_b128 v[142:145], v180 offset:3072
	ds_read_b128 v[146:149], v181
	ds_read_b128 v[150:153], v181 offset:1024
	ds_read_b128 v[154:157], v181 offset:2048
	ds_read_b128 v[158:161], v181 offset:3072
	s_add_u32 s24, s16, 0x100
	s_addc_u32 s25, s17, 0
	s_cmp_eq_u32 s87, 60
	s_cselect_b32 s28, s83, s24
	s_cselect_b32 s29, s55, s25
	s_cselect_b32 s26, s84, s85
	s_cselect_b32 s27, s53, s86
	s_add_u32 s2, s28, 0x80
	s_addc_u32 s3, s29, 0
	s_add_u32 s16, s16, 0x100080
	s_addc_u32 s17, s17, 0
	s_add_i32 m0, s69, 0xc000
	ds_read_b128 v[166:169], v182
	ds_read_b128 v[170:173], v182 offset:1024
	ds_read_b128 v[184:187], v182 offset:2048
	ds_read_b128 v[188:191], v182 offset:3072
	ds_read_b128 v[192:195], v182 offset:4096
	ds_read_b128 v[196:199], v182 offset:5120
	ds_read_b128 v[200:203], v182 offset:6144
	ds_read_b128 v[204:207], v182 offset:7168
	s_nop 0
	global_load_lds_dwordx4 v1, s[16:17]
	s_add_i32 m0, s69, 0xe000
	s_nop 0
	global_load_lds_dwordx4 v175, s[16:17]
	s_waitcnt vmcnt(8)
	s_waitcnt lgkmcnt(0)
	s_setprio 1
	s_waitcnt lgkmcnt(0)
	s_barrier
	v_mfma_f32_16x16x32_bf16 v[126:129], v[130:133], v[166:169], v[126:129]
	v_mfma_f32_16x16x32_bf16 v[122:125], v[138:141], v[166:169], v[122:125]
	v_mfma_f32_16x16x32_bf16 v[110:113], v[130:133], v[184:187], v[110:113]
	v_mfma_f32_16x16x32_bf16 v[106:109], v[138:141], v[184:187], v[106:109]
	v_mfma_f32_16x16x32_bf16 v[94:97], v[130:133], v[192:195], v[94:97]
	v_mfma_f32_16x16x32_bf16 v[90:93], v[138:141], v[192:195], v[90:93]
	v_mfma_f32_16x16x32_bf16 v[78:81], v[130:133], v[200:203], v[78:81]
	v_mfma_f32_16x16x32_bf16 v[74:77], v[138:141], v[200:203], v[74:77]
	v_mfma_f32_16x16x32_bf16 v[118:121], v[146:149], v[166:169], v[118:121]
	v_mfma_f32_16x16x32_bf16 v[114:117], v[154:157], v[166:169], v[114:117]
	v_mfma_f32_16x16x32_bf16 v[102:105], v[146:149], v[184:187], v[102:105]
	v_mfma_f32_16x16x32_bf16 v[98:101], v[154:157], v[184:187], v[98:101]
	v_mfma_f32_16x16x32_bf16 v[86:89], v[146:149], v[192:195], v[86:89]
	v_mfma_f32_16x16x32_bf16 v[82:85], v[154:157], v[192:195], v[82:85]
	v_mfma_f32_16x16x32_bf16 v[70:73], v[146:149], v[200:203], v[70:73]
	v_mfma_f32_16x16x32_bf16 v[66:69], v[154:157], v[200:203], v[66:69]
	v_mfma_f32_16x16x32_bf16 v[126:129], v[134:137], v[170:173], v[126:129]
	v_mfma_f32_16x16x32_bf16 v[122:125], v[142:145], v[170:173], v[122:125]
	v_mfma_f32_16x16x32_bf16 v[110:113], v[134:137], v[188:191], v[110:113]
	v_mfma_f32_16x16x32_bf16 v[106:109], v[142:145], v[188:191], v[106:109]
	v_mfma_f32_16x16x32_bf16 v[94:97], v[134:137], v[196:199], v[94:97]
	v_mfma_f32_16x16x32_bf16 v[90:93], v[142:145], v[196:199], v[90:93]
	v_mfma_f32_16x16x32_bf16 v[78:81], v[134:137], v[204:207], v[78:81]
	v_mfma_f32_16x16x32_bf16 v[74:77], v[142:145], v[204:207], v[74:77]
	v_mfma_f32_16x16x32_bf16 v[118:121], v[150:153], v[170:173], v[118:121]
	v_mfma_f32_16x16x32_bf16 v[114:117], v[158:161], v[170:173], v[114:117]
	v_mfma_f32_16x16x32_bf16 v[102:105], v[150:153], v[188:191], v[102:105]
	v_mfma_f32_16x16x32_bf16 v[98:101], v[158:161], v[188:191], v[98:101]
	v_mfma_f32_16x16x32_bf16 v[86:89], v[150:153], v[196:199], v[86:89]
	v_mfma_f32_16x16x32_bf16 v[82:85], v[158:161], v[196:199], v[82:85]
	v_mfma_f32_16x16x32_bf16 v[70:73], v[150:153], v[204:207], v[70:73]
	s_setprio 0
	v_mfma_f32_16x16x32_bf16 v[66:69], v[158:161], v[204:207], v[66:69]
	s_barrier
	s_add_i32 s88, s81, s73
	s_mov_b64 s[16:17], s[26:27]
	s_mov_b32 m0, s88
	ds_read_b128 v[166:169], v182 offset:16384
	ds_read_b128 v[170:173], v182 offset:17408
	ds_read_b128 v[184:187], v182 offset:18432
	ds_read_b128 v[188:191], v182 offset:19456
	ds_read_b128 v[192:195], v182 offset:20480
	ds_read_b128 v[196:199], v182 offset:21504
	ds_read_b128 v[200:203], v182 offset:22528
	ds_read_b128 v[204:207], v182 offset:23552
	s_nop 0
	global_load_lds_dwordx4 v174, s[16:17]
	s_add_i32 m0, s88, 0x2000
	s_nop 0
	global_load_lds_dwordx4 v176, s[16:17]
	s_add_u32 s16, s26, 0x100000
	s_addc_u32 s17, s27, 0
	s_add_i32 s88, s82, s73
	s_mov_b32 m0, s88
	s_nop 0
	global_load_lds_dwordx4 v174, s[16:17]
	s_add_i32 m0, s88, 0x2000
	s_nop 0
	global_load_lds_dwordx4 v176, s[16:17]
	s_mov_b64 s[16:17], s[28:29]
	s_mov_b32 m0, s69
	s_nop 0
	global_load_lds_dwordx4 v1, s[16:17]
	s_mov_b32 m0, s71
	s_nop 0
	global_load_lds_dwordx4 v175, s[16:17]
	s_waitcnt vmcnt(8)
	s_waitcnt lgkmcnt(0)
	s_setprio 1
	s_waitcnt lgkmcnt(0)
	s_barrier
	v_mfma_f32_16x16x32_bf16 v[62:65], v[130:133], v[166:169], v[62:65]
	v_mfma_f32_16x16x32_bf16 v[58:61], v[138:141], v[166:169], v[58:61]
	v_mfma_f32_16x16x32_bf16 v[46:49], v[130:133], v[184:187], v[46:49]
	v_mfma_f32_16x16x32_bf16 v[42:45], v[138:141], v[184:187], v[42:45]
	v_mfma_f32_16x16x32_bf16 v[30:33], v[130:133], v[192:195], v[30:33]
	v_mfma_f32_16x16x32_bf16 v[26:29], v[138:141], v[192:195], v[26:29]
	v_mfma_f32_16x16x32_bf16 v[14:17], v[130:133], v[200:203], v[14:17]
	v_mfma_f32_16x16x32_bf16 v[10:13], v[138:141], v[200:203], v[10:13]
	v_mfma_f32_16x16x32_bf16 v[54:57], v[146:149], v[166:169], v[54:57]
	v_mfma_f32_16x16x32_bf16 v[50:53], v[154:157], v[166:169], v[50:53]
	v_mfma_f32_16x16x32_bf16 v[38:41], v[146:149], v[184:187], v[38:41]
	v_mfma_f32_16x16x32_bf16 v[34:37], v[154:157], v[184:187], v[34:37]
	v_mfma_f32_16x16x32_bf16 v[22:25], v[146:149], v[192:195], v[22:25]
	v_mfma_f32_16x16x32_bf16 v[18:21], v[154:157], v[192:195], v[18:21]
	v_mfma_f32_16x16x32_bf16 v[6:9], v[146:149], v[200:203], v[6:9]
	v_mfma_f32_16x16x32_bf16 v[2:5], v[154:157], v[200:203], v[2:5]
	v_mfma_f32_16x16x32_bf16 v[62:65], v[134:137], v[170:173], v[62:65]
	v_mfma_f32_16x16x32_bf16 v[58:61], v[142:145], v[170:173], v[58:61]
	v_mfma_f32_16x16x32_bf16 v[46:49], v[134:137], v[188:191], v[46:49]
	v_mfma_f32_16x16x32_bf16 v[42:45], v[142:145], v[188:191], v[42:45]
	v_mfma_f32_16x16x32_bf16 v[30:33], v[134:137], v[196:199], v[30:33]
	v_mfma_f32_16x16x32_bf16 v[26:29], v[142:145], v[196:199], v[26:29]
	v_mfma_f32_16x16x32_bf16 v[14:17], v[134:137], v[204:207], v[14:17]
	v_mfma_f32_16x16x32_bf16 v[10:13], v[142:145], v[204:207], v[10:13]
	v_mfma_f32_16x16x32_bf16 v[54:57], v[150:153], v[170:173], v[54:57]
	v_mfma_f32_16x16x32_bf16 v[50:53], v[158:161], v[170:173], v[50:53]
	v_mfma_f32_16x16x32_bf16 v[38:41], v[150:153], v[188:191], v[38:41]
	v_mfma_f32_16x16x32_bf16 v[34:37], v[158:161], v[188:191], v[34:37]
	v_mfma_f32_16x16x32_bf16 v[22:25], v[150:153], v[196:199], v[22:25]
	v_mfma_f32_16x16x32_bf16 v[18:21], v[158:161], v[196:199], v[18:21]
	v_mfma_f32_16x16x32_bf16 v[6:9], v[150:153], v[204:207], v[6:9]
	s_setprio 0
	v_mfma_f32_16x16x32_bf16 v[2:5], v[158:161], v[204:207], v[2:5]
	s_barrier
; #define PG8_STAGE(bufoff, gbase, voff) do { const char* _gb = (const char*)(gbase); asm volatile("" : "+s"(_gb)); _Pragma("unroll") for (int _i = 0; _i < 2; ++_i) { asm volatile("" : "+v"((voff)[_i])); \
;         __builtin_amdgcn_global_load_lds((const unsigned*)(_gb + (voff)[_i]), (PG8_LAS unsigned*)(lds + (bufoff) + ldsw + _i * 8192), 16, 0, 0); } } while (0)
; #define PG8_LDA(dst, b, h) do { _Pragma("unroll") for (int m = 0; m < 4; ++m) _Pragma("unroll") for (int k = 0; k < 2; ++k) dst[m][k] = *(const PG8_LAS bf16x8*)(lds + PG8_SA(b, h) + aoff + m * 2048 + k * 1024); } while (0)
; #define PG8_LDB(dst, b, h) do { _Pragma("unroll") for (int n = 0; n < 2; ++n) _Pragma("unroll") for (int k = 0; k < 2; ++k) dst[n][k] = *(const PG8_LAS bf16x8*)(lds + PG8_SB(b, h) + boff + n * 2048 + k * 1024); } while (0)
; #define PG8_WAIT_V(n) asm volatile("s_waitcnt vmcnt(" #n ")" ::: "memory")
; #define PG8_WAIT_L(n) asm volatile("s_waitcnt lgkmcnt(" #n ")" ::: "memory")
; #define PG8_BAR __builtin_amdgcn_s_barrier()
; #define PG8_SCHED __builtin_amdgcn_sched_barrier(0)
; #define PG8_STAGE(bufoff, gbase, voff) do { const char* _gb = (const char*)(gbase); asm volatile("" : "+s"(_gb)); _Pragma("unroll") for (int _i = 0; _i < 2; ++_i) { asm volatile("" : "+v"((voff)[_i])); \
;         __builtin_amdgcn_global_load_lds((const unsigned*)(_gb + (voff)[_i]), (PG8_LAS unsigned*)(lds + (bufoff) + ldsw + _i * 8192), 16, 0, 0); } } while (0)
; #define PG8_LDA(dst, b, h) do { _Pragma("unroll") for (int m = 0; m < 4; ++m) _Pragma("unroll") for (int k = 0; k < 2; ++k) dst[m][k] = *(const PG8_LAS bf16x8*)(lds + PG8_SA(b, h) + aoff + m * 2048 + k * 1024); } while (0)
; #define PG8_WAIT_V(n) asm volatile("s_waitcnt vmcnt(" #n ")" ::: "memory")
; template <class Epi, class Sched, bool ALIGN_EPI = false, bool SP2 = false>
; __device__ __forceinline__ void gemm_phase(PG8_LAS unsigned char* lds, const Gemm g, const Sched& S, const Epi& E) {
;     ...
;             PG8_LDB(B0, 1, 0); PG8_LDB(B1, 1, 1); PG8_SCHED; PG8_LDA(At, 1, 0); PG8_STAGE(PG8_SA(0, 1), a2 + hstep, voffA);
;             PG8_WAIT_V(8); PG8_WAIT_L(0); PG8_BAR; PG8_MMA2(0); PG8_BAR; PG8_SCHED;
;             PG8_LDA(At, 1, 1); PG8_STAGE(PG8_SB(1, 0), b3, voffB); PG8_STAGE(PG8_SB(1, 1), b3 + hstep, voffB); PG8_STAGE(PG8_SA(1, 0), a3, voffA);
;             PG8_WAIT_V(8); PG8_WAIT_L(0); PG8_BAR; PG8_MMA2(1); PG8_BAR; PG8_SCHED;
	s_add_i32 s88, 0, 0x18000
	s_add_i32 s89, 0, 0x1c000
	v_add_u32_e32 v142, s88, v178
	v_add_u32_e32 v158, s89, v178
	ds_read_b128 v[130:133], v142
	ds_read_b128 v[134:137], v142 offset:1024
	ds_read_b128 v[138:141], v142 offset:2048
	ds_read_b128 v[142:145], v142 offset:3072
	ds_read_b128 v[146:149], v158
	ds_read_b128 v[150:153], v158 offset:1024
	ds_read_b128 v[154:157], v158 offset:2048
	ds_read_b128 v[158:161], v158 offset:3072
	s_add_u32 s16, s28, 0x100000
	s_addc_u32 s17, s29, 0
	s_mov_b32 m0, s74
	ds_read_b128 v[166:169], v182 offset:32768
	ds_read_b128 v[170:173], v182 offset:33792
	ds_read_b128 v[184:187], v182 offset:34816
	ds_read_b128 v[188:191], v182 offset:35840
	ds_read_b128 v[192:195], v182 offset:36864
	ds_read_b128 v[196:199], v182 offset:37888
	ds_read_b128 v[200:203], v182 offset:38912
	ds_read_b128 v[204:207], v182 offset:39936
	s_nop 0
	global_load_lds_dwordx4 v1, s[16:17]
	s_mov_b32 m0, s75
	s_nop 0
	global_load_lds_dwordx4 v175, s[16:17]
	s_waitcnt vmcnt(8)
	s_waitcnt lgkmcnt(0)
	s_setprio 1
	s_waitcnt lgkmcnt(0)
	s_barrier
	v_mfma_f32_16x16x32_bf16 v[126:129], v[130:133], v[166:169], v[126:129]
	v_mfma_f32_16x16x32_bf16 v[122:125], v[138:141], v[166:169], v[122:125]
	v_mfma_f32_16x16x32_bf16 v[110:113], v[130:133], v[184:187], v[110:113]
	v_mfma_f32_16x16x32_bf16 v[106:109], v[138:141], v[184:187], v[106:109]
	v_mfma_f32_16x16x32_bf16 v[94:97], v[130:133], v[192:195], v[94:97]
	v_mfma_f32_16x16x32_bf16 v[90:93], v[138:141], v[192:195], v[90:93]
	v_mfma_f32_16x16x32_bf16 v[78:81], v[130:133], v[200:203], v[78:81]
	v_mfma_f32_16x16x32_bf16 v[74:77], v[138:141], v[200:203], v[74:77]
	v_mfma_f32_16x16x32_bf16 v[118:121], v[146:149], v[166:169], v[118:121]
	v_mfma_f32_16x16x32_bf16 v[114:117], v[154:157], v[166:169], v[114:117]
	v_mfma_f32_16x16x32_bf16 v[102:105], v[146:149], v[184:187], v[102:105]
	v_mfma_f32_16x16x32_bf16 v[98:101], v[154:157], v[184:187], v[98:101]
	v_mfma_f32_16x16x32_bf16 v[86:89], v[146:149], v[192:195], v[86:89]
	v_mfma_f32_16x16x32_bf16 v[82:85], v[154:157], v[192:195], v[82:85]
	v_mfma_f32_16x16x32_bf16 v[70:73], v[146:149], v[200:203], v[70:73]
	v_mfma_f32_16x16x32_bf16 v[66:69], v[154:157], v[200:203], v[66:69]
	v_mfma_f32_16x16x32_bf16 v[126:129], v[134:137], v[170:173], v[126:129]
	v_mfma_f32_16x16x32_bf16 v[122:125], v[142:145], v[170:173], v[122:125]
	v_mfma_f32_16x16x32_bf16 v[110:113], v[134:137], v[188:191], v[110:113]
	v_mfma_f32_16x16x32_bf16 v[106:109], v[142:145], v[188:191], v[106:109]
	v_mfma_f32_16x16x32_bf16 v[94:97], v[134:137], v[196:199], v[94:97]
	v_mfma_f32_16x16x32_bf16 v[90:93], v[142:145], v[196:199], v[90:93]
	v_mfma_f32_16x16x32_bf16 v[78:81], v[134:137], v[204:207], v[78:81]
	v_mfma_f32_16x16x32_bf16 v[74:77], v[142:145], v[204:207], v[74:77]
	v_mfma_f32_16x16x32_bf16 v[118:121], v[150:153], v[170:173], v[118:121]
	v_mfma_f32_16x16x32_bf16 v[114:117], v[158:161], v[170:173], v[114:117]
	v_mfma_f32_16x16x32_bf16 v[102:105], v[150:153], v[188:191], v[102:105]
	v_mfma_f32_16x16x32_bf16 v[98:101], v[158:161], v[188:191], v[98:101]
	v_mfma_f32_16x16x32_bf16 v[86:89], v[150:153], v[196:199], v[86:89]
	v_mfma_f32_16x16x32_bf16 v[82:85], v[158:161], v[196:199], v[82:85]
	v_mfma_f32_16x16x32_bf16 v[70:73], v[150:153], v[204:207], v[70:73]
	s_setprio 0
	v_mfma_f32_16x16x32_bf16 v[66:69], v[158:161], v[204:207], v[66:69]
	s_barrier
	s_add_u32 s16, s26, 0x80
	s_addc_u32 s17, s27, 0
	s_add_i32 s28, s88, s73
	s_mov_b32 m0, s28
	ds_read_b128 v[166:169], v182 offset:49152
	ds_read_b128 v[170:173], v182 offset:50176
	ds_read_b128 v[184:187], v182 offset:51200
	ds_read_b128 v[188:191], v182 offset:52224
	ds_read_b128 v[192:195], v182 offset:53248
	ds_read_b128 v[196:199], v182 offset:54272
	ds_read_b128 v[200:203], v182 offset:55296
	ds_read_b128 v[204:207], v182 offset:56320
	s_nop 0
	global_load_lds_dwordx4 v174, s[16:17]
	s_add_i32 m0, s28, 0x2000
	s_nop 0
	global_load_lds_dwordx4 v176, s[16:17]
	s_add_u32 s16, s26, 0x100080
	s_addc_u32 s17, s27, 0
	s_add_i32 s26, s89, s73
	s_mov_b32 m0, s26
	s_nop 0
	global_load_lds_dwordx4 v174, s[16:17]
	s_add_i32 m0, s26, 0x2000
	s_nop 0
	global_load_lds_dwordx4 v176, s[16:17]
	s_mov_b32 m0, s77
	s_nop 0
	global_load_lds_dwordx4 v1, s[2:3]
	s_mov_b32 m0, s78
	s_nop 0
	global_load_lds_dwordx4 v175, s[2:3]
	s_waitcnt vmcnt(8)
	s_waitcnt lgkmcnt(0)
	s_setprio 1
	s_waitcnt lgkmcnt(0)
	s_barrier
	v_mfma_f32_16x16x32_bf16 v[62:65], v[130:133], v[166:169], v[62:65]
	v_mfma_f32_16x16x32_bf16 v[58:61], v[138:141], v[166:169], v[58:61]
	v_mfma_f32_16x16x32_bf16 v[46:49], v[130:133], v[184:187], v[46:49]
	v_mfma_f32_16x16x32_bf16 v[42:45], v[138:141], v[184:187], v[42:45]
	v_mfma_f32_16x16x32_bf16 v[30:33], v[130:133], v[192:195], v[30:33]
	v_mfma_f32_16x16x32_bf16 v[26:29], v[138:141], v[192:195], v[26:29]
	v_mfma_f32_16x16x32_bf16 v[14:17], v[130:133], v[200:203], v[14:17]
	v_mfma_f32_16x16x32_bf16 v[10:13], v[138:141], v[200:203], v[10:13]
	v_mfma_f32_16x16x32_bf16 v[54:57], v[146:149], v[166:169], v[54:57]
	v_mfma_f32_16x16x32_bf16 v[50:53], v[154:157], v[166:169], v[50:53]
	v_mfma_f32_16x16x32_bf16 v[38:41], v[146:149], v[184:187], v[38:41]
	v_mfma_f32_16x16x32_bf16 v[34:37], v[154:157], v[184:187], v[34:37]
	v_mfma_f32_16x16x32_bf16 v[22:25], v[146:149], v[192:195], v[22:25]
	v_mfma_f32_16x16x32_bf16 v[18:21], v[154:157], v[192:195], v[18:21]
	v_mfma_f32_16x16x32_bf16 v[6:9], v[146:149], v[200:203], v[6:9]
	v_mfma_f32_16x16x32_bf16 v[2:5], v[154:157], v[200:203], v[2:5]
	v_mfma_f32_16x16x32_bf16 v[62:65], v[134:137], v[170:173], v[62:65]
	v_mfma_f32_16x16x32_bf16 v[58:61], v[142:145], v[170:173], v[58:61]
	v_mfma_f32_16x16x32_bf16 v[46:49], v[134:137], v[188:191], v[46:49]
	v_mfma_f32_16x16x32_bf16 v[42:45], v[142:145], v[188:191], v[42:45]
	v_mfma_f32_16x16x32_bf16 v[30:33], v[134:137], v[196:199], v[30:33]
	v_mfma_f32_16x16x32_bf16 v[26:29], v[142:145], v[196:199], v[26:29]
	v_mfma_f32_16x16x32_bf16 v[14:17], v[134:137], v[204:207], v[14:17]
	v_mfma_f32_16x16x32_bf16 v[10:13], v[142:145], v[204:207], v[10:13]
	v_mfma_f32_16x16x32_bf16 v[54:57], v[150:153], v[170:173], v[54:57]
	v_mfma_f32_16x16x32_bf16 v[50:53], v[158:161], v[170:173], v[50:53]
	v_mfma_f32_16x16x32_bf16 v[38:41], v[150:153], v[188:191], v[38:41]
	v_mfma_f32_16x16x32_bf16 v[34:37], v[158:161], v[188:191], v[34:37]
	v_mfma_f32_16x16x32_bf16 v[22:25], v[150:153], v[196:199], v[22:25]
	v_mfma_f32_16x16x32_bf16 v[18:21], v[158:161], v[196:199], v[18:21]
	v_mfma_f32_16x16x32_bf16 v[6:9], v[150:153], v[204:207], v[6:9]
	s_setprio 0
	v_mfma_f32_16x16x32_bf16 v[2:5], v[158:161], v[204:207], v[2:5]
	s_barrier
	s_add_i32 s87, s87, 2
	s_add_u32 s85, s85, 0x100
	s_addc_u32 s86, s86, 0
	s_cmp_gt_u32 s87, 61
	s_mov_b64 s[16:17], s[24:25]
	s_cbranch_scc0 .LBB0_833
	s_and_b64 vcc, exec, s[12:13]
	s_cbranch_vccz .LBB0_836
	s_barrier

; #define PG8_STAGE(bufoff, gbase, voff) do { const char* _gb = (const char*)(gbase); asm volatile("" : "+s"(_gb)); _Pragma("unroll") for (int _i = 0; _i < 2; ++_i) { asm volatile("" : "+v"((voff)[_i])); \
;         __builtin_amdgcn_global_load_lds((const unsigned*)(_gb + (voff)[_i]), (PG8_LAS unsigned*)(lds + (bufoff) + ldsw + _i * 8192), 16, 0, 0); } } while (0)
; #define PG8_LDA(dst, b, h) do { _Pragma("unroll") for (int m = 0; m < 4; ++m) _Pragma("unroll") for (int k = 0; k < 2; ++k) dst[m][k] = *(const PG8_LAS bf16x8*)(lds + PG8_SA(b, h) + aoff + m * 2048 + k * 1024); } while (0)
; #define PG8_LDB(dst, b, h) do { _Pragma("unroll") for (int n = 0; n < 2; ++n) _Pragma("unroll") for (int k = 0; k < 2; ++k) dst[n][k] = *(const PG8_LAS bf16x8*)(lds + PG8_SB(b, h) + boff + n * 2048 + k * 1024); } while (0)
; #define PG8_WAIT_V(n) asm volatile("s_waitcnt vmcnt(" #n ")" ::: "memory")
; #define PG8_WAIT_L(n) asm volatile("s_waitcnt lgkmcnt(" #n ")" ::: "memory")
; #define PG8_BAR __builtin_amdgcn_s_barrier()
; #define PG8_SCHED __builtin_amdgcn_sched_barrier(0)
; #define PG8_STAGE(bufoff, gbase, voff) do { const char* _gb = (const char*)(gbase); asm volatile("" : "+s"(_gb)); _Pragma("unroll") for (int _i = 0; _i < 2; ++_i) { asm volatile("" : "+v"((voff)[_i])); \
;         __builtin_amdgcn_global_load_lds((const unsigned*)(_gb + (voff)[_i]), (PG8_LAS unsigned*)(lds + (bufoff) + ldsw + _i * 8192), 16, 0, 0); } } while (0)
; template <class Epi, class Sched, bool ALIGN_EPI = false, bool SP2 = false>
; __device__ __forceinline__ void gemm_phase(PG8_LAS unsigned char* lds, const Gemm g, const Sched& S, const Epi& E) {
;     ...
;             const bool last = (t == nt - 2);
;             const char* a1 = cA + (size_t)(t + 1) * kstep;
;             const char* a2 = last ? nA : cA + (size_t)(t + 2) * kstep; const char* b2 = last ? nB : cB + (size_t)(t + 2) * kstep;
;             const char* a3 = a2 + kstep; const char* b3 = b2 + kstep;
;             if (last && has_next) S.a_ready(nxt);
;             if constexpr (SP2) {
;             PG8_LDB(B0, 0, 0); PG8_LDB(B1, 0, 1); PG8_SCHED; PG8_LDA(At, 0, 0); PG8_STAGE(PG8_SA(1, 1), a1 + hstep, voffA);
;             PG8_WAIT_V(8); PG8_WAIT_L(0); PG8_BAR; PG8_MMA2(0); PG8_BAR; PG8_SCHED;
;             PG8_LDA(At, 0, 1); PG8_STAGE(PG8_SB(0, 0), b2, voffB); PG8_STAGE(PG8_SB(0, 1), b2 + hstep, voffB); PG8_STAGE(PG8_SA(0, 0), a2, voffA);
.LBB0_933:
	v_add_u32_e32 v142, s78, v201
	v_add_u32_e32 v147, s79, v201
	s_nop 0
	ds_read_b128 v[6:9], v142
	ds_read_b128 v[62:65], v142 offset:1024
	ds_read_b128 v[138:141], v142 offset:2048
	ds_read_b128 v[142:145], v142 offset:3072
	ds_read_b128 v[164:167], v147
	ds_read_b128 v[168:171], v147 offset:1024
	ds_read_b128 v[172:175], v147 offset:2048
	ds_read_b128 v[176:179], v147 offset:3072
	s_add_u32 s14, s12, 0x100
	s_addc_u32 s15, s13, 0
	s_cmp_eq_u32 s83, 60
	s_cselect_b32 s18, s21, s14
	s_cselect_b32 s19, s20, s15
	s_cselect_b32 s16, s51, s62
	s_cselect_b32 s17, s49, s63
	s_add_u32 s2, s18, 0x80
	s_addc_u32 s3, s19, 0
	s_add_u32 s12, s12, 0x100080
	s_addc_u32 s13, s13, 0
	s_add_i32 m0, s33, 0xc000
	ds_read_b128 v[180:183], v219
	ds_read_b128 v[184:187], v219 offset:1024
	ds_read_b128 v[188:191], v219 offset:2048
	ds_read_b128 v[192:195], v219 offset:3072
	ds_read_b128 v[222:225], v219 offset:4096
	ds_read_b128 v[226:229], v219 offset:5120
	ds_read_b128 v[230:233], v219 offset:6144
	ds_read_b128 v[234:237], v219 offset:7168
	s_nop 0
	global_load_lds_dwordx4 v1, s[12:13]
	s_add_i32 m0, s33, 0xe000
	s_nop 0
	global_load_lds_dwordx4 v199, s[12:13]
	s_waitcnt vmcnt(8)
	s_waitcnt lgkmcnt(0)
	s_setprio 1
	s_waitcnt lgkmcnt(0)
	s_barrier
	v_mfma_f32_16x16x32_bf16 v[118:121], v[6:9], v[180:183], v[118:121]
	v_mfma_f32_16x16x32_bf16 v[114:117], v[138:141], v[180:183], v[114:117]
	v_mfma_f32_16x16x32_bf16 v[106:109], v[6:9], v[188:191], v[106:109]
	v_mfma_f32_16x16x32_bf16 v[86:89], v[138:141], v[188:191], v[86:89]
	v_mfma_f32_16x16x32_bf16 v[134:137], v[6:9], v[222:225], v[134:137]
	v_mfma_f32_16x16x32_bf16 v[90:93], v[138:141], v[222:225], v[90:93]
	v_mfma_f32_16x16x32_bf16 v[130:133], v[6:9], v[230:233], v[130:133]
	v_mfma_f32_16x16x32_bf16 v[110:113], v[138:141], v[230:233], v[110:113]
	v_mfma_f32_16x16x32_bf16 v[94:97], v[164:167], v[180:183], v[94:97]
	v_mfma_f32_16x16x32_bf16 v[82:85], v[172:175], v[180:183], v[82:85]
	v_mfma_f32_16x16x32_bf16 v[78:81], v[164:167], v[188:191], v[78:81]
	v_mfma_f32_16x16x32_bf16 v[74:77], v[172:175], v[188:191], v[74:77]
	v_mfma_f32_16x16x32_bf16 v[126:129], v[164:167], v[222:225], v[126:129]
	v_mfma_f32_16x16x32_bf16 v[98:101], v[172:175], v[222:225], v[98:101]
	v_mfma_f32_16x16x32_bf16 v[122:125], v[164:167], v[230:233], v[122:125]
	v_mfma_f32_16x16x32_bf16 v[102:105], v[172:175], v[230:233], v[102:105]
	v_mfma_f32_16x16x32_bf16 v[118:121], v[62:65], v[184:187], v[118:121]
	v_mfma_f32_16x16x32_bf16 v[114:117], v[142:145], v[184:187], v[114:117]
	v_mfma_f32_16x16x32_bf16 v[106:109], v[62:65], v[192:195], v[106:109]
	v_mfma_f32_16x16x32_bf16 v[86:89], v[142:145], v[192:195], v[86:89]
	v_mfma_f32_16x16x32_bf16 v[134:137], v[62:65], v[226:229], v[134:137]
	v_mfma_f32_16x16x32_bf16 v[90:93], v[142:145], v[226:229], v[90:93]
	v_mfma_f32_16x16x32_bf16 v[130:133], v[62:65], v[234:237], v[130:133]
	v_mfma_f32_16x16x32_bf16 v[110:113], v[142:145], v[234:237], v[110:113]
	v_mfma_f32_16x16x32_bf16 v[94:97], v[168:171], v[184:187], v[94:97]
	v_mfma_f32_16x16x32_bf16 v[82:85], v[176:179], v[184:187], v[82:85]
	v_mfma_f32_16x16x32_bf16 v[78:81], v[168:171], v[192:195], v[78:81]
	v_mfma_f32_16x16x32_bf16 v[74:77], v[176:179], v[192:195], v[74:77]
	v_mfma_f32_16x16x32_bf16 v[126:129], v[168:171], v[226:229], v[126:129]
	v_mfma_f32_16x16x32_bf16 v[98:101], v[176:179], v[226:229], v[98:101]
	v_mfma_f32_16x16x32_bf16 v[122:125], v[168:171], v[234:237], v[122:125]
	s_setprio 0
	v_mfma_f32_16x16x32_bf16 v[102:105], v[176:179], v[234:237], v[102:105]
	s_barrier
	s_add_i32 s84, s78, s25
	s_mov_b64 s[12:13], s[16:17]
	s_mov_b32 m0, s84
	ds_read_b128 v[180:183], v219 offset:16384
	ds_read_b128 v[184:187], v219 offset:17408
	ds_read_b128 v[188:191], v219 offset:18432
	ds_read_b128 v[192:195], v219 offset:19456
	ds_read_b128 v[222:225], v219 offset:20480
	ds_read_b128 v[226:229], v219 offset:21504
	ds_read_b128 v[230:233], v219 offset:22528
	ds_read_b128 v[234:237], v219 offset:23552
	s_nop 0
	global_load_lds_dwordx4 v198, s[12:13]
	s_add_i32 m0, s84, 0x2000
	s_nop 0
	global_load_lds_dwordx4 v200, s[12:13]
	s_add_u32 s12, s16, 0x100000
	s_addc_u32 s13, s17, 0
	s_add_i32 s84, s79, s25
	s_mov_b32 m0, s84
	s_nop 0
	global_load_lds_dwordx4 v198, s[12:13]
	s_add_i32 m0, s84, 0x2000
	s_nop 0
	global_load_lds_dwordx4 v200, s[12:13]
	s_mov_b64 s[12:13], s[18:19]
	s_mov_b32 m0, s33
	s_nop 0
	global_load_lds_dwordx4 v1, s[12:13]
	s_mov_b32 m0, s45
	s_nop 0
	global_load_lds_dwordx4 v199, s[12:13]
	s_waitcnt vmcnt(8)
	s_waitcnt lgkmcnt(0)
	s_setprio 1
	s_waitcnt lgkmcnt(0)
	s_barrier
; #define PG8_STAGE(bufoff, gbase, voff) do { const char* _gb = (const char*)(gbase); asm volatile("" : "+s"(_gb)); _Pragma("unroll") for (int _i = 0; _i < 2; ++_i) { asm volatile("" : "+v"((voff)[_i])); \
;         __builtin_amdgcn_global_load_lds((const unsigned*)(_gb + (voff)[_i]), (PG8_LAS unsigned*)(lds + (bufoff) + ldsw + _i * 8192), 16, 0, 0); } } while (0)
; #define PG8_LDA(dst, b, h) do { _Pragma("unroll") for (int m = 0; m < 4; ++m) _Pragma("unroll") for (int k = 0; k < 2; ++k) dst[m][k] = *(const PG8_LAS bf16x8*)(lds + PG8_SA(b, h) + aoff + m * 2048 + k * 1024); } while (0)
; #define PG8_LDB(dst, b, h) do { _Pragma("unroll") for (int n = 0; n < 2; ++n) _Pragma("unroll") for (int k = 0; k < 2; ++k) dst[n][k] = *(const PG8_LAS bf16x8*)(lds + PG8_SB(b, h) + boff + n * 2048 + k * 1024); } while (0)
; #define PG8_WAIT_V(n) asm volatile("s_waitcnt vmcnt(" #n ")" ::: "memory")
; #define PG8_WAIT_L(n) asm volatile("s_waitcnt lgkmcnt(" #n ")" ::: "memory")
; #define PG8_BAR __builtin_amdgcn_s_barrier()
; #define PG8_SCHED __builtin_amdgcn_sched_barrier(0)
; #define PG8_STAGE(bufoff, gbase, voff) do { const char* _gb = (const char*)(gbase); asm volatile("" : "+s"(_gb)); _Pragma("unroll") for (int _i = 0; _i < 2; ++_i) { asm volatile("" : "+v"((voff)[_i])); \
;         __builtin_amdgcn_global_load_lds((const unsigned*)(_gb + (voff)[_i]), (PG8_LAS unsigned*)(lds + (bufoff) + ldsw + _i * 8192), 16, 0, 0); } } while (0)
; #define PG8_LDA(dst, b, h) do { _Pragma("unroll") for (int m = 0; m < 4; ++m) _Pragma("unroll") for (int k = 0; k < 2; ++k) dst[m][k] = *(const PG8_LAS bf16x8*)(lds + PG8_SA(b, h) + aoff + m * 2048 + k * 1024); } while (0)
; #define PG8_LDB(dst, b, h) do { _Pragma("unroll") for (int n = 0; n < 2; ++n) _Pragma("unroll") for (int k = 0; k < 2; ++k) dst[n][k] = *(const PG8_LAS bf16x8*)(lds + PG8_SB(b, h) + boff + n * 2048 + k * 1024); } while (0)
; template <class Epi, class Sched, bool ALIGN_EPI = false, bool SP2 = false>
; __device__ __forceinline__ void gemm_phase(PG8_LAS unsigned char* lds, const Gemm g, const Sched& S, const Epi& E) {
;     ...
;             PG8_WAIT_V(8); PG8_WAIT_L(0); PG8_BAR; PG8_MMA2(1); PG8_BAR; PG8_SCHED;
;             PG8_LDB(B0, 1, 0); PG8_LDB(B1, 1, 1); PG8_SCHED; PG8_LDA(At, 1, 0); PG8_STAGE(PG8_SA(0, 1), a2 + hstep, voffA);
;             PG8_WAIT_V(8); PG8_WAIT_L(0); PG8_BAR; PG8_MMA2(0); PG8_BAR; PG8_SCHED;
	v_mfma_f32_16x16x32_bf16 v[34:37], v[6:9], v[180:183], v[34:37]
	v_mfma_f32_16x16x32_bf16 v[30:33], v[138:141], v[180:183], v[30:33]
	v_mfma_f32_16x16x32_bf16 v[26:29], v[6:9], v[188:191], v[26:29]
	v_mfma_f32_16x16x32_bf16 v[22:25], v[138:141], v[188:191], v[22:25]
	v_mfma_f32_16x16x32_bf16 v[70:73], v[6:9], v[222:225], v[70:73]
	v_mfma_f32_16x16x32_bf16 v[66:69], v[138:141], v[222:225], v[66:69]
	v_mfma_f32_16x16x32_bf16 v[50:53], v[138:141], v[230:233], v[50:53]
	v_mfma_f32_16x16x32_bf16 v[18:21], v[164:167], v[180:183], v[18:21]
	v_mfma_f32_16x16x32_bf16 v[14:17], v[172:175], v[180:183], v[14:17]
	v_mfma_f32_16x16x32_bf16 v[10:13], v[164:167], v[188:191], v[10:13]
	v_mfma_f32_16x16x32_bf16 v[2:5], v[172:175], v[188:191], v[2:5]
	v_mfma_f32_16x16x32_bf16 v[54:57], v[164:167], v[222:225], v[54:57]
	v_mfma_f32_16x16x32_bf16 v[46:49], v[172:175], v[222:225], v[46:49]
	v_mfma_f32_16x16x32_bf16 v[42:45], v[164:167], v[230:233], v[42:45]
	v_mfma_f32_16x16x32_bf16 v[38:41], v[172:175], v[230:233], v[38:41]
	v_mfma_f32_16x16x32_bf16 v[34:37], v[62:65], v[184:187], v[34:37]
	v_mfma_f32_16x16x32_bf16 v[30:33], v[142:145], v[184:187], v[30:33]
	v_mfma_f32_16x16x32_bf16 v[26:29], v[62:65], v[192:195], v[26:29]
	v_mfma_f32_16x16x32_bf16 v[22:25], v[142:145], v[192:195], v[22:25]
	v_mfma_f32_16x16x32_bf16 v[70:73], v[62:65], v[226:229], v[70:73]
	v_mfma_f32_16x16x32_bf16 v[66:69], v[142:145], v[226:229], v[66:69]
	v_mfma_f32_16x16x32_bf16 v[6:9], v[6:9], v[230:233], v[58:61]
	v_mfma_f32_16x16x32_bf16 v[50:53], v[142:145], v[234:237], v[50:53]
	v_mfma_f32_16x16x32_bf16 v[18:21], v[168:171], v[184:187], v[18:21]
	v_mfma_f32_16x16x32_bf16 v[14:17], v[176:179], v[184:187], v[14:17]
	v_mfma_f32_16x16x32_bf16 v[10:13], v[168:171], v[192:195], v[10:13]
	v_mfma_f32_16x16x32_bf16 v[2:5], v[176:179], v[192:195], v[2:5]
	v_mfma_f32_16x16x32_bf16 v[54:57], v[168:171], v[226:229], v[54:57]
	v_mfma_f32_16x16x32_bf16 v[46:49], v[176:179], v[226:229], v[46:49]
	v_mfma_f32_16x16x32_bf16 v[42:45], v[168:171], v[234:237], v[42:45]
	v_mfma_f32_16x16x32_bf16 v[38:41], v[176:179], v[234:237], v[38:41]
	s_setprio 0
	v_mfma_f32_16x16x32_bf16 v[6:9], v[62:65], v[234:237], v[6:9]
	s_barrier
	s_add_i32 s84, 0, 0x18000
	s_add_i32 s85, 0, 0x1c000
	v_add_u32_e32 v142, s84, v201
	v_add_u32_e32 v147, s85, v201
	ds_read_b128 v[58:61], v142
	ds_read_b128 v[62:65], v142 offset:1024
	ds_read_b128 v[138:141], v142 offset:2048
	ds_read_b128 v[142:145], v142 offset:3072
	ds_read_b128 v[164:167], v147
	ds_read_b128 v[168:171], v147 offset:1024
	ds_read_b128 v[172:175], v147 offset:2048
	ds_read_b128 v[176:179], v147 offset:3072
	s_add_u32 s12, s18, 0x100000
	s_addc_u32 s13, s19, 0
	s_mov_b32 m0, s47
	ds_read_b128 v[180:183], v219 offset:32768
	ds_read_b128 v[184:187], v219 offset:33792
	ds_read_b128 v[188:191], v219 offset:34816
	ds_read_b128 v[192:195], v219 offset:35840
	ds_read_b128 v[222:225], v219 offset:36864
	ds_read_b128 v[226:229], v219 offset:37888
	ds_read_b128 v[230:233], v219 offset:38912
	ds_read_b128 v[234:237], v219 offset:39936
	s_nop 0
	global_load_lds_dwordx4 v1, s[12:13]
	s_mov_b32 m0, s87
	s_nop 0
	global_load_lds_dwordx4 v199, s[12:13]
	s_waitcnt vmcnt(8)
	s_waitcnt lgkmcnt(0)
	s_setprio 1
	s_waitcnt lgkmcnt(0)
	s_barrier
	v_mfma_f32_16x16x32_bf16 v[118:121], v[58:61], v[180:183], v[118:121]
	v_mfma_f32_16x16x32_bf16 v[114:117], v[138:141], v[180:183], v[114:117]
	v_mfma_f32_16x16x32_bf16 v[106:109], v[58:61], v[188:191], v[106:109]
	v_mfma_f32_16x16x32_bf16 v[86:89], v[138:141], v[188:191], v[86:89]
	v_mfma_f32_16x16x32_bf16 v[134:137], v[58:61], v[222:225], v[134:137]
	v_mfma_f32_16x16x32_bf16 v[90:93], v[138:141], v[222:225], v[90:93]
	v_mfma_f32_16x16x32_bf16 v[130:133], v[58:61], v[230:233], v[130:133]
	v_mfma_f32_16x16x32_bf16 v[110:113], v[138:141], v[230:233], v[110:113]
	v_mfma_f32_16x16x32_bf16 v[94:97], v[164:167], v[180:183], v[94:97]
	v_mfma_f32_16x16x32_bf16 v[82:85], v[172:175], v[180:183], v[82:85]
	v_mfma_f32_16x16x32_bf16 v[78:81], v[164:167], v[188:191], v[78:81]
	v_mfma_f32_16x16x32_bf16 v[74:77], v[172:175], v[188:191], v[74:77]
	v_mfma_f32_16x16x32_bf16 v[126:129], v[164:167], v[222:225], v[126:129]
	v_mfma_f32_16x16x32_bf16 v[98:101], v[172:175], v[222:225], v[98:101]
	v_mfma_f32_16x16x32_bf16 v[122:125], v[164:167], v[230:233], v[122:125]
	v_mfma_f32_16x16x32_bf16 v[102:105], v[172:175], v[230:233], v[102:105]
	v_mfma_f32_16x16x32_bf16 v[118:121], v[62:65], v[184:187], v[118:121]
	v_mfma_f32_16x16x32_bf16 v[114:117], v[142:145], v[184:187], v[114:117]
	v_mfma_f32_16x16x32_bf16 v[106:109], v[62:65], v[192:195], v[106:109]
	v_mfma_f32_16x16x32_bf16 v[86:89], v[142:145], v[192:195], v[86:89]
	v_mfma_f32_16x16x32_bf16 v[134:137], v[62:65], v[226:229], v[134:137]
	v_mfma_f32_16x16x32_bf16 v[90:93], v[142:145], v[226:229], v[90:93]
	v_mfma_f32_16x16x32_bf16 v[130:133], v[62:65], v[234:237], v[130:133]
	v_mfma_f32_16x16x32_bf16 v[110:113], v[142:145], v[234:237], v[110:113]
	v_mfma_f32_16x16x32_bf16 v[94:97], v[168:171], v[184:187], v[94:97]
	v_mfma_f32_16x16x32_bf16 v[82:85], v[176:179], v[184:187], v[82:85]
	v_mfma_f32_16x16x32_bf16 v[78:81], v[168:171], v[192:195], v[78:81]
	v_mfma_f32_16x16x32_bf16 v[74:77], v[176:179], v[192:195], v[74:77]
	v_mfma_f32_16x16x32_bf16 v[126:129], v[168:171], v[226:229], v[126:129]
	v_mfma_f32_16x16x32_bf16 v[98:101], v[176:179], v[226:229], v[98:101]
	v_mfma_f32_16x16x32_bf16 v[122:125], v[168:171], v[234:237], v[122:125]
	s_setprio 0
	v_mfma_f32_16x16x32_bf16 v[102:105], v[176:179], v[234:237], v[102:105]
	s_barrier
; #define PG8_STAGE(bufoff, gbase, voff) do { const char* _gb = (const char*)(gbase); asm volatile("" : "+s"(_gb)); _Pragma("unroll") for (int _i = 0; _i < 2; ++_i) { asm volatile("" : "+v"((voff)[_i])); \
;         __builtin_amdgcn_global_load_lds((const unsigned*)(_gb + (voff)[_i]), (PG8_LAS unsigned*)(lds + (bufoff) + ldsw + _i * 8192), 16, 0, 0); } } while (0)
; #define PG8_LDA(dst, b, h) do { _Pragma("unroll") for (int m = 0; m < 4; ++m) _Pragma("unroll") for (int k = 0; k < 2; ++k) dst[m][k] = *(const PG8_LAS bf16x8*)(lds + PG8_SA(b, h) + aoff + m * 2048 + k * 1024); } while (0)
; #define PG8_WAIT_V(n) asm volatile("s_waitcnt vmcnt(" #n ")" ::: "memory")
; #define PG8_WAIT_L(n) asm volatile("s_waitcnt lgkmcnt(" #n ")" ::: "memory")
; #define PG8_BAR __builtin_amdgcn_s_barrier()
; #define PG8_SCHED __builtin_amdgcn_sched_barrier(0)
; #define PG8_STAGE(bufoff, gbase, voff) do { const char* _gb = (const char*)(gbase); asm volatile("" : "+s"(_gb)); _Pragma("unroll") for (int _i = 0; _i < 2; ++_i) { asm volatile("" : "+v"((voff)[_i])); \
;         __builtin_amdgcn_global_load_lds((const unsigned*)(_gb + (voff)[_i]), (PG8_LAS unsigned*)(lds + (bufoff) + ldsw + _i * 8192), 16, 0, 0); } } while (0)
; #define PG8_LDA(dst, b, h) do { _Pragma("unroll") for (int m = 0; m < 4; ++m) _Pragma("unroll") for (int k = 0; k < 2; ++k) dst[m][k] = *(const PG8_LAS bf16x8*)(lds + PG8_SA(b, h) + aoff + m * 2048 + k * 1024); } while (0)
; #define PG8_WAIT_V(n) asm volatile("s_waitcnt vmcnt(" #n ")" ::: "memory")
; #define PG8_WAIT_L(n) asm volatile("s_waitcnt lgkmcnt(" #n ")" ::: "memory")
; #define PG8_BAR __builtin_amdgcn_s_barrier()
; #define PG8_SCHED __builtin_amdgcn_sched_barrier(0)
; template <class Epi, class Sched, bool ALIGN_EPI = false, bool SP2 = false>
; __device__ __forceinline__ void gemm_phase(PG8_LAS unsigned char* lds, const Gemm g, const Sched& S, const Epi& E) {
;     ...
;             PG8_LDA(At, 1, 1); PG8_STAGE(PG8_SB(1, 0), b3, voffB); PG8_STAGE(PG8_SB(1, 1), b3 + hstep, voffB); PG8_STAGE(PG8_SA(1, 0), a3, voffA);
;             PG8_WAIT_V(8); PG8_WAIT_L(0); PG8_BAR; PG8_MMA2(1); PG8_BAR; PG8_SCHED;
	s_add_u32 s12, s16, 0x80
	s_addc_u32 s13, s17, 0
	s_add_i32 s18, s84, s25
	s_mov_b32 m0, s18
	ds_read_b128 v[180:183], v219 offset:49152
	ds_read_b128 v[184:187], v219 offset:50176
	ds_read_b128 v[188:191], v219 offset:51200
	ds_read_b128 v[192:195], v219 offset:52224
	ds_read_b128 v[222:225], v219 offset:53248
	ds_read_b128 v[226:229], v219 offset:54272
	ds_read_b128 v[230:233], v219 offset:55296
	ds_read_b128 v[234:237], v219 offset:56320
	s_nop 0
	global_load_lds_dwordx4 v198, s[12:13]
	s_add_i32 m0, s18, 0x2000
	s_nop 0
	global_load_lds_dwordx4 v200, s[12:13]
	s_add_u32 s12, s16, 0x100080
	s_addc_u32 s13, s17, 0
	s_add_i32 s16, s85, s25
	s_mov_b32 m0, s16
	s_nop 0
	global_load_lds_dwordx4 v198, s[12:13]
	s_add_i32 m0, s16, 0x2000
	s_nop 0
	global_load_lds_dwordx4 v200, s[12:13]
	s_mov_b32 m0, s71
	s_nop 0
	global_load_lds_dwordx4 v1, s[2:3]
	s_mov_b32 m0, s72
	s_nop 0
	global_load_lds_dwordx4 v199, s[2:3]
	s_waitcnt vmcnt(8)
	s_waitcnt lgkmcnt(0)
	s_setprio 1
	s_waitcnt lgkmcnt(0)
	s_barrier
	v_mfma_f32_16x16x32_bf16 v[6:9], v[58:61], v[230:233], v[6:9]
	v_mfma_f32_16x16x32_bf16 v[34:37], v[58:61], v[180:183], v[34:37]
	v_mfma_f32_16x16x32_bf16 v[26:29], v[58:61], v[188:191], v[26:29]
	v_mfma_f32_16x16x32_bf16 v[70:73], v[58:61], v[222:225], v[70:73]
	v_mfma_f32_16x16x32_bf16 v[58:61], v[62:65], v[234:237], v[6:9]
	v_mfma_f32_16x16x32_bf16 v[6:9], v[138:141], v[230:233], v[50:53]
	v_mfma_f32_16x16x32_bf16 v[50:53], v[142:145], v[234:237], v[6:9]
	v_mfma_f32_16x16x32_bf16 v[6:9], v[164:167], v[180:183], v[18:21]
	v_mfma_f32_16x16x32_bf16 v[18:21], v[168:171], v[184:187], v[6:9]
	v_mfma_f32_16x16x32_bf16 v[6:9], v[172:175], v[180:183], v[14:17]
	v_mfma_f32_16x16x32_bf16 v[14:17], v[176:179], v[184:187], v[6:9]
	v_mfma_f32_16x16x32_bf16 v[6:9], v[164:167], v[188:191], v[10:13]
	v_mfma_f32_16x16x32_bf16 v[10:13], v[168:171], v[192:195], v[6:9]
	v_mfma_f32_16x16x32_bf16 v[6:9], v[164:167], v[222:225], v[54:57]
	v_mfma_f32_16x16x32_bf16 v[54:57], v[168:171], v[226:229], v[6:9]
	v_mfma_f32_16x16x32_bf16 v[6:9], v[172:175], v[222:225], v[46:49]
	v_mfma_f32_16x16x32_bf16 v[46:49], v[176:179], v[226:229], v[6:9]
	v_mfma_f32_16x16x32_bf16 v[6:9], v[164:167], v[230:233], v[42:45]
	v_mfma_f32_16x16x32_bf16 v[30:33], v[138:141], v[180:183], v[30:33]
	v_mfma_f32_16x16x32_bf16 v[22:25], v[138:141], v[188:191], v[22:25]
	v_mfma_f32_16x16x32_bf16 v[66:69], v[138:141], v[222:225], v[66:69]
	v_mfma_f32_16x16x32_bf16 v[2:5], v[172:175], v[188:191], v[2:5]
	v_mfma_f32_16x16x32_bf16 v[42:45], v[168:171], v[234:237], v[6:9]
	v_mfma_f32_16x16x32_bf16 v[6:9], v[172:175], v[230:233], v[38:41]
	v_mfma_f32_16x16x32_bf16 v[34:37], v[62:65], v[184:187], v[34:37]
	v_mfma_f32_16x16x32_bf16 v[30:33], v[142:145], v[184:187], v[30:33]
	v_mfma_f32_16x16x32_bf16 v[26:29], v[62:65], v[192:195], v[26:29]
	v_mfma_f32_16x16x32_bf16 v[22:25], v[142:145], v[192:195], v[22:25]
	v_mfma_f32_16x16x32_bf16 v[70:73], v[62:65], v[226:229], v[70:73]
	v_mfma_f32_16x16x32_bf16 v[66:69], v[142:145], v[226:229], v[66:69]
	v_mfma_f32_16x16x32_bf16 v[2:5], v[176:179], v[192:195], v[2:5]
	s_setprio 0
	v_mfma_f32_16x16x32_bf16 v[38:41], v[176:179], v[234:237], v[6:9]
	s_barrier
	s_add_i32 s83, s83, 2
	s_add_u32 s62, s62, 0x100
	s_addc_u32 s63, s63, 0
	s_cmp_gt_u32 s83, 61
	s_mov_b64 s[12:13], s[14:15]
	s_cbranch_scc0 .LBB0_933
	s_and_b64 vcc, exec, s[38:39]
	s_cbranch_vccz .LBB0_936
	s_barrier

; #define PG8_STAGE(bufoff, gbase, voff) do { const char* _gb = (const char*)(gbase); asm volatile("" : "+s"(_gb)); _Pragma("unroll") for (int _i = 0; _i < 2; ++_i) { asm volatile("" : "+v"((voff)[_i])); \
;         __builtin_amdgcn_global_load_lds((const unsigned*)(_gb + (voff)[_i]), (PG8_LAS unsigned*)(lds + (bufoff) + ldsw + _i * 8192), 16, 0, 0); } } while (0)
; #define PG8_LDA(dst, b, h) do { _Pragma("unroll") for (int m = 0; m < 4; ++m) _Pragma("unroll") for (int k = 0; k < 2; ++k) dst[m][k] = *(const PG8_LAS bf16x8*)(lds + PG8_SA(b, h) + aoff + m * 2048 + k * 1024); } while (0)
; #define PG8_LDB(dst, b, h) do { _Pragma("unroll") for (int n = 0; n < 2; ++n) _Pragma("unroll") for (int k = 0; k < 2; ++k) dst[n][k] = *(const PG8_LAS bf16x8*)(lds + PG8_SB(b, h) + boff + n * 2048 + k * 1024); } while (0)
; #define PG8_WAIT_V(n) asm volatile("s_waitcnt vmcnt(" #n ")" ::: "memory")
; #define PG8_WAIT_L(n) asm volatile("s_waitcnt lgkmcnt(" #n ")" ::: "memory")
; #define PG8_BAR __builtin_amdgcn_s_barrier()
; #define PG8_SCHED __builtin_amdgcn_sched_barrier(0)
; #define PG8_LDA(dst, b, h) do { _Pragma("unroll") for (int m = 0; m < 4; ++m) _Pragma("unroll") for (int k = 0; k < 2; ++k) dst[m][k] = *(const PG8_LAS bf16x8*)(lds + PG8_SA(b, h) + aoff + m * 2048 + k * 1024); } while (0)
; template <class Epi, class Sched, bool ALIGN_EPI = false, bool SP2 = false>
; __device__ __forceinline__ void gemm_phase(PG8_LAS unsigned char* lds, const Gemm g, const Sched& S, const Epi& E) {
;     ...
;         for (int t = 0; t < nt; t += 2) {
;             const bool last = (t == nt - 2);
;             const char* a1 = cA + (size_t)(t + 1) * kstep;
;             const char* a2 = last ? nA : cA + (size_t)(t + 2) * kstep; const char* b2 = last ? nB : cB + (size_t)(t + 2) * kstep;
;             const char* a3 = a2 + kstep; const char* b3 = b2 + kstep;
;             if (last && has_next) S.a_ready(nxt);
;             if constexpr (SP2) {
;             PG8_LDB(B0, 0, 0); PG8_LDB(B1, 0, 1); PG8_SCHED; PG8_LDA(At, 0, 0); PG8_STAGE(PG8_SA(1, 1), a1 + hstep, voffA);
;             PG8_WAIT_V(8); PG8_WAIT_L(0); PG8_BAR; PG8_MMA2(0); PG8_BAR; PG8_SCHED;
;             PG8_LDA(At, 0, 1); PG8_STAGE(PG8_SB(0, 0), b2, voffB); PG8_STAGE(PG8_SB(0, 1), b2 + hstep, voffB); PG8_STAGE(PG8_SA(0, 0), a2, voffA);
;             PG8_WAIT_V(8); PG8_WAIT_L(0); PG8_BAR; PG8_MMA2(1); PG8_BAR; PG8_SCHED;
.LBB0_1125:
	ds_read_b128 v[130:133], v162
	ds_read_b128 v[134:137], v162 offset:1024
	ds_read_b128 v[138:141], v162 offset:2048
	ds_read_b128 v[142:145], v162 offset:3072
	ds_read_b128 v[150:153], v163
	ds_read_b128 v[166:169], v163 offset:1024
	ds_read_b128 v[170:173], v163 offset:2048
	ds_read_b128 v[174:177], v163 offset:3072
	s_add_u32 s20, s16, 0x100
	s_addc_u32 s21, s17, 0
	s_cmpk_eq_i32 s53, 0xbc
	s_cselect_b32 s26, s6, s20
	s_cselect_b32 s27, s7, s21
	s_cselect_b32 s24, s18, s51
	s_cselect_b32 s25, s19, s52
	s_add_u32 s2, s26, 0x80
	s_addc_u32 s3, s27, 0
	s_add_u32 s16, s16, 0x300080
	s_addc_u32 s17, s17, 0
	s_add_i32 m0, s34, 0xc000
	ds_read_b128 v[178:181], v164
	ds_read_b128 v[182:185], v164 offset:1024
	ds_read_b128 v[186:189], v164 offset:2048
	ds_read_b128 v[190:193], v164 offset:3072
	ds_read_b128 v[194:197], v164 offset:4096
	ds_read_b128 v[198:201], v164 offset:5120
	ds_read_b128 v[202:205], v164 offset:6144
	ds_read_b128 v[206:209], v164 offset:7168
	s_nop 0
	global_load_lds_dwordx4 v1, s[16:17]
	s_add_i32 m0, s34, 0xe000
	s_nop 0
	global_load_lds_dwordx4 v157, s[16:17]
	s_waitcnt vmcnt(8)
	s_waitcnt lgkmcnt(0)
	s_setprio 1
	s_waitcnt lgkmcnt(0)
	s_barrier
	v_mfma_f32_16x16x32_bf16 v[126:129], v[130:133], v[178:181], v[126:129]
	v_mfma_f32_16x16x32_bf16 v[122:125], v[138:141], v[178:181], v[122:125]
	v_mfma_f32_16x16x32_bf16 v[110:113], v[130:133], v[186:189], v[110:113]
	v_mfma_f32_16x16x32_bf16 v[106:109], v[138:141], v[186:189], v[106:109]
	v_mfma_f32_16x16x32_bf16 v[94:97], v[130:133], v[194:197], v[94:97]
	v_mfma_f32_16x16x32_bf16 v[90:93], v[138:141], v[194:197], v[90:93]
	v_mfma_f32_16x16x32_bf16 v[78:81], v[130:133], v[202:205], v[78:81]
	v_mfma_f32_16x16x32_bf16 v[74:77], v[138:141], v[202:205], v[74:77]
	v_mfma_f32_16x16x32_bf16 v[118:121], v[150:153], v[178:181], v[118:121]
	v_mfma_f32_16x16x32_bf16 v[114:117], v[170:173], v[178:181], v[114:117]
	v_mfma_f32_16x16x32_bf16 v[102:105], v[150:153], v[186:189], v[102:105]
	v_mfma_f32_16x16x32_bf16 v[98:101], v[170:173], v[186:189], v[98:101]
	v_mfma_f32_16x16x32_bf16 v[86:89], v[150:153], v[194:197], v[86:89]
	v_mfma_f32_16x16x32_bf16 v[82:85], v[170:173], v[194:197], v[82:85]
	v_mfma_f32_16x16x32_bf16 v[70:73], v[150:153], v[202:205], v[70:73]
	v_mfma_f32_16x16x32_bf16 v[66:69], v[170:173], v[202:205], v[66:69]
	v_mfma_f32_16x16x32_bf16 v[126:129], v[134:137], v[182:185], v[126:129]
	v_mfma_f32_16x16x32_bf16 v[122:125], v[142:145], v[182:185], v[122:125]
	v_mfma_f32_16x16x32_bf16 v[110:113], v[134:137], v[190:193], v[110:113]
	v_mfma_f32_16x16x32_bf16 v[106:109], v[142:145], v[190:193], v[106:109]
	v_mfma_f32_16x16x32_bf16 v[94:97], v[134:137], v[198:201], v[94:97]
	v_mfma_f32_16x16x32_bf16 v[90:93], v[142:145], v[198:201], v[90:93]
	v_mfma_f32_16x16x32_bf16 v[78:81], v[134:137], v[206:209], v[78:81]
	v_mfma_f32_16x16x32_bf16 v[74:77], v[142:145], v[206:209], v[74:77]
	v_mfma_f32_16x16x32_bf16 v[118:121], v[166:169], v[182:185], v[118:121]
	v_mfma_f32_16x16x32_bf16 v[114:117], v[174:177], v[182:185], v[114:117]
	v_mfma_f32_16x16x32_bf16 v[102:105], v[166:169], v[190:193], v[102:105]
	v_mfma_f32_16x16x32_bf16 v[98:101], v[174:177], v[190:193], v[98:101]
	v_mfma_f32_16x16x32_bf16 v[86:89], v[166:169], v[198:201], v[86:89]
	v_mfma_f32_16x16x32_bf16 v[82:85], v[174:177], v[198:201], v[82:85]
	v_mfma_f32_16x16x32_bf16 v[70:73], v[166:169], v[206:209], v[70:73]
	s_setprio 0
	v_mfma_f32_16x16x32_bf16 v[66:69], v[174:177], v[206:209], v[66:69]
	s_barrier
	s_add_i32 s54, s43, s33
	s_mov_b64 s[16:17], s[24:25]
	s_mov_b32 m0, s54
	ds_read_b128 v[178:181], v164 offset:16384
	ds_read_b128 v[182:185], v164 offset:17408
	ds_read_b128 v[186:189], v164 offset:18432
	ds_read_b128 v[190:193], v164 offset:19456
	ds_read_b128 v[194:197], v164 offset:20480
	ds_read_b128 v[198:201], v164 offset:21504
	ds_read_b128 v[202:205], v164 offset:22528
	ds_read_b128 v[206:209], v164 offset:23552
	s_nop 0
	global_load_lds_dwordx4 v156, s[16:17]
	s_add_i32 m0, s54, 0x2000
	s_nop 0
	global_load_lds_dwordx4 v158, s[16:17]
	s_add_u32 s16, s24, 0x300000
	s_addc_u32 s17, s25, 0
	s_add_i32 s54, s44, s33
	s_mov_b32 m0, s54
	s_nop 0
	global_load_lds_dwordx4 v156, s[16:17]
	s_add_i32 m0, s54, 0x2000
	s_nop 0
	global_load_lds_dwordx4 v158, s[16:17]
	s_mov_b64 s[16:17], s[26:27]
	s_mov_b32 m0, s34
	s_nop 0
	global_load_lds_dwordx4 v1, s[16:17]
	s_mov_b32 m0, s35
	s_nop 0
	global_load_lds_dwordx4 v157, s[16:17]
	s_waitcnt vmcnt(8)
	s_waitcnt lgkmcnt(0)
	s_setprio 1
	s_waitcnt lgkmcnt(0)
	s_barrier
	v_mfma_f32_16x16x32_bf16 v[62:65], v[130:133], v[178:181], v[62:65]
	v_mfma_f32_16x16x32_bf16 v[58:61], v[138:141], v[178:181], v[58:61]
	v_mfma_f32_16x16x32_bf16 v[46:49], v[130:133], v[186:189], v[46:49]
	v_mfma_f32_16x16x32_bf16 v[42:45], v[138:141], v[186:189], v[42:45]
	v_mfma_f32_16x16x32_bf16 v[30:33], v[130:133], v[194:197], v[30:33]
	v_mfma_f32_16x16x32_bf16 v[26:29], v[138:141], v[194:197], v[26:29]
	v_mfma_f32_16x16x32_bf16 v[14:17], v[130:133], v[202:205], v[14:17]
	v_mfma_f32_16x16x32_bf16 v[10:13], v[138:141], v[202:205], v[10:13]
	v_mfma_f32_16x16x32_bf16 v[54:57], v[150:153], v[178:181], v[54:57]
	v_mfma_f32_16x16x32_bf16 v[50:53], v[170:173], v[178:181], v[50:53]
	v_mfma_f32_16x16x32_bf16 v[38:41], v[150:153], v[186:189], v[38:41]
	v_mfma_f32_16x16x32_bf16 v[34:37], v[170:173], v[186:189], v[34:37]
	v_mfma_f32_16x16x32_bf16 v[22:25], v[150:153], v[194:197], v[22:25]
	v_mfma_f32_16x16x32_bf16 v[18:21], v[170:173], v[194:197], v[18:21]
	v_mfma_f32_16x16x32_bf16 v[6:9], v[150:153], v[202:205], v[6:9]
	v_mfma_f32_16x16x32_bf16 v[2:5], v[170:173], v[202:205], v[2:5]
	v_mfma_f32_16x16x32_bf16 v[62:65], v[134:137], v[182:185], v[62:65]
	v_mfma_f32_16x16x32_bf16 v[58:61], v[142:145], v[182:185], v[58:61]
	v_mfma_f32_16x16x32_bf16 v[46:49], v[134:137], v[190:193], v[46:49]
	v_mfma_f32_16x16x32_bf16 v[42:45], v[142:145], v[190:193], v[42:45]
	v_mfma_f32_16x16x32_bf16 v[30:33], v[134:137], v[198:201], v[30:33]
	v_mfma_f32_16x16x32_bf16 v[26:29], v[142:145], v[198:201], v[26:29]
	v_mfma_f32_16x16x32_bf16 v[14:17], v[134:137], v[206:209], v[14:17]
	v_mfma_f32_16x16x32_bf16 v[10:13], v[142:145], v[206:209], v[10:13]
	v_mfma_f32_16x16x32_bf16 v[54:57], v[166:169], v[182:185], v[54:57]
	v_mfma_f32_16x16x32_bf16 v[50:53], v[174:177], v[182:185], v[50:53]
	v_mfma_f32_16x16x32_bf16 v[38:41], v[166:169], v[190:193], v[38:41]
	v_mfma_f32_16x16x32_bf16 v[34:37], v[174:177], v[190:193], v[34:37]
	v_mfma_f32_16x16x32_bf16 v[22:25], v[166:169], v[198:201], v[22:25]
	v_mfma_f32_16x16x32_bf16 v[18:21], v[174:177], v[198:201], v[18:21]
	v_mfma_f32_16x16x32_bf16 v[6:9], v[166:169], v[206:209], v[6:9]
	s_setprio 0
	v_mfma_f32_16x16x32_bf16 v[2:5], v[174:177], v[206:209], v[2:5]
	s_barrier
; #define PG8_STAGE(bufoff, gbase, voff) do { const char* _gb = (const char*)(gbase); asm volatile("" : "+s"(_gb)); _Pragma("unroll") for (int _i = 0; _i < 2; ++_i) { asm volatile("" : "+v"((voff)[_i])); \
;         __builtin_amdgcn_global_load_lds((const unsigned*)(_gb + (voff)[_i]), (PG8_LAS unsigned*)(lds + (bufoff) + ldsw + _i * 8192), 16, 0, 0); } } while (0)
; #define PG8_LDA(dst, b, h) do { _Pragma("unroll") for (int m = 0; m < 4; ++m) _Pragma("unroll") for (int k = 0; k < 2; ++k) dst[m][k] = *(const PG8_LAS bf16x8*)(lds + PG8_SA(b, h) + aoff + m * 2048 + k * 1024); } while (0)
; #define PG8_LDB(dst, b, h) do { _Pragma("unroll") for (int n = 0; n < 2; ++n) _Pragma("unroll") for (int k = 0; k < 2; ++k) dst[n][k] = *(const PG8_LAS bf16x8*)(lds + PG8_SB(b, h) + boff + n * 2048 + k * 1024); } while (0)
; #define PG8_WAIT_V(n) asm volatile("s_waitcnt vmcnt(" #n ")" ::: "memory")
; #define PG8_WAIT_L(n) asm volatile("s_waitcnt lgkmcnt(" #n ")" ::: "memory")
; #define PG8_BAR __builtin_amdgcn_s_barrier()
; #define PG8_SCHED __builtin_amdgcn_sched_barrier(0)
; #define PG8_STAGE(bufoff, gbase, voff) do { const char* _gb = (const char*)(gbase); asm volatile("" : "+s"(_gb)); _Pragma("unroll") for (int _i = 0; _i < 2; ++_i) { asm volatile("" : "+v"((voff)[_i])); \
;         __builtin_amdgcn_global_load_lds((const unsigned*)(_gb + (voff)[_i]), (PG8_LAS unsigned*)(lds + (bufoff) + ldsw + _i * 8192), 16, 0, 0); } } while (0)
; #define PG8_LDA(dst, b, h) do { _Pragma("unroll") for (int m = 0; m < 4; ++m) _Pragma("unroll") for (int k = 0; k < 2; ++k) dst[m][k] = *(const PG8_LAS bf16x8*)(lds + PG8_SA(b, h) + aoff + m * 2048 + k * 1024); } while (0)
; #define PG8_WAIT_V(n) asm volatile("s_waitcnt vmcnt(" #n ")" ::: "memory")
; template <class Epi, class Sched, bool ALIGN_EPI = false, bool SP2 = false>
; __device__ __forceinline__ void gemm_phase(PG8_LAS unsigned char* lds, const Gemm g, const Sched& S, const Epi& E) {
;     ...
;             PG8_LDB(B0, 1, 0); PG8_LDB(B1, 1, 1); PG8_SCHED; PG8_LDA(At, 1, 0); PG8_STAGE(PG8_SA(0, 1), a2 + hstep, voffA);
;             PG8_WAIT_V(8); PG8_WAIT_L(0); PG8_BAR; PG8_MMA2(0); PG8_BAR; PG8_SCHED;
;             PG8_LDA(At, 1, 1); PG8_STAGE(PG8_SB(1, 0), b3, voffB); PG8_STAGE(PG8_SB(1, 1), b3 + hstep, voffB); PG8_STAGE(PG8_SA(1, 0), a3, voffA);
;             PG8_WAIT_V(8); PG8_WAIT_L(0); PG8_BAR; PG8_MMA2(1); PG8_BAR; PG8_SCHED;
	s_add_i32 s54, 0, 0x18000
	s_add_i32 s55, 0, 0x1c000
	v_add_u32_e32 v142, s54, v160
	v_add_u32_e32 v154, s55, v160
	ds_read_b128 v[130:133], v142
	ds_read_b128 v[134:137], v142 offset:1024
	ds_read_b128 v[138:141], v142 offset:2048
	ds_read_b128 v[142:145], v142 offset:3072
	ds_read_b128 v[150:153], v154
	ds_read_b128 v[166:169], v154 offset:1024
	ds_read_b128 v[170:173], v154 offset:2048
	ds_read_b128 v[174:177], v154 offset:3072
	s_add_u32 s16, s26, 0x300000
	s_addc_u32 s17, s27, 0
	s_mov_b32 m0, s36
	ds_read_b128 v[178:181], v164 offset:32768
	ds_read_b128 v[182:185], v164 offset:33792
	ds_read_b128 v[186:189], v164 offset:34816
	ds_read_b128 v[190:193], v164 offset:35840
	ds_read_b128 v[194:197], v164 offset:36864
	ds_read_b128 v[198:201], v164 offset:37888
	ds_read_b128 v[202:205], v164 offset:38912
	ds_read_b128 v[206:209], v164 offset:39936
	s_nop 0
	global_load_lds_dwordx4 v1, s[16:17]
	s_mov_b32 m0, s37
	s_nop 0
	global_load_lds_dwordx4 v157, s[16:17]
	s_waitcnt vmcnt(8)
	s_waitcnt lgkmcnt(0)
	s_setprio 1
	s_waitcnt lgkmcnt(0)
	s_barrier
	v_mfma_f32_16x16x32_bf16 v[126:129], v[130:133], v[178:181], v[126:129]
	v_mfma_f32_16x16x32_bf16 v[122:125], v[138:141], v[178:181], v[122:125]
	v_mfma_f32_16x16x32_bf16 v[110:113], v[130:133], v[186:189], v[110:113]
	v_mfma_f32_16x16x32_bf16 v[106:109], v[138:141], v[186:189], v[106:109]
	v_mfma_f32_16x16x32_bf16 v[94:97], v[130:133], v[194:197], v[94:97]
	v_mfma_f32_16x16x32_bf16 v[90:93], v[138:141], v[194:197], v[90:93]
	v_mfma_f32_16x16x32_bf16 v[78:81], v[130:133], v[202:205], v[78:81]
	v_mfma_f32_16x16x32_bf16 v[74:77], v[138:141], v[202:205], v[74:77]
	v_mfma_f32_16x16x32_bf16 v[118:121], v[150:153], v[178:181], v[118:121]
	v_mfma_f32_16x16x32_bf16 v[114:117], v[170:173], v[178:181], v[114:117]
	v_mfma_f32_16x16x32_bf16 v[102:105], v[150:153], v[186:189], v[102:105]
	v_mfma_f32_16x16x32_bf16 v[98:101], v[170:173], v[186:189], v[98:101]
	v_mfma_f32_16x16x32_bf16 v[86:89], v[150:153], v[194:197], v[86:89]
	v_mfma_f32_16x16x32_bf16 v[82:85], v[170:173], v[194:197], v[82:85]
	v_mfma_f32_16x16x32_bf16 v[70:73], v[150:153], v[202:205], v[70:73]
	v_mfma_f32_16x16x32_bf16 v[66:69], v[170:173], v[202:205], v[66:69]
	v_mfma_f32_16x16x32_bf16 v[126:129], v[134:137], v[182:185], v[126:129]
	v_mfma_f32_16x16x32_bf16 v[122:125], v[142:145], v[182:185], v[122:125]
	v_mfma_f32_16x16x32_bf16 v[110:113], v[134:137], v[190:193], v[110:113]
	v_mfma_f32_16x16x32_bf16 v[106:109], v[142:145], v[190:193], v[106:109]
	v_mfma_f32_16x16x32_bf16 v[94:97], v[134:137], v[198:201], v[94:97]
	v_mfma_f32_16x16x32_bf16 v[90:93], v[142:145], v[198:201], v[90:93]
	v_mfma_f32_16x16x32_bf16 v[78:81], v[134:137], v[206:209], v[78:81]
	v_mfma_f32_16x16x32_bf16 v[74:77], v[142:145], v[206:209], v[74:77]
	v_mfma_f32_16x16x32_bf16 v[118:121], v[166:169], v[182:185], v[118:121]
	v_mfma_f32_16x16x32_bf16 v[114:117], v[174:177], v[182:185], v[114:117]
	v_mfma_f32_16x16x32_bf16 v[102:105], v[166:169], v[190:193], v[102:105]
	v_mfma_f32_16x16x32_bf16 v[98:101], v[174:177], v[190:193], v[98:101]
	v_mfma_f32_16x16x32_bf16 v[86:89], v[166:169], v[198:201], v[86:89]
	v_mfma_f32_16x16x32_bf16 v[82:85], v[174:177], v[198:201], v[82:85]
	v_mfma_f32_16x16x32_bf16 v[70:73], v[166:169], v[206:209], v[70:73]
	s_setprio 0
	v_mfma_f32_16x16x32_bf16 v[66:69], v[174:177], v[206:209], v[66:69]
	s_barrier
	s_add_u32 s16, s24, 0x80
	s_addc_u32 s17, s25, 0
	s_add_i32 s26, s54, s33
	s_mov_b32 m0, s26
	ds_read_b128 v[178:181], v164 offset:49152
	ds_read_b128 v[182:185], v164 offset:50176
	ds_read_b128 v[186:189], v164 offset:51200
	ds_read_b128 v[190:193], v164 offset:52224
	ds_read_b128 v[194:197], v164 offset:53248
	ds_read_b128 v[198:201], v164 offset:54272
	ds_read_b128 v[202:205], v164 offset:55296
	ds_read_b128 v[206:209], v164 offset:56320
	s_nop 0
	global_load_lds_dwordx4 v156, s[16:17]
	s_add_i32 m0, s26, 0x2000
	s_nop 0
	global_load_lds_dwordx4 v158, s[16:17]
	s_add_u32 s16, s24, 0x300080
	s_addc_u32 s17, s25, 0
	s_add_i32 s24, s55, s33
	s_mov_b32 m0, s24
	s_nop 0
	global_load_lds_dwordx4 v156, s[16:17]
	s_add_i32 m0, s24, 0x2000
	s_nop 0
	global_load_lds_dwordx4 v158, s[16:17]
	s_mov_b32 m0, s39
	s_nop 0
	global_load_lds_dwordx4 v1, s[2:3]
	s_mov_b32 m0, s40
	s_nop 0
	global_load_lds_dwordx4 v157, s[2:3]
	s_waitcnt vmcnt(8)
	s_waitcnt lgkmcnt(0)
	s_setprio 1
	s_waitcnt lgkmcnt(0)
	s_barrier
	v_mfma_f32_16x16x32_bf16 v[62:65], v[130:133], v[178:181], v[62:65]
	v_mfma_f32_16x16x32_bf16 v[58:61], v[138:141], v[178:181], v[58:61]
	v_mfma_f32_16x16x32_bf16 v[46:49], v[130:133], v[186:189], v[46:49]
	v_mfma_f32_16x16x32_bf16 v[42:45], v[138:141], v[186:189], v[42:45]
	v_mfma_f32_16x16x32_bf16 v[30:33], v[130:133], v[194:197], v[30:33]
	v_mfma_f32_16x16x32_bf16 v[26:29], v[138:141], v[194:197], v[26:29]
	v_mfma_f32_16x16x32_bf16 v[14:17], v[130:133], v[202:205], v[14:17]
	v_mfma_f32_16x16x32_bf16 v[10:13], v[138:141], v[202:205], v[10:13]
	v_mfma_f32_16x16x32_bf16 v[54:57], v[150:153], v[178:181], v[54:57]
	v_mfma_f32_16x16x32_bf16 v[50:53], v[170:173], v[178:181], v[50:53]
	v_mfma_f32_16x16x32_bf16 v[38:41], v[150:153], v[186:189], v[38:41]
	v_mfma_f32_16x16x32_bf16 v[34:37], v[170:173], v[186:189], v[34:37]
	v_mfma_f32_16x16x32_bf16 v[22:25], v[150:153], v[194:197], v[22:25]
	v_mfma_f32_16x16x32_bf16 v[18:21], v[170:173], v[194:197], v[18:21]
	v_mfma_f32_16x16x32_bf16 v[6:9], v[150:153], v[202:205], v[6:9]
	v_mfma_f32_16x16x32_bf16 v[2:5], v[170:173], v[202:205], v[2:5]
	v_mfma_f32_16x16x32_bf16 v[62:65], v[134:137], v[182:185], v[62:65]
	v_mfma_f32_16x16x32_bf16 v[58:61], v[142:145], v[182:185], v[58:61]
	v_mfma_f32_16x16x32_bf16 v[46:49], v[134:137], v[190:193], v[46:49]
	v_mfma_f32_16x16x32_bf16 v[42:45], v[142:145], v[190:193], v[42:45]
	v_mfma_f32_16x16x32_bf16 v[30:33], v[134:137], v[198:201], v[30:33]
	v_mfma_f32_16x16x32_bf16 v[26:29], v[142:145], v[198:201], v[26:29]
	v_mfma_f32_16x16x32_bf16 v[14:17], v[134:137], v[206:209], v[14:17]
	v_mfma_f32_16x16x32_bf16 v[10:13], v[142:145], v[206:209], v[10:13]
	v_mfma_f32_16x16x32_bf16 v[54:57], v[166:169], v[182:185], v[54:57]
	v_mfma_f32_16x16x32_bf16 v[50:53], v[174:177], v[182:185], v[50:53]
	v_mfma_f32_16x16x32_bf16 v[38:41], v[166:169], v[190:193], v[38:41]
	v_mfma_f32_16x16x32_bf16 v[34:37], v[174:177], v[190:193], v[34:37]
	v_mfma_f32_16x16x32_bf16 v[22:25], v[166:169], v[198:201], v[22:25]
	v_mfma_f32_16x16x32_bf16 v[18:21], v[174:177], v[198:201], v[18:21]
	v_mfma_f32_16x16x32_bf16 v[6:9], v[166:169], v[206:209], v[6:9]
	s_setprio 0
	v_mfma_f32_16x16x32_bf16 v[2:5], v[174:177], v[206:209], v[2:5]
	s_barrier
	s_add_i32 s53, s53, 2
	s_add_u32 s51, s51, 0x100
	s_addc_u32 s52, s52, 0
	s_cmpk_gt_u32 s53, 0xbd
	s_mov_b64 s[16:17], s[20:21]
	s_cbranch_scc0 .LBB0_1125
	s_and_b64 vcc, exec, s[14:15]
	s_cbranch_vccz .LBB0_1128
	s_barrier

; #define PG8_STAGE(bufoff, gbase, voff) do { const char* _gb = (const char*)(gbase); asm volatile("" : "+s"(_gb)); _Pragma("unroll") for (int _i = 0; _i < 2; ++_i) { asm volatile("" : "+v"((voff)[_i])); \
;         __builtin_amdgcn_global_load_lds((const unsigned*)(_gb + (voff)[_i]), (PG8_LAS unsigned*)(lds + (bufoff) + ldsw + _i * 8192), 16, 0, 0); } } while (0)
; #define PG8_LDA(dst, b, h) do { _Pragma("unroll") for (int m = 0; m < 4; ++m) _Pragma("unroll") for (int k = 0; k < 2; ++k) dst[m][k] = *(const PG8_LAS bf16x8*)(lds + PG8_SA(b, h) + aoff + m * 2048 + k * 1024); } while (0)
; #define PG8_LDB(dst, b, h) do { _Pragma("unroll") for (int n = 0; n < 2; ++n) _Pragma("unroll") for (int k = 0; k < 2; ++k) dst[n][k] = *(const PG8_LAS bf16x8*)(lds + PG8_SB(b, h) + boff + n * 2048 + k * 1024); } while (0)
; #define PG8_WAIT_V(n) asm volatile("s_waitcnt vmcnt(" #n ")" ::: "memory")
; #define PG8_WAIT_L(n) asm volatile("s_waitcnt lgkmcnt(" #n ")" ::: "memory")
; #define PG8_BAR __builtin_amdgcn_s_barrier()
; #define PG8_SCHED __builtin_amdgcn_sched_barrier(0)
; #define PG8_LDA(dst, b, h) do { _Pragma("unroll") for (int m = 0; m < 4; ++m) _Pragma("unroll") for (int k = 0; k < 2; ++k) dst[m][k] = *(const PG8_LAS bf16x8*)(lds + PG8_SA(b, h) + aoff + m * 2048 + k * 1024); } while (0)
; #define PG8_BAR __builtin_amdgcn_s_barrier()
; template <class Epi, class Sched, bool ALIGN_EPI = false, bool SP2 = false>
; __device__ __forceinline__ void gemm_phase(PG8_LAS unsigned char* lds, const Gemm g, const Sched& S, const Epi& E) {
;     ...
;             const bool last = (t == nt - 2);
;             const char* a1 = cA + (size_t)(t + 1) * kstep;
;             const char* a2 = last ? nA : cA + (size_t)(t + 2) * kstep; const char* b2 = last ? nB : cB + (size_t)(t + 2) * kstep;
;             const char* a3 = a2 + kstep; const char* b3 = b2 + kstep;
;             if (last && has_next) S.a_ready(nxt);
;             if constexpr (SP2) {
;             PG8_LDB(B0, 0, 0); PG8_LDB(B1, 0, 1); PG8_SCHED; PG8_LDA(At, 0, 0); PG8_STAGE(PG8_SA(1, 1), a1 + hstep, voffA);
;             PG8_WAIT_V(8); PG8_WAIT_L(0); PG8_BAR; PG8_MMA2(0); PG8_BAR; PG8_SCHED;
;             PG8_LDA(At, 0, 1); PG8_STAGE(PG8_SB(0, 0), b2, voffB); PG8_STAGE(PG8_SB(0, 1), b2 + hstep, voffB); PG8_STAGE(PG8_SA(0, 0), a2, voffA);
;             PG8_WAIT_V(8); PG8_WAIT_L(0); PG8_BAR; PG8_MMA2(1); PG8_BAR; PG8_SCHED;
.LBB0_1217:
	ds_read_b128 v[128:131], v175
	ds_read_b128 v[132:135], v175 offset:1024
	ds_read_b128 v[136:139], v175 offset:2048
	ds_read_b128 v[140:143], v175 offset:3072
	ds_read_b128 v[152:155], v176
	ds_read_b128 v[156:159], v176 offset:1024
	ds_read_b128 v[160:163], v176 offset:2048
	ds_read_b128 v[184:187], v176 offset:3072
	s_add_u32 s28, s6, 0x100
	s_addc_u32 s29, s7, 0
	s_cmpk_eq_i32 s58, 0xbc
	s_cselect_b32 s36, s57, s28
	s_cselect_b32 s37, s56, s29
	s_cselect_b32 s34, s8, s4
	s_cselect_b32 s35, s9, s5
	s_add_u32 s30, s36, 0x80
	s_addc_u32 s31, s37, 0
	s_add_u32 s6, s6, 0x300080
	s_addc_u32 s7, s7, 0
	s_add_i32 m0, s41, 0xc000
	ds_read_b128 v[188:191], v177
	ds_read_b128 v[192:195], v177 offset:1024
	ds_read_b128 v[196:199], v177 offset:2048
	ds_read_b128 v[200:203], v177 offset:3072
	ds_read_b128 v[204:207], v177 offset:4096
	ds_read_b128 v[208:211], v177 offset:5120
	ds_read_b128 v[212:215], v177 offset:6144
	ds_read_b128 v[216:219], v177 offset:7168
	s_nop 0
	global_load_lds_dwordx4 v167, s[6:7]
	s_add_i32 m0, s41, 0xe000
	s_nop 0
	global_load_lds_dwordx4 v171, s[6:7]
	s_waitcnt vmcnt(8)
	s_waitcnt lgkmcnt(0)
	s_setprio 1
	s_waitcnt lgkmcnt(0)
	s_barrier
	v_mfma_f32_16x16x32_bf16 v[124:127], v[128:131], v[188:191], v[124:127]
	v_mfma_f32_16x16x32_bf16 v[120:123], v[136:139], v[188:191], v[120:123]
	v_mfma_f32_16x16x32_bf16 v[108:111], v[128:131], v[196:199], v[108:111]
	v_mfma_f32_16x16x32_bf16 v[104:107], v[136:139], v[196:199], v[104:107]
	v_mfma_f32_16x16x32_bf16 v[92:95], v[128:131], v[204:207], v[92:95]
	v_mfma_f32_16x16x32_bf16 v[88:91], v[136:139], v[204:207], v[88:91]
	v_mfma_f32_16x16x32_bf16 v[76:79], v[128:131], v[212:215], v[76:79]
	v_mfma_f32_16x16x32_bf16 v[72:75], v[136:139], v[212:215], v[72:75]
	v_mfma_f32_16x16x32_bf16 v[116:119], v[152:155], v[188:191], v[116:119]
	v_mfma_f32_16x16x32_bf16 v[112:115], v[160:163], v[188:191], v[112:115]
	v_mfma_f32_16x16x32_bf16 v[100:103], v[152:155], v[196:199], v[100:103]
	v_mfma_f32_16x16x32_bf16 v[96:99], v[160:163], v[196:199], v[96:99]
	v_mfma_f32_16x16x32_bf16 v[84:87], v[152:155], v[204:207], v[84:87]
	v_mfma_f32_16x16x32_bf16 v[80:83], v[160:163], v[204:207], v[80:83]
	v_mfma_f32_16x16x32_bf16 v[68:71], v[152:155], v[212:215], v[68:71]
	v_mfma_f32_16x16x32_bf16 v[64:67], v[160:163], v[212:215], v[64:67]
	v_mfma_f32_16x16x32_bf16 v[124:127], v[132:135], v[192:195], v[124:127]
	v_mfma_f32_16x16x32_bf16 v[120:123], v[140:143], v[192:195], v[120:123]
	v_mfma_f32_16x16x32_bf16 v[108:111], v[132:135], v[200:203], v[108:111]
	v_mfma_f32_16x16x32_bf16 v[104:107], v[140:143], v[200:203], v[104:107]
	v_mfma_f32_16x16x32_bf16 v[92:95], v[132:135], v[208:211], v[92:95]
	v_mfma_f32_16x16x32_bf16 v[88:91], v[140:143], v[208:211], v[88:91]
	v_mfma_f32_16x16x32_bf16 v[76:79], v[132:135], v[216:219], v[76:79]
	v_mfma_f32_16x16x32_bf16 v[72:75], v[140:143], v[216:219], v[72:75]
	v_mfma_f32_16x16x32_bf16 v[116:119], v[156:159], v[192:195], v[116:119]
	v_mfma_f32_16x16x32_bf16 v[112:115], v[184:187], v[192:195], v[112:115]
	v_mfma_f32_16x16x32_bf16 v[100:103], v[156:159], v[200:203], v[100:103]
	v_mfma_f32_16x16x32_bf16 v[96:99], v[184:187], v[200:203], v[96:99]
	v_mfma_f32_16x16x32_bf16 v[84:87], v[156:159], v[208:211], v[84:87]
	v_mfma_f32_16x16x32_bf16 v[80:83], v[184:187], v[208:211], v[80:83]
	v_mfma_f32_16x16x32_bf16 v[68:71], v[156:159], v[216:219], v[68:71]
	s_setprio 0
	v_mfma_f32_16x16x32_bf16 v[64:67], v[184:187], v[216:219], v[64:67]
	s_barrier
	s_add_i32 s59, s49, s39
	s_mov_b64 s[6:7], s[34:35]
	s_mov_b32 m0, s59
	ds_read_b128 v[188:191], v177 offset:16384
	ds_read_b128 v[192:195], v177 offset:17408
	ds_read_b128 v[196:199], v177 offset:18432
	ds_read_b128 v[200:203], v177 offset:19456
	ds_read_b128 v[204:207], v177 offset:20480
	ds_read_b128 v[208:211], v177 offset:21504
	ds_read_b128 v[212:215], v177 offset:22528
	ds_read_b128 v[216:219], v177 offset:23552
	s_nop 0
	global_load_lds_dwordx4 v169, s[6:7]
	s_add_i32 m0, s59, 0x2000
	s_nop 0
	global_load_lds_dwordx4 v172, s[6:7]
	s_add_u32 s6, s34, 0x300000
	s_addc_u32 s7, s35, 0
	s_add_i32 s59, s50, s39
	s_mov_b32 m0, s59
	s_nop 0
	global_load_lds_dwordx4 v169, s[6:7]
	s_add_i32 m0, s59, 0x2000
	s_nop 0
	global_load_lds_dwordx4 v172, s[6:7]
	s_mov_b64 s[6:7], s[36:37]
	s_mov_b32 m0, s41
	s_nop 0
	global_load_lds_dwordx4 v167, s[6:7]
	s_mov_b32 m0, s42
	s_nop 0
	global_load_lds_dwordx4 v171, s[6:7]
	s_waitcnt vmcnt(8)
	s_waitcnt lgkmcnt(0)
	s_setprio 1
	s_waitcnt lgkmcnt(0)
	s_barrier
	v_mfma_f32_16x16x32_bf16 v[60:63], v[128:131], v[188:191], v[60:63]
	v_mfma_f32_16x16x32_bf16 v[56:59], v[136:139], v[188:191], v[56:59]
	v_mfma_f32_16x16x32_bf16 v[44:47], v[128:131], v[196:199], v[44:47]
	v_mfma_f32_16x16x32_bf16 v[40:43], v[136:139], v[196:199], v[40:43]
	v_mfma_f32_16x16x32_bf16 v[28:31], v[128:131], v[204:207], v[28:31]
	v_mfma_f32_16x16x32_bf16 v[24:27], v[136:139], v[204:207], v[24:27]
	v_mfma_f32_16x16x32_bf16 v[12:15], v[128:131], v[212:215], v[12:15]
	v_mfma_f32_16x16x32_bf16 v[8:11], v[136:139], v[212:215], v[8:11]
	v_mfma_f32_16x16x32_bf16 v[52:55], v[152:155], v[188:191], v[52:55]
	v_mfma_f32_16x16x32_bf16 v[48:51], v[160:163], v[188:191], v[48:51]
	v_mfma_f32_16x16x32_bf16 v[36:39], v[152:155], v[196:199], v[36:39]
	v_mfma_f32_16x16x32_bf16 v[32:35], v[160:163], v[196:199], v[32:35]
	v_mfma_f32_16x16x32_bf16 v[20:23], v[152:155], v[204:207], v[20:23]
	v_mfma_f32_16x16x32_bf16 v[16:19], v[160:163], v[204:207], v[16:19]
	v_mfma_f32_16x16x32_bf16 v[4:7], v[152:155], v[212:215], v[4:7]
	v_mfma_f32_16x16x32_bf16 v[0:3], v[160:163], v[212:215], v[0:3]
	v_mfma_f32_16x16x32_bf16 v[60:63], v[132:135], v[192:195], v[60:63]
	v_mfma_f32_16x16x32_bf16 v[56:59], v[140:143], v[192:195], v[56:59]
	v_mfma_f32_16x16x32_bf16 v[44:47], v[132:135], v[200:203], v[44:47]
	v_mfma_f32_16x16x32_bf16 v[40:43], v[140:143], v[200:203], v[40:43]
	v_mfma_f32_16x16x32_bf16 v[28:31], v[132:135], v[208:211], v[28:31]
	v_mfma_f32_16x16x32_bf16 v[24:27], v[140:143], v[208:211], v[24:27]
	v_mfma_f32_16x16x32_bf16 v[12:15], v[132:135], v[216:219], v[12:15]
	v_mfma_f32_16x16x32_bf16 v[8:11], v[140:143], v[216:219], v[8:11]
	v_mfma_f32_16x16x32_bf16 v[52:55], v[156:159], v[192:195], v[52:55]
	v_mfma_f32_16x16x32_bf16 v[48:51], v[184:187], v[192:195], v[48:51]
	v_mfma_f32_16x16x32_bf16 v[36:39], v[156:159], v[200:203], v[36:39]
	v_mfma_f32_16x16x32_bf16 v[32:35], v[184:187], v[200:203], v[32:35]
	v_mfma_f32_16x16x32_bf16 v[20:23], v[156:159], v[208:211], v[20:23]
	v_mfma_f32_16x16x32_bf16 v[16:19], v[184:187], v[208:211], v[16:19]
	v_mfma_f32_16x16x32_bf16 v[4:7], v[156:159], v[216:219], v[4:7]
	s_setprio 0
	v_mfma_f32_16x16x32_bf16 v[0:3], v[184:187], v[216:219], v[0:3]
	s_barrier
; #define PG8_STAGE(bufoff, gbase, voff) do { const char* _gb = (const char*)(gbase); asm volatile("" : "+s"(_gb)); _Pragma("unroll") for (int _i = 0; _i < 2; ++_i) { asm volatile("" : "+v"((voff)[_i])); \
;         __builtin_amdgcn_global_load_lds((const unsigned*)(_gb + (voff)[_i]), (PG8_LAS unsigned*)(lds + (bufoff) + ldsw + _i * 8192), 16, 0, 0); } } while (0)
; #define PG8_LDA(dst, b, h) do { _Pragma("unroll") for (int m = 0; m < 4; ++m) _Pragma("unroll") for (int k = 0; k < 2; ++k) dst[m][k] = *(const PG8_LAS bf16x8*)(lds + PG8_SA(b, h) + aoff + m * 2048 + k * 1024); } while (0)
; #define PG8_LDB(dst, b, h) do { _Pragma("unroll") for (int n = 0; n < 2; ++n) _Pragma("unroll") for (int k = 0; k < 2; ++k) dst[n][k] = *(const PG8_LAS bf16x8*)(lds + PG8_SB(b, h) + boff + n * 2048 + k * 1024); } while (0)
; #define PG8_WAIT_V(n) asm volatile("s_waitcnt vmcnt(" #n ")" ::: "memory")
; #define PG8_WAIT_L(n) asm volatile("s_waitcnt lgkmcnt(" #n ")" ::: "memory")
; #define PG8_BAR __builtin_amdgcn_s_barrier()
; #define PG8_SCHED __builtin_amdgcn_sched_barrier(0)
; #define PG8_STAGE(bufoff, gbase, voff) do { const char* _gb = (const char*)(gbase); asm volatile("" : "+s"(_gb)); _Pragma("unroll") for (int _i = 0; _i < 2; ++_i) { asm volatile("" : "+v"((voff)[_i])); \
;         __builtin_amdgcn_global_load_lds((const unsigned*)(_gb + (voff)[_i]), (PG8_LAS unsigned*)(lds + (bufoff) + ldsw + _i * 8192), 16, 0, 0); } } while (0)
; #define PG8_LDA(dst, b, h) do { _Pragma("unroll") for (int m = 0; m < 4; ++m) _Pragma("unroll") for (int k = 0; k < 2; ++k) dst[m][k] = *(const PG8_LAS bf16x8*)(lds + PG8_SA(b, h) + aoff + m * 2048 + k * 1024); } while (0)
; template <class Epi, class Sched, bool ALIGN_EPI = false, bool SP2 = false>
; __device__ __forceinline__ void gemm_phase(PG8_LAS unsigned char* lds, const Gemm g, const Sched& S, const Epi& E) {
;     ...
;         for (int t = 0; t < nt; t += 2) {
;     ...
;             PG8_LDB(B0, 1, 0); PG8_LDB(B1, 1, 1); PG8_SCHED; PG8_LDA(At, 1, 0); PG8_STAGE(PG8_SA(0, 1), a2 + hstep, voffA);
;             PG8_WAIT_V(8); PG8_WAIT_L(0); PG8_BAR; PG8_MMA2(0); PG8_BAR; PG8_SCHED;
;             PG8_LDA(At, 1, 1); PG8_STAGE(PG8_SB(1, 0), b3, voffB); PG8_STAGE(PG8_SB(1, 1), b3 + hstep, voffB); PG8_STAGE(PG8_SA(1, 0), a3, voffA);
;             PG8_WAIT_V(8); PG8_WAIT_L(0); PG8_BAR; PG8_MMA2(1); PG8_BAR; PG8_SCHED;
	s_add_i32 s59, 0, 0x18000
	s_add_i32 s60, 0, 0x1c000
	v_add_u32_e32 v140, s59, v174
	v_add_u32_e32 v164, s60, v174
	ds_read_b128 v[128:131], v140
	ds_read_b128 v[132:135], v140 offset:1024
	ds_read_b128 v[136:139], v140 offset:2048
	ds_read_b128 v[140:143], v140 offset:3072
	ds_read_b128 v[152:155], v164
	ds_read_b128 v[156:159], v164 offset:1024
	ds_read_b128 v[160:163], v164 offset:2048
	ds_read_b128 v[184:187], v164 offset:3072
	s_add_u32 s6, s36, 0x300000
	s_addc_u32 s7, s37, 0
	s_mov_b32 m0, s43
	ds_read_b128 v[188:191], v177 offset:32768
	ds_read_b128 v[192:195], v177 offset:33792
	ds_read_b128 v[196:199], v177 offset:34816
	ds_read_b128 v[200:203], v177 offset:35840
	ds_read_b128 v[204:207], v177 offset:36864
	ds_read_b128 v[208:211], v177 offset:37888
	ds_read_b128 v[212:215], v177 offset:38912
	ds_read_b128 v[216:219], v177 offset:39936
	s_nop 0
	global_load_lds_dwordx4 v167, s[6:7]
	s_mov_b32 m0, s44
	s_nop 0
	global_load_lds_dwordx4 v171, s[6:7]
	s_waitcnt vmcnt(8)
	s_waitcnt lgkmcnt(0)
	s_setprio 1
	s_waitcnt lgkmcnt(0)
	s_barrier
	v_mfma_f32_16x16x32_bf16 v[124:127], v[128:131], v[188:191], v[124:127]
	v_mfma_f32_16x16x32_bf16 v[120:123], v[136:139], v[188:191], v[120:123]
	v_mfma_f32_16x16x32_bf16 v[108:111], v[128:131], v[196:199], v[108:111]
	v_mfma_f32_16x16x32_bf16 v[104:107], v[136:139], v[196:199], v[104:107]
	v_mfma_f32_16x16x32_bf16 v[92:95], v[128:131], v[204:207], v[92:95]
	v_mfma_f32_16x16x32_bf16 v[88:91], v[136:139], v[204:207], v[88:91]
	v_mfma_f32_16x16x32_bf16 v[76:79], v[128:131], v[212:215], v[76:79]
	v_mfma_f32_16x16x32_bf16 v[72:75], v[136:139], v[212:215], v[72:75]
	v_mfma_f32_16x16x32_bf16 v[116:119], v[152:155], v[188:191], v[116:119]
	v_mfma_f32_16x16x32_bf16 v[112:115], v[160:163], v[188:191], v[112:115]
	v_mfma_f32_16x16x32_bf16 v[100:103], v[152:155], v[196:199], v[100:103]
	v_mfma_f32_16x16x32_bf16 v[96:99], v[160:163], v[196:199], v[96:99]
	v_mfma_f32_16x16x32_bf16 v[84:87], v[152:155], v[204:207], v[84:87]
	v_mfma_f32_16x16x32_bf16 v[80:83], v[160:163], v[204:207], v[80:83]
	v_mfma_f32_16x16x32_bf16 v[68:71], v[152:155], v[212:215], v[68:71]
	v_mfma_f32_16x16x32_bf16 v[64:67], v[160:163], v[212:215], v[64:67]
	v_mfma_f32_16x16x32_bf16 v[124:127], v[132:135], v[192:195], v[124:127]
	v_mfma_f32_16x16x32_bf16 v[120:123], v[140:143], v[192:195], v[120:123]
	v_mfma_f32_16x16x32_bf16 v[108:111], v[132:135], v[200:203], v[108:111]
	v_mfma_f32_16x16x32_bf16 v[104:107], v[140:143], v[200:203], v[104:107]
	v_mfma_f32_16x16x32_bf16 v[92:95], v[132:135], v[208:211], v[92:95]
	v_mfma_f32_16x16x32_bf16 v[88:91], v[140:143], v[208:211], v[88:91]
	v_mfma_f32_16x16x32_bf16 v[76:79], v[132:135], v[216:219], v[76:79]
	v_mfma_f32_16x16x32_bf16 v[72:75], v[140:143], v[216:219], v[72:75]
	v_mfma_f32_16x16x32_bf16 v[116:119], v[156:159], v[192:195], v[116:119]
	v_mfma_f32_16x16x32_bf16 v[112:115], v[184:187], v[192:195], v[112:115]
	v_mfma_f32_16x16x32_bf16 v[100:103], v[156:159], v[200:203], v[100:103]
	v_mfma_f32_16x16x32_bf16 v[96:99], v[184:187], v[200:203], v[96:99]
	v_mfma_f32_16x16x32_bf16 v[84:87], v[156:159], v[208:211], v[84:87]
	v_mfma_f32_16x16x32_bf16 v[80:83], v[184:187], v[208:211], v[80:83]
	v_mfma_f32_16x16x32_bf16 v[68:71], v[156:159], v[216:219], v[68:71]
	s_setprio 0
	v_mfma_f32_16x16x32_bf16 v[64:67], v[184:187], v[216:219], v[64:67]
	s_barrier
	s_add_u32 s6, s34, 0x80
	s_addc_u32 s7, s35, 0
	s_add_i32 s36, s59, s39
	s_mov_b32 m0, s36
	ds_read_b128 v[188:191], v177 offset:49152
	ds_read_b128 v[192:195], v177 offset:50176
	ds_read_b128 v[196:199], v177 offset:51200
	ds_read_b128 v[200:203], v177 offset:52224
	ds_read_b128 v[204:207], v177 offset:53248
	ds_read_b128 v[208:211], v177 offset:54272
	ds_read_b128 v[212:215], v177 offset:55296
	ds_read_b128 v[216:219], v177 offset:56320
	s_nop 0
	global_load_lds_dwordx4 v169, s[6:7]
	s_add_i32 m0, s36, 0x2000
	s_nop 0
	global_load_lds_dwordx4 v172, s[6:7]
	s_add_u32 s6, s34, 0x300080
	s_addc_u32 s7, s35, 0
	s_add_i32 s34, s60, s39
	s_mov_b32 m0, s34
	s_nop 0
	global_load_lds_dwordx4 v169, s[6:7]
	s_add_i32 m0, s34, 0x2000
	s_nop 0
	global_load_lds_dwordx4 v172, s[6:7]
	s_mov_b32 m0, s47
	s_nop 0
	global_load_lds_dwordx4 v167, s[30:31]
	s_mov_b32 m0, s48
	s_nop 0
	global_load_lds_dwordx4 v171, s[30:31]
	s_waitcnt vmcnt(8)
	s_waitcnt lgkmcnt(0)
	s_setprio 1
	s_waitcnt lgkmcnt(0)
	s_barrier
	v_mfma_f32_16x16x32_bf16 v[60:63], v[128:131], v[188:191], v[60:63]
	v_mfma_f32_16x16x32_bf16 v[56:59], v[136:139], v[188:191], v[56:59]
	v_mfma_f32_16x16x32_bf16 v[44:47], v[128:131], v[196:199], v[44:47]
	v_mfma_f32_16x16x32_bf16 v[40:43], v[136:139], v[196:199], v[40:43]
	v_mfma_f32_16x16x32_bf16 v[28:31], v[128:131], v[204:207], v[28:31]
	v_mfma_f32_16x16x32_bf16 v[24:27], v[136:139], v[204:207], v[24:27]
	v_mfma_f32_16x16x32_bf16 v[12:15], v[128:131], v[212:215], v[12:15]
	v_mfma_f32_16x16x32_bf16 v[8:11], v[136:139], v[212:215], v[8:11]
	v_mfma_f32_16x16x32_bf16 v[52:55], v[152:155], v[188:191], v[52:55]
	v_mfma_f32_16x16x32_bf16 v[48:51], v[160:163], v[188:191], v[48:51]
	v_mfma_f32_16x16x32_bf16 v[36:39], v[152:155], v[196:199], v[36:39]
	v_mfma_f32_16x16x32_bf16 v[32:35], v[160:163], v[196:199], v[32:35]
	v_mfma_f32_16x16x32_bf16 v[20:23], v[152:155], v[204:207], v[20:23]
	v_mfma_f32_16x16x32_bf16 v[16:19], v[160:163], v[204:207], v[16:19]
	v_mfma_f32_16x16x32_bf16 v[4:7], v[152:155], v[212:215], v[4:7]
	v_mfma_f32_16x16x32_bf16 v[0:3], v[160:163], v[212:215], v[0:3]
	v_mfma_f32_16x16x32_bf16 v[60:63], v[132:135], v[192:195], v[60:63]
	v_mfma_f32_16x16x32_bf16 v[56:59], v[140:143], v[192:195], v[56:59]
	v_mfma_f32_16x16x32_bf16 v[44:47], v[132:135], v[200:203], v[44:47]
	v_mfma_f32_16x16x32_bf16 v[40:43], v[140:143], v[200:203], v[40:43]
	v_mfma_f32_16x16x32_bf16 v[28:31], v[132:135], v[208:211], v[28:31]
	v_mfma_f32_16x16x32_bf16 v[24:27], v[140:143], v[208:211], v[24:27]
	v_mfma_f32_16x16x32_bf16 v[12:15], v[132:135], v[216:219], v[12:15]
	v_mfma_f32_16x16x32_bf16 v[8:11], v[140:143], v[216:219], v[8:11]
	v_mfma_f32_16x16x32_bf16 v[52:55], v[156:159], v[192:195], v[52:55]
	v_mfma_f32_16x16x32_bf16 v[48:51], v[184:187], v[192:195], v[48:51]
	v_mfma_f32_16x16x32_bf16 v[36:39], v[156:159], v[200:203], v[36:39]
	v_mfma_f32_16x16x32_bf16 v[32:35], v[184:187], v[200:203], v[32:35]
	v_mfma_f32_16x16x32_bf16 v[20:23], v[156:159], v[208:211], v[20:23]
	v_mfma_f32_16x16x32_bf16 v[16:19], v[184:187], v[208:211], v[16:19]
	v_mfma_f32_16x16x32_bf16 v[4:7], v[156:159], v[216:219], v[4:7]
	s_setprio 0
	v_mfma_f32_16x16x32_bf16 v[0:3], v[184:187], v[216:219], v[0:3]
	s_barrier
	s_add_i32 s58, s58, 2
	s_add_u32 s4, s4, 0x100
	s_addc_u32 s5, s5, 0
	s_cmpk_gt_u32 s58, 0xbd
	s_mov_b64 s[6:7], s[28:29]
	s_cbranch_scc0 .LBB0_1217
	s_and_b64 vcc, exec, s[18:19]
	s_cbranch_vccz .LBB0_1220
	s_barrier
